# as previous but y0/y1 row loads back to default policy (only f32 x rows and once-read f32 weights non-temporal)
# speedup vs baseline: 1.0291x; 1.0017x over previous
; #define FRESH() int gtid; do { int t_ = threadIdx.x; asm volatile("" : "+v"(t_)); F.tid = t_; F.lane = t_ & 63; gtid = blockIdx.x * (NWAVES * 64) + t_; (void)gtid; } while (0)
; __global__ void __launch_bounds__(NWAVES * 64, 2) mk_fwd(Args args) {
;     ...
;     if (IN(11)) { FRESH();
;         const int per = (ML + F.NGW - 1) / F.NGW, per2 = (per + 1) & ~1, rbeg = F.gw * per2;
;         int rcur = -1; f32x4 PA[8];
;         for (int row0 = rbeg; row0 < rbeg + per2 && row0 < ML; row0 += 2) {
;             f32x4 v[2][8]; u32x2 yw[2][8];
; #pragma unroll
;             for (int q = 0; q < 2; ++q) { const int row = row0 + q; load_row_f32(args.out + (size_t)row * DM, F.lane, v[q]);
;                 const bf16_t* yr = Y + (size_t)row * DM;
; #pragma unroll
;                 for (int j = 0; j < 8; ++j) yw[q][j] = *(const u32x2*)(yr + 4 * F.lane + 256 * j); }
; #pragma unroll
;             for (int q = 0; q < 2; ++q) { const int row = row0 + q; const int r = row / SEQ;
;                 if (r != rcur) { const float* m1 = mod + (size_t)(9 + r) * 6144; rcur = r;
; #pragma unroll
;                     for (int j = 0; j < 8; ++j) { const int col = 4 * F.lane + 256 * j; PA[j] = *(const f32x4*)(m1 + 2 * DM + col) * *(const f32x4*)(post_norm + DM + col); } }
.LBB0_1288:
	s_cmp_gt_i32 s86, 11
	s_cselect_b64 s[2:3], -1, 0
	s_xor_b64 s[0:1], s[0:1], -1
	s_or_b64 s[0:1], s[2:3], s[0:1]
	s_and_b64 vcc, exec, s[0:1]
	s_cbranch_vccnz .LBB0_1296
	s_cmpk_lg_i32 s63, 0x100
	s_cbranch_scc1 .Lp11_generic
	v_and_b32_e32 v194, 63, v198
	v_lshlrev_b32_e32 v192, 4, v194
	v_add_u32_e32 v193, 0x1000, v192
	v_lshlrev_b32_e32 v194, 3, v194
	v_mov_b32_e32 v195, 0x358637bd
	s_lshr_b32 s0, s33, 8
	s_mul_i32 s1, s0, 0x6000
	s_add_u32 s8, s84, s1
	s_addc_u32 s9, s85, 0
	s_add_u32 s8, s8, 0x4000
	s_addc_u32 s9, s9, 0
	s_add_u32 s10, s8, 0x36000
	s_addc_u32 s11, s9, 0
	s_add_u32 s12, s82, 0x2000
	s_addc_u32 s13, s83, 0
	s_lshl_b32 s0, s33, 16
	s_add_u32 s14, s68, s0
	s_addc_u32 s15, s69, 0
	s_add_u32 s18, s94, s0
	s_addc_u32 s19, s95, 0
	s_lshl_b32 s0, s33, 15
	s_add_u32 s16, s84, s0
	s_addc_u32 s17, s85, 0
	s_add_u32 s22, s16, 0x8800000
	s_addc_u32 s23, s17, 0
	s_add_u32 s16, s16, 0x11800000
	s_addc_u32 s17, s17, 0
	global_load_dwordx4 v[128:131], v192, s[8:9] offset:0
	global_load_dwordx4 v[132:135], v192, s[8:9] offset:1024
	global_load_dwordx4 v[136:139], v192, s[8:9] offset:2048
	global_load_dwordx4 v[140:143], v192, s[8:9] offset:3072
	global_load_dwordx4 v[144:147], v193, s[8:9] offset:0
	global_load_dwordx4 v[148:151], v193, s[8:9] offset:1024
	global_load_dwordx4 v[152:155], v193, s[8:9] offset:2048
	global_load_dwordx4 v[156:159], v193, s[8:9] offset:3072
	global_load_dwordx4 v[32:35], v192, s[82:83] offset:0
	global_load_dwordx4 v[36:39], v192, s[82:83] offset:1024
	global_load_dwordx4 v[40:43], v192, s[82:83] offset:2048
	global_load_dwordx4 v[44:47], v192, s[82:83] offset:3072
	global_load_dwordx4 v[48:51], v193, s[82:83] offset:0
	global_load_dwordx4 v[52:55], v193, s[82:83] offset:1024
	global_load_dwordx4 v[56:59], v193, s[82:83] offset:2048
	global_load_dwordx4 v[60:63], v193, s[82:83] offset:3072
	global_load_dwordx4 v[160:163], v192, s[10:11] offset:0
	global_load_dwordx4 v[164:167], v192, s[10:11] offset:1024
	global_load_dwordx4 v[168:171], v192, s[10:11] offset:2048
	global_load_dwordx4 v[172:175], v192, s[10:11] offset:3072
	global_load_dwordx4 v[176:179], v193, s[10:11] offset:0
	global_load_dwordx4 v[180:183], v193, s[10:11] offset:1024
	global_load_dwordx4 v[184:187], v193, s[10:11] offset:2048
	global_load_dwordx4 v[188:191], v193, s[10:11] offset:3072
	global_load_dwordx4 v[96:99], v192, s[12:13] offset:0
	global_load_dwordx4 v[100:103], v192, s[12:13] offset:1024
	global_load_dwordx4 v[104:107], v192, s[12:13] offset:2048
	global_load_dwordx4 v[108:111], v192, s[12:13] offset:3072
	global_load_dwordx4 v[112:115], v193, s[12:13] offset:0
	global_load_dwordx4 v[116:119], v193, s[12:13] offset:1024
	global_load_dwordx4 v[120:123], v193, s[12:13] offset:2048
	global_load_dwordx4 v[124:127], v193, s[12:13] offset:3072
	s_waitcnt vmcnt(0)
	v_mul_f32_e32 v128, v128, v32
	v_mul_f32_e32 v129, v129, v33
	v_mul_f32_e32 v130, v130, v34
	v_mul_f32_e32 v131, v131, v35
	v_mul_f32_e32 v132, v132, v36
	v_mul_f32_e32 v133, v133, v37
	v_mul_f32_e32 v134, v134, v38
	v_mul_f32_e32 v135, v135, v39
	v_mul_f32_e32 v136, v136, v40
	v_mul_f32_e32 v137, v137, v41
	v_mul_f32_e32 v138, v138, v42
	v_mul_f32_e32 v139, v139, v43
	v_mul_f32_e32 v140, v140, v44
	v_mul_f32_e32 v141, v141, v45
	v_mul_f32_e32 v142, v142, v46
	v_mul_f32_e32 v143, v143, v47
	v_mul_f32_e32 v144, v144, v48
	v_mul_f32_e32 v145, v145, v49
	v_mul_f32_e32 v146, v146, v50
	v_mul_f32_e32 v147, v147, v51
	v_mul_f32_e32 v148, v148, v52
	v_mul_f32_e32 v149, v149, v53
	v_mul_f32_e32 v150, v150, v54
	v_mul_f32_e32 v151, v151, v55
	v_mul_f32_e32 v152, v152, v56
	v_mul_f32_e32 v153, v153, v57
	v_mul_f32_e32 v154, v154, v58
	v_mul_f32_e32 v155, v155, v59
	v_mul_f32_e32 v156, v156, v60
	v_mul_f32_e32 v157, v157, v61
	v_mul_f32_e32 v158, v158, v62
	v_mul_f32_e32 v159, v159, v63
	v_mul_f32_e32 v160, v160, v96
	v_mul_f32_e32 v161, v161, v97
	v_mul_f32_e32 v162, v162, v98
	v_mul_f32_e32 v163, v163, v99
	v_mul_f32_e32 v164, v164, v100
	v_mul_f32_e32 v165, v165, v101
	v_mul_f32_e32 v166, v166, v102
	v_mul_f32_e32 v167, v167, v103
	v_mul_f32_e32 v168, v168, v104
	v_mul_f32_e32 v169, v169, v105
	v_mul_f32_e32 v170, v170, v106
	v_mul_f32_e32 v171, v171, v107
	v_mul_f32_e32 v172, v172, v108
	v_mul_f32_e32 v173, v173, v109
	v_mul_f32_e32 v174, v174, v110
	v_mul_f32_e32 v175, v175, v111
	v_mul_f32_e32 v176, v176, v112
	v_mul_f32_e32 v177, v177, v113
	v_mul_f32_e32 v178, v178, v114
	v_mul_f32_e32 v179, v179, v115
	v_mul_f32_e32 v180, v180, v116
	v_mul_f32_e32 v181, v181, v117
	v_mul_f32_e32 v182, v182, v118
	v_mul_f32_e32 v183, v183, v119
	v_mul_f32_e32 v184, v184, v120
	v_mul_f32_e32 v185, v185, v121
	v_mul_f32_e32 v186, v186, v122
	v_mul_f32_e32 v187, v187, v123
	v_mul_f32_e32 v188, v188, v124
	v_mul_f32_e32 v189, v189, v125
	v_mul_f32_e32 v190, v190, v126
	v_mul_f32_e32 v191, v191, v127
	global_load_dwordx4 v[0:3], v192, s[14:15] offset:0 nt
	global_load_dwordx4 v[4:7], v192, s[14:15] offset:1024 nt
	global_load_dwordx4 v[8:11], v192, s[14:15] offset:2048 nt
	global_load_dwordx4 v[12:15], v192, s[14:15] offset:3072 nt
	global_load_dwordx4 v[16:19], v193, s[14:15] offset:0 nt
	global_load_dwordx4 v[20:23], v193, s[14:15] offset:1024 nt
	global_load_dwordx4 v[24:27], v193, s[14:15] offset:2048 nt
	global_load_dwordx4 v[28:31], v193, s[14:15] offset:3072 nt
	global_load_dwordx2 v[64:65], v194, s[16:17] offset:0
	global_load_dwordx2 v[66:67], v194, s[16:17] offset:512
	global_load_dwordx2 v[68:69], v194, s[16:17] offset:1024
	global_load_dwordx2 v[70:71], v194, s[16:17] offset:1536
	global_load_dwordx2 v[72:73], v194, s[16:17] offset:2048
	global_load_dwordx2 v[74:75], v194, s[16:17] offset:2560
; __device__ __forceinline__ float bf_lo(unsigned w) { return __uint_as_float(w << 16); }
; __device__ __forceinline__ float bf_hi(unsigned w) { return __uint_as_float(w & 0xffff0000u); }
; __global__ void __launch_bounds__(NWAVES * 64, 2) mk_fwd(Args args) {
;     ...
;         for (int row0 = rbeg; row0 < rbeg + per2 && row0 < ML; row0 += 2) {
;             f32x4 v[2][8]; u32x2 yw[2][8];
; #pragma unroll
;             for (int q = 0; q < 2; ++q) { const int row = row0 + q; load_row_f32(args.out + (size_t)row * DM, F.lane, v[q]);
;                 const bf16_t* yr = Y + (size_t)row * DM;
; #pragma unroll
;                 for (int j = 0; j < 8; ++j) yw[q][j] = *(const u32x2*)(yr + 4 * F.lane + 256 * j); }
; #pragma unroll
;             for (int q = 0; q < 2; ++q) { const int row = row0 + q; const int r = row / SEQ;
;                 if (r != rcur) { const float* m1 = mod + (size_t)(9 + r) * 6144; rcur = r;
; #pragma unroll
;                     for (int j = 0; j < 8; ++j) { const int col = 4 * F.lane + 256 * j; PA[j] = *(const f32x4*)(m1 + 2 * DM + col) * *(const f32x4*)(post_norm + DM + col); } }
;                 float sy = 0.f;
; #pragma unroll
;                 for (int j = 0; j < 8; ++j) { const float a = bf_lo(yw[q][j].x), b = bf_hi(yw[q][j].x), c2 = bf_lo(yw[q][j].y), d = bf_hi(yw[q][j].y); sy += (a * a + b * b) + (c2 * c2 + d * d); }
	global_load_dwordx2 v[76:77], v194, s[16:17] offset:3072
	global_load_dwordx2 v[78:79], v194, s[16:17] offset:3584
	global_load_dwordx2 v[96:97], v194, s[22:23] offset:0
	global_load_dwordx2 v[98:99], v194, s[22:23] offset:512
	global_load_dwordx2 v[100:101], v194, s[22:23] offset:1024
	global_load_dwordx2 v[102:103], v194, s[22:23] offset:1536
	global_load_dwordx2 v[104:105], v194, s[22:23] offset:2048
	global_load_dwordx2 v[106:107], v194, s[22:23] offset:2560
	global_load_dwordx2 v[108:109], v194, s[22:23] offset:3072
	global_load_dwordx2 v[110:111], v194, s[22:23] offset:3584
	s_add_u32 s14, s14, 0x2000
	s_addc_u32 s15, s15, 0
	s_add_u32 s16, s16, 0x1000
	s_addc_u32 s17, s17, 0
	s_add_u32 s22, s22, 0x1000
	s_addc_u32 s23, s23, 0
	global_load_dwordx4 v[32:35], v192, s[14:15] offset:0 nt
	global_load_dwordx4 v[36:39], v192, s[14:15] offset:1024 nt
	global_load_dwordx4 v[40:43], v192, s[14:15] offset:2048 nt
	global_load_dwordx4 v[44:47], v192, s[14:15] offset:3072 nt
	global_load_dwordx4 v[48:51], v193, s[14:15] offset:0 nt
	global_load_dwordx4 v[52:55], v193, s[14:15] offset:1024 nt
	global_load_dwordx4 v[56:59], v193, s[14:15] offset:2048 nt
	global_load_dwordx4 v[60:63], v193, s[14:15] offset:3072 nt
	global_load_dwordx2 v[80:81], v194, s[16:17] offset:0
	global_load_dwordx2 v[82:83], v194, s[16:17] offset:512
	global_load_dwordx2 v[84:85], v194, s[16:17] offset:1024
	global_load_dwordx2 v[86:87], v194, s[16:17] offset:1536
	global_load_dwordx2 v[88:89], v194, s[16:17] offset:2048
	global_load_dwordx2 v[90:91], v194, s[16:17] offset:2560
	global_load_dwordx2 v[92:93], v194, s[16:17] offset:3072
	global_load_dwordx2 v[94:95], v194, s[16:17] offset:3584
	global_load_dwordx2 v[112:113], v194, s[22:23] offset:0
	global_load_dwordx2 v[114:115], v194, s[22:23] offset:512
	global_load_dwordx2 v[116:117], v194, s[22:23] offset:1024
	global_load_dwordx2 v[118:119], v194, s[22:23] offset:1536
	global_load_dwordx2 v[120:121], v194, s[22:23] offset:2048
	global_load_dwordx2 v[122:123], v194, s[22:23] offset:2560
	global_load_dwordx2 v[124:125], v194, s[22:23] offset:3072
	global_load_dwordx2 v[126:127], v194, s[22:23] offset:3584
	s_add_u32 s14, s14, 0x2000
	s_addc_u32 s15, s15, 0
	s_add_u32 s16, s16, 0x1000
	s_addc_u32 s17, s17, 0
	s_add_u32 s22, s22, 0x1000
	s_addc_u32 s23, s23, 0
	s_waitcnt vmcnt(24)
	v_lshlrev_b32_e32 v200, 16, v64
	v_and_b32_e32 v201, 0xffff0000, v64
	v_lshlrev_b32_e32 v202, 16, v65
	v_and_b32_e32 v203, 0xffff0000, v65
	v_mul_f32_e32 v208, v200, v200
	v_mul_f32_e32 v209, v201, v201
	v_fmac_f32_e32 v208, v202, v202
	v_fmac_f32_e32 v209, v203, v203
	v_lshlrev_b32_e32 v204, 16, v96
	v_and_b32_e32 v205, 0xffff0000, v96
	v_lshlrev_b32_e32 v206, 16, v97
	v_and_b32_e32 v207, 0xffff0000, v97
	v_mul_f32_e32 v210, v204, v204
	v_mul_f32_e32 v211, v205, v205
	v_fmac_f32_e32 v210, v206, v206
	v_fmac_f32_e32 v211, v207, v207
	v_lshlrev_b32_e32 v200, 16, v66
	v_and_b32_e32 v201, 0xffff0000, v66
	v_lshlrev_b32_e32 v202, 16, v67
	v_and_b32_e32 v203, 0xffff0000, v67
	v_fmac_f32_e32 v208, v200, v200
	v_fmac_f32_e32 v209, v201, v201
	v_fmac_f32_e32 v208, v202, v202
	v_fmac_f32_e32 v209, v203, v203
	v_lshlrev_b32_e32 v204, 16, v98
	v_and_b32_e32 v205, 0xffff0000, v98
	v_lshlrev_b32_e32 v206, 16, v99
	v_and_b32_e32 v207, 0xffff0000, v99
	v_fmac_f32_e32 v210, v204, v204
	v_fmac_f32_e32 v211, v205, v205
	v_fmac_f32_e32 v210, v206, v206
	v_fmac_f32_e32 v211, v207, v207
	v_lshlrev_b32_e32 v200, 16, v68
	v_and_b32_e32 v201, 0xffff0000, v68
	v_lshlrev_b32_e32 v202, 16, v69
	v_and_b32_e32 v203, 0xffff0000, v69
	v_fmac_f32_e32 v208, v200, v200
	v_fmac_f32_e32 v209, v201, v201
	v_fmac_f32_e32 v208, v202, v202
	v_fmac_f32_e32 v209, v203, v203
	v_lshlrev_b32_e32 v204, 16, v100
	v_and_b32_e32 v205, 0xffff0000, v100
	v_lshlrev_b32_e32 v206, 16, v101
	v_and_b32_e32 v207, 0xffff0000, v101
	v_fmac_f32_e32 v210, v204, v204
	v_fmac_f32_e32 v211, v205, v205
	v_fmac_f32_e32 v210, v206, v206
	v_fmac_f32_e32 v211, v207, v207
	v_lshlrev_b32_e32 v200, 16, v70
	v_and_b32_e32 v201, 0xffff0000, v70
	v_lshlrev_b32_e32 v202, 16, v71
	v_and_b32_e32 v203, 0xffff0000, v71
	v_fmac_f32_e32 v208, v200, v200
	v_fmac_f32_e32 v209, v201, v201
	v_fmac_f32_e32 v208, v202, v202
	v_fmac_f32_e32 v209, v203, v203
	v_lshlrev_b32_e32 v204, 16, v102
	v_and_b32_e32 v205, 0xffff0000, v102
	v_lshlrev_b32_e32 v206, 16, v103
	v_and_b32_e32 v207, 0xffff0000, v103
	v_fmac_f32_e32 v210, v204, v204
	v_fmac_f32_e32 v211, v205, v205
	v_fmac_f32_e32 v210, v206, v206
	v_fmac_f32_e32 v211, v207, v207
	v_lshlrev_b32_e32 v200, 16, v72
	v_and_b32_e32 v201, 0xffff0000, v72
	v_lshlrev_b32_e32 v202, 16, v73
	v_and_b32_e32 v203, 0xffff0000, v73
	v_fmac_f32_e32 v208, v200, v200
	v_fmac_f32_e32 v209, v201, v201
	v_fmac_f32_e32 v208, v202, v202
	v_fmac_f32_e32 v209, v203, v203
	v_lshlrev_b32_e32 v204, 16, v104
	v_and_b32_e32 v205, 0xffff0000, v104
	v_lshlrev_b32_e32 v206, 16, v105
	v_and_b32_e32 v207, 0xffff0000, v105
	v_fmac_f32_e32 v210, v204, v204
	v_fmac_f32_e32 v211, v205, v205
	v_fmac_f32_e32 v210, v206, v206
	v_fmac_f32_e32 v211, v207, v207
	v_lshlrev_b32_e32 v200, 16, v74
	v_and_b32_e32 v201, 0xffff0000, v74
	v_lshlrev_b32_e32 v202, 16, v75
	v_and_b32_e32 v203, 0xffff0000, v75
	v_fmac_f32_e32 v208, v200, v200
	v_fmac_f32_e32 v209, v201, v201
	v_fmac_f32_e32 v208, v202, v202
	v_fmac_f32_e32 v209, v203, v203
	v_lshlrev_b32_e32 v204, 16, v106
	v_and_b32_e32 v205, 0xffff0000, v106
	v_lshlrev_b32_e32 v206, 16, v107
	v_and_b32_e32 v207, 0xffff0000, v107
	v_fmac_f32_e32 v210, v204, v204
	v_fmac_f32_e32 v211, v205, v205
	v_fmac_f32_e32 v210, v206, v206
	v_fmac_f32_e32 v211, v207, v207
	v_lshlrev_b32_e32 v200, 16, v76
; __device__ __forceinline__ float bf_lo(unsigned w) { return __uint_as_float(w << 16); }
; __device__ __forceinline__ float bf_hi(unsigned w) { return __uint_as_float(w & 0xffff0000u); }
; __global__ void __launch_bounds__(NWAVES * 64, 2) mk_fwd(Args args) {
;     ...
;                 float sy = 0.f;
; #pragma unroll
;                 for (int j = 0; j < 8; ++j) { const float a = bf_lo(yw[q][j].x), b = bf_hi(yw[q][j].x), c2 = bf_lo(yw[q][j].y), d = bf_hi(yw[q][j].y); sy += (a * a + b * b) + (c2 * c2 + d * d); }
;                 const float rsy = __builtin_amdgcn_rsqf(wave_sum(sy) * (1.f / DM) + EPS);
; #pragma unroll
;                 for (int j = 0; j < 8; ++j) { const int col = 4 * F.lane + 256 * j;
;                     const f32x4 y4 = (f32x4){bf_lo(yw[q][j].x), bf_hi(yw[q][j].x), bf_lo(yw[q][j].y), bf_hi(yw[q][j].y)};
;                     *(f32x4*)(args.out + (size_t)row * DM + col) = v[q][j] + PA[j] * (y4 * rsy); }
	v_and_b32_e32 v201, 0xffff0000, v76
	v_lshlrev_b32_e32 v202, 16, v77
	v_and_b32_e32 v203, 0xffff0000, v77
	v_fmac_f32_e32 v208, v200, v200
	v_fmac_f32_e32 v209, v201, v201
	v_fmac_f32_e32 v208, v202, v202
	v_fmac_f32_e32 v209, v203, v203
	v_lshlrev_b32_e32 v204, 16, v108
	v_and_b32_e32 v205, 0xffff0000, v108
	v_lshlrev_b32_e32 v206, 16, v109
	v_and_b32_e32 v207, 0xffff0000, v109
	v_fmac_f32_e32 v210, v204, v204
	v_fmac_f32_e32 v211, v205, v205
	v_fmac_f32_e32 v210, v206, v206
	v_fmac_f32_e32 v211, v207, v207
	v_lshlrev_b32_e32 v200, 16, v78
	v_and_b32_e32 v201, 0xffff0000, v78
	v_lshlrev_b32_e32 v202, 16, v79
	v_and_b32_e32 v203, 0xffff0000, v79
	v_fmac_f32_e32 v208, v200, v200
	v_fmac_f32_e32 v209, v201, v201
	v_fmac_f32_e32 v208, v202, v202
	v_fmac_f32_e32 v209, v203, v203
	v_lshlrev_b32_e32 v204, 16, v110
	v_and_b32_e32 v205, 0xffff0000, v110
	v_lshlrev_b32_e32 v206, 16, v111
	v_and_b32_e32 v207, 0xffff0000, v111
	v_fmac_f32_e32 v210, v204, v204
	v_fmac_f32_e32 v211, v205, v205
	v_fmac_f32_e32 v210, v206, v206
	v_fmac_f32_e32 v211, v207, v207
	v_add_f32_e32 v208, v208, v209
	v_add_f32_e32 v210, v210, v211
	s_nop 0
	v_add_f32_dpp v212, v208, v208 quad_perm:[1,0,3,2] row_mask:0xf bank_mask:0xf
	v_add_f32_dpp v213, v210, v210 quad_perm:[1,0,3,2] row_mask:0xf bank_mask:0xf
	s_nop 0
	v_add_f32_dpp v212, v212, v212 quad_perm:[2,3,0,1] row_mask:0xf bank_mask:0xf
	v_add_f32_dpp v213, v213, v213 quad_perm:[2,3,0,1] row_mask:0xf bank_mask:0xf
	s_nop 0
	v_add_f32_dpp v212, v212, v212 row_half_mirror row_mask:0xf bank_mask:0xf
	v_add_f32_dpp v213, v213, v213 row_half_mirror row_mask:0xf bank_mask:0xf
	s_nop 0
	v_add_f32_dpp v212, v212, v212 row_mirror row_mask:0xf bank_mask:0xf
	v_add_f32_dpp v213, v213, v213 row_mirror row_mask:0xf bank_mask:0xf
	s_nop 0
	v_readlane_b32 s4, v212, 0
	v_readlane_b32 s5, v212, 16
	v_readlane_b32 s6, v212, 32
	v_readlane_b32 s7, v212, 48
	v_readlane_b32 s24, v213, 0
	v_readlane_b32 s25, v213, 16
	v_readlane_b32 s26, v213, 32
	v_readlane_b32 s27, v213, 48
	s_nop 1
	v_mov_b32_e32 v214, s4
	v_mov_b32_e32 v215, s24
	v_add_f32_e32 v214, s5, v214
	v_add_f32_e32 v215, s25, v215
	v_add_f32_e32 v214, s6, v214
	v_add_f32_e32 v215, s26, v215
	v_add_f32_e32 v214, s7, v214
	v_add_f32_e32 v215, s27, v215
	v_fmamk_f32 v214, v214, 0x3a000000, v195
	v_fmamk_f32 v215, v215, 0x3a000000, v195
	v_rsq_f32_e32 v214, v214
	v_rsq_f32_e32 v215, v215
	s_nop 0
	v_lshlrev_b32_e32 v200, 16, v64
	v_and_b32_e32 v201, 0xffff0000, v64
	v_lshlrev_b32_e32 v202, 16, v65
	v_and_b32_e32 v203, 0xffff0000, v65
	v_lshlrev_b32_e32 v204, 16, v96
	v_and_b32_e32 v205, 0xffff0000, v96
	v_lshlrev_b32_e32 v206, 16, v97
	v_and_b32_e32 v207, 0xffff0000, v97
	v_mul_f32_e32 v200, v214, v200
	v_mul_f32_e32 v201, v214, v201
	v_mul_f32_e32 v202, v214, v202
	v_mul_f32_e32 v203, v214, v203
	v_mul_f32_e32 v204, v215, v204
	v_mul_f32_e32 v205, v215, v205
	v_mul_f32_e32 v206, v215, v206
	v_mul_f32_e32 v207, v215, v207
	v_fmac_f32_e32 v0, v128, v200
	v_fmac_f32_e32 v1, v129, v201
	v_fmac_f32_e32 v2, v130, v202
	v_fmac_f32_e32 v3, v131, v203
	v_fmac_f32_e32 v0, v160, v204
	v_fmac_f32_e32 v1, v161, v205
	v_fmac_f32_e32 v2, v162, v206
	v_fmac_f32_e32 v3, v163, v207
	global_store_dwordx4 v192, v[0:3], s[18:19] offset:0
	v_lshlrev_b32_e32 v200, 16, v66
	v_and_b32_e32 v201, 0xffff0000, v66
	v_lshlrev_b32_e32 v202, 16, v67
	v_and_b32_e32 v203, 0xffff0000, v67
	v_lshlrev_b32_e32 v204, 16, v98
	v_and_b32_e32 v205, 0xffff0000, v98
	v_lshlrev_b32_e32 v206, 16, v99
	v_and_b32_e32 v207, 0xffff0000, v99
	v_mul_f32_e32 v200, v214, v200
	v_mul_f32_e32 v201, v214, v201
	v_mul_f32_e32 v202, v214, v202
	v_mul_f32_e32 v203, v214, v203
	v_mul_f32_e32 v204, v215, v204
	v_mul_f32_e32 v205, v215, v205
	v_mul_f32_e32 v206, v215, v206
	v_mul_f32_e32 v207, v215, v207
	v_fmac_f32_e32 v4, v132, v200
	v_fmac_f32_e32 v5, v133, v201
	v_fmac_f32_e32 v6, v134, v202
	v_fmac_f32_e32 v7, v135, v203
	v_fmac_f32_e32 v4, v164, v204
	v_fmac_f32_e32 v5, v165, v205
	v_fmac_f32_e32 v6, v166, v206
	v_fmac_f32_e32 v7, v167, v207
	global_store_dwordx4 v192, v[4:7], s[18:19] offset:1024
	v_lshlrev_b32_e32 v200, 16, v68
	v_and_b32_e32 v201, 0xffff0000, v68
	v_lshlrev_b32_e32 v202, 16, v69
	v_and_b32_e32 v203, 0xffff0000, v69
	v_lshlrev_b32_e32 v204, 16, v100
	v_and_b32_e32 v205, 0xffff0000, v100
	v_lshlrev_b32_e32 v206, 16, v101
	v_and_b32_e32 v207, 0xffff0000, v101
	v_mul_f32_e32 v200, v214, v200
	v_mul_f32_e32 v201, v214, v201
	v_mul_f32_e32 v202, v214, v202
	v_mul_f32_e32 v203, v214, v203
	v_mul_f32_e32 v204, v215, v204
	v_mul_f32_e32 v205, v215, v205
	v_mul_f32_e32 v206, v215, v206
	v_mul_f32_e32 v207, v215, v207
	v_fmac_f32_e32 v8, v136, v200
	v_fmac_f32_e32 v9, v137, v201
	v_fmac_f32_e32 v10, v138, v202
	v_fmac_f32_e32 v11, v139, v203
	v_fmac_f32_e32 v8, v168, v204
	v_fmac_f32_e32 v9, v169, v205
	v_fmac_f32_e32 v10, v170, v206
	v_fmac_f32_e32 v11, v171, v207
	global_store_dwordx4 v192, v[8:11], s[18:19] offset:2048
	v_lshlrev_b32_e32 v200, 16, v70
	v_and_b32_e32 v201, 0xffff0000, v70
	v_lshlrev_b32_e32 v202, 16, v71
	v_and_b32_e32 v203, 0xffff0000, v71
	v_lshlrev_b32_e32 v204, 16, v102
	v_and_b32_e32 v205, 0xffff0000, v102
	v_lshlrev_b32_e32 v206, 16, v103
	v_and_b32_e32 v207, 0xffff0000, v103
	v_mul_f32_e32 v200, v214, v200
	v_mul_f32_e32 v201, v214, v201
	v_mul_f32_e32 v202, v214, v202
	v_mul_f32_e32 v203, v214, v203
	v_mul_f32_e32 v204, v215, v204
	v_mul_f32_e32 v205, v215, v205
	v_mul_f32_e32 v206, v215, v206
	v_mul_f32_e32 v207, v215, v207
	v_fmac_f32_e32 v12, v140, v200
	v_fmac_f32_e32 v13, v141, v201
	v_fmac_f32_e32 v14, v142, v202
	v_fmac_f32_e32 v15, v143, v203
	v_fmac_f32_e32 v12, v172, v204
; __device__ __forceinline__ float bf_lo(unsigned w) { return __uint_as_float(w << 16); }
; __device__ __forceinline__ float bf_hi(unsigned w) { return __uint_as_float(w & 0xffff0000u); }
; __global__ void __launch_bounds__(NWAVES * 64, 2) mk_fwd(Args args) {
;     ...
;         for (int row0 = rbeg; row0 < rbeg + per2 && row0 < ML; row0 += 2) {
;             f32x4 v[2][8]; u32x2 yw[2][8];
; #pragma unroll
;             for (int q = 0; q < 2; ++q) { const int row = row0 + q; load_row_f32(args.out + (size_t)row * DM, F.lane, v[q]);
;                 const bf16_t* yr = Y + (size_t)row * DM;
; #pragma unroll
;                 for (int j = 0; j < 8; ++j) yw[q][j] = *(const u32x2*)(yr + 4 * F.lane + 256 * j); }
; #pragma unroll
;             for (int q = 0; q < 2; ++q) { const int row = row0 + q; const int r = row / SEQ;
;                 if (r != rcur) { const float* m1 = mod + (size_t)(9 + r) * 6144; rcur = r;
; #pragma unroll
;                     for (int j = 0; j < 8; ++j) { const int col = 4 * F.lane + 256 * j; PA[j] = *(const f32x4*)(m1 + 2 * DM + col) * *(const f32x4*)(post_norm + DM + col); } }
;                 float sy = 0.f;
; #pragma unroll
;                 for (int j = 0; j < 8; ++j) { const float a = bf_lo(yw[q][j].x), b = bf_hi(yw[q][j].x), c2 = bf_lo(yw[q][j].y), d = bf_hi(yw[q][j].y); sy += (a * a + b * b) + (c2 * c2 + d * d); }
;                 const float rsy = __builtin_amdgcn_rsqf(wave_sum(sy) * (1.f / DM) + EPS);
; #pragma unroll
;                 for (int j = 0; j < 8; ++j) { const int col = 4 * F.lane + 256 * j;
;                     const f32x4 y4 = (f32x4){bf_lo(yw[q][j].x), bf_hi(yw[q][j].x), bf_lo(yw[q][j].y), bf_hi(yw[q][j].y)};
;                     *(f32x4*)(args.out + (size_t)row * DM + col) = v[q][j] + PA[j] * (y4 * rsy); }
	v_fmac_f32_e32 v13, v173, v205
	v_fmac_f32_e32 v14, v174, v206
	v_fmac_f32_e32 v15, v175, v207
	global_store_dwordx4 v192, v[12:15], s[18:19] offset:3072
	v_lshlrev_b32_e32 v200, 16, v72
	v_and_b32_e32 v201, 0xffff0000, v72
	v_lshlrev_b32_e32 v202, 16, v73
	v_and_b32_e32 v203, 0xffff0000, v73
	v_lshlrev_b32_e32 v204, 16, v104
	v_and_b32_e32 v205, 0xffff0000, v104
	v_lshlrev_b32_e32 v206, 16, v105
	v_and_b32_e32 v207, 0xffff0000, v105
	v_mul_f32_e32 v200, v214, v200
	v_mul_f32_e32 v201, v214, v201
	v_mul_f32_e32 v202, v214, v202
	v_mul_f32_e32 v203, v214, v203
	v_mul_f32_e32 v204, v215, v204
	v_mul_f32_e32 v205, v215, v205
	v_mul_f32_e32 v206, v215, v206
	v_mul_f32_e32 v207, v215, v207
	v_fmac_f32_e32 v16, v144, v200
	v_fmac_f32_e32 v17, v145, v201
	v_fmac_f32_e32 v18, v146, v202
	v_fmac_f32_e32 v19, v147, v203
	v_fmac_f32_e32 v16, v176, v204
	v_fmac_f32_e32 v17, v177, v205
	v_fmac_f32_e32 v18, v178, v206
	v_fmac_f32_e32 v19, v179, v207
	global_store_dwordx4 v193, v[16:19], s[18:19] offset:0
	v_lshlrev_b32_e32 v200, 16, v74
	v_and_b32_e32 v201, 0xffff0000, v74
	v_lshlrev_b32_e32 v202, 16, v75
	v_and_b32_e32 v203, 0xffff0000, v75
	v_lshlrev_b32_e32 v204, 16, v106
	v_and_b32_e32 v205, 0xffff0000, v106
	v_lshlrev_b32_e32 v206, 16, v107
	v_and_b32_e32 v207, 0xffff0000, v107
	v_mul_f32_e32 v200, v214, v200
	v_mul_f32_e32 v201, v214, v201
	v_mul_f32_e32 v202, v214, v202
	v_mul_f32_e32 v203, v214, v203
	v_mul_f32_e32 v204, v215, v204
	v_mul_f32_e32 v205, v215, v205
	v_mul_f32_e32 v206, v215, v206
	v_mul_f32_e32 v207, v215, v207
	v_fmac_f32_e32 v20, v148, v200
	v_fmac_f32_e32 v21, v149, v201
	v_fmac_f32_e32 v22, v150, v202
	v_fmac_f32_e32 v23, v151, v203
	v_fmac_f32_e32 v20, v180, v204
	v_fmac_f32_e32 v21, v181, v205
	v_fmac_f32_e32 v22, v182, v206
	v_fmac_f32_e32 v23, v183, v207
	global_store_dwordx4 v193, v[20:23], s[18:19] offset:1024
	v_lshlrev_b32_e32 v200, 16, v76
	v_and_b32_e32 v201, 0xffff0000, v76
	v_lshlrev_b32_e32 v202, 16, v77
	v_and_b32_e32 v203, 0xffff0000, v77
	v_lshlrev_b32_e32 v204, 16, v108
	v_and_b32_e32 v205, 0xffff0000, v108
	v_lshlrev_b32_e32 v206, 16, v109
	v_and_b32_e32 v207, 0xffff0000, v109
	v_mul_f32_e32 v200, v214, v200
	v_mul_f32_e32 v201, v214, v201
	v_mul_f32_e32 v202, v214, v202
	v_mul_f32_e32 v203, v214, v203
	v_mul_f32_e32 v204, v215, v204
	v_mul_f32_e32 v205, v215, v205
	v_mul_f32_e32 v206, v215, v206
	v_mul_f32_e32 v207, v215, v207
	v_fmac_f32_e32 v24, v152, v200
	v_fmac_f32_e32 v25, v153, v201
	v_fmac_f32_e32 v26, v154, v202
	v_fmac_f32_e32 v27, v155, v203
	v_fmac_f32_e32 v24, v184, v204
	v_fmac_f32_e32 v25, v185, v205
	v_fmac_f32_e32 v26, v186, v206
	v_fmac_f32_e32 v27, v187, v207
	global_store_dwordx4 v193, v[24:27], s[18:19] offset:2048
	v_lshlrev_b32_e32 v200, 16, v78
	v_and_b32_e32 v201, 0xffff0000, v78
	v_lshlrev_b32_e32 v202, 16, v79
	v_and_b32_e32 v203, 0xffff0000, v79
	v_lshlrev_b32_e32 v204, 16, v110
	v_and_b32_e32 v205, 0xffff0000, v110
	v_lshlrev_b32_e32 v206, 16, v111
	v_and_b32_e32 v207, 0xffff0000, v111
	v_mul_f32_e32 v200, v214, v200
	v_mul_f32_e32 v201, v214, v201
	v_mul_f32_e32 v202, v214, v202
	v_mul_f32_e32 v203, v214, v203
	v_mul_f32_e32 v204, v215, v204
	v_mul_f32_e32 v205, v215, v205
	v_mul_f32_e32 v206, v215, v206
	v_mul_f32_e32 v207, v215, v207
	v_fmac_f32_e32 v28, v156, v200
	v_fmac_f32_e32 v29, v157, v201
	v_fmac_f32_e32 v30, v158, v202
	v_fmac_f32_e32 v31, v159, v203
	v_fmac_f32_e32 v28, v188, v204
	v_fmac_f32_e32 v29, v189, v205
	v_fmac_f32_e32 v30, v190, v206
	v_fmac_f32_e32 v31, v191, v207
	global_store_dwordx4 v193, v[28:31], s[18:19] offset:3072
	s_add_u32 s18, s18, 0x2000
	s_addc_u32 s19, s19, 0
	global_load_dwordx4 v[0:3], v192, s[14:15] offset:0 nt
	global_load_dwordx4 v[4:7], v192, s[14:15] offset:1024 nt
	global_load_dwordx4 v[8:11], v192, s[14:15] offset:2048 nt
	global_load_dwordx4 v[12:15], v192, s[14:15] offset:3072 nt
	global_load_dwordx4 v[16:19], v193, s[14:15] offset:0 nt
	global_load_dwordx4 v[20:23], v193, s[14:15] offset:1024 nt
	global_load_dwordx4 v[24:27], v193, s[14:15] offset:2048 nt
	global_load_dwordx4 v[28:31], v193, s[14:15] offset:3072 nt
	global_load_dwordx2 v[64:65], v194, s[16:17] offset:0
	global_load_dwordx2 v[66:67], v194, s[16:17] offset:512
	global_load_dwordx2 v[68:69], v194, s[16:17] offset:1024
	global_load_dwordx2 v[70:71], v194, s[16:17] offset:1536
	global_load_dwordx2 v[72:73], v194, s[16:17] offset:2048
	global_load_dwordx2 v[74:75], v194, s[16:17] offset:2560
	global_load_dwordx2 v[76:77], v194, s[16:17] offset:3072
	global_load_dwordx2 v[78:79], v194, s[16:17] offset:3584
	global_load_dwordx2 v[96:97], v194, s[22:23] offset:0
	global_load_dwordx2 v[98:99], v194, s[22:23] offset:512
	global_load_dwordx2 v[100:101], v194, s[22:23] offset:1024
	global_load_dwordx2 v[102:103], v194, s[22:23] offset:1536
	global_load_dwordx2 v[104:105], v194, s[22:23] offset:2048
	global_load_dwordx2 v[106:107], v194, s[22:23] offset:2560
	global_load_dwordx2 v[108:109], v194, s[22:23] offset:3072
	global_load_dwordx2 v[110:111], v194, s[22:23] offset:3584
	s_add_u32 s14, s14, 0x2000
	s_addc_u32 s15, s15, 0
	s_add_u32 s16, s16, 0x1000
	s_addc_u32 s17, s17, 0
	s_add_u32 s22, s22, 0x1000
	s_addc_u32 s23, s23, 0
	s_waitcnt vmcnt(32)
; __device__ __forceinline__ float bf_lo(unsigned w) { return __uint_as_float(w << 16); }
; __device__ __forceinline__ float bf_hi(unsigned w) { return __uint_as_float(w & 0xffff0000u); }
; __global__ void __launch_bounds__(NWAVES * 64, 2) mk_fwd(Args args) {
;     ...
;                 float sy = 0.f;
; #pragma unroll
;                 for (int j = 0; j < 8; ++j) { const float a = bf_lo(yw[q][j].x), b = bf_hi(yw[q][j].x), c2 = bf_lo(yw[q][j].y), d = bf_hi(yw[q][j].y); sy += (a * a + b * b) + (c2 * c2 + d * d); }
;                 const float rsy = __builtin_amdgcn_rsqf(wave_sum(sy) * (1.f / DM) + EPS);
	v_lshlrev_b32_e32 v200, 16, v80
	v_and_b32_e32 v201, 0xffff0000, v80
	v_lshlrev_b32_e32 v202, 16, v81
	v_and_b32_e32 v203, 0xffff0000, v81
	v_mul_f32_e32 v208, v200, v200
	v_mul_f32_e32 v209, v201, v201
	v_fmac_f32_e32 v208, v202, v202
	v_fmac_f32_e32 v209, v203, v203
	v_lshlrev_b32_e32 v204, 16, v112
	v_and_b32_e32 v205, 0xffff0000, v112
	v_lshlrev_b32_e32 v206, 16, v113
	v_and_b32_e32 v207, 0xffff0000, v113
	v_mul_f32_e32 v210, v204, v204
	v_mul_f32_e32 v211, v205, v205
	v_fmac_f32_e32 v210, v206, v206
	v_fmac_f32_e32 v211, v207, v207
	v_lshlrev_b32_e32 v200, 16, v82
	v_and_b32_e32 v201, 0xffff0000, v82
	v_lshlrev_b32_e32 v202, 16, v83
	v_and_b32_e32 v203, 0xffff0000, v83
	v_fmac_f32_e32 v208, v200, v200
	v_fmac_f32_e32 v209, v201, v201
	v_fmac_f32_e32 v208, v202, v202
	v_fmac_f32_e32 v209, v203, v203
	v_lshlrev_b32_e32 v204, 16, v114
	v_and_b32_e32 v205, 0xffff0000, v114
	v_lshlrev_b32_e32 v206, 16, v115
	v_and_b32_e32 v207, 0xffff0000, v115
	v_fmac_f32_e32 v210, v204, v204
	v_fmac_f32_e32 v211, v205, v205
	v_fmac_f32_e32 v210, v206, v206
	v_fmac_f32_e32 v211, v207, v207
	v_lshlrev_b32_e32 v200, 16, v84
	v_and_b32_e32 v201, 0xffff0000, v84
	v_lshlrev_b32_e32 v202, 16, v85
	v_and_b32_e32 v203, 0xffff0000, v85
	v_fmac_f32_e32 v208, v200, v200
	v_fmac_f32_e32 v209, v201, v201
	v_fmac_f32_e32 v208, v202, v202
	v_fmac_f32_e32 v209, v203, v203
	v_lshlrev_b32_e32 v204, 16, v116
	v_and_b32_e32 v205, 0xffff0000, v116
	v_lshlrev_b32_e32 v206, 16, v117
	v_and_b32_e32 v207, 0xffff0000, v117
	v_fmac_f32_e32 v210, v204, v204
	v_fmac_f32_e32 v211, v205, v205
	v_fmac_f32_e32 v210, v206, v206
	v_fmac_f32_e32 v211, v207, v207
	v_lshlrev_b32_e32 v200, 16, v86
	v_and_b32_e32 v201, 0xffff0000, v86
	v_lshlrev_b32_e32 v202, 16, v87
	v_and_b32_e32 v203, 0xffff0000, v87
	v_fmac_f32_e32 v208, v200, v200
	v_fmac_f32_e32 v209, v201, v201
	v_fmac_f32_e32 v208, v202, v202
	v_fmac_f32_e32 v209, v203, v203
	v_lshlrev_b32_e32 v204, 16, v118
	v_and_b32_e32 v205, 0xffff0000, v118
	v_lshlrev_b32_e32 v206, 16, v119
	v_and_b32_e32 v207, 0xffff0000, v119
	v_fmac_f32_e32 v210, v204, v204
	v_fmac_f32_e32 v211, v205, v205
	v_fmac_f32_e32 v210, v206, v206
	v_fmac_f32_e32 v211, v207, v207
	v_lshlrev_b32_e32 v200, 16, v88
	v_and_b32_e32 v201, 0xffff0000, v88
	v_lshlrev_b32_e32 v202, 16, v89
	v_and_b32_e32 v203, 0xffff0000, v89
	v_fmac_f32_e32 v208, v200, v200
	v_fmac_f32_e32 v209, v201, v201
	v_fmac_f32_e32 v208, v202, v202
	v_fmac_f32_e32 v209, v203, v203
	v_lshlrev_b32_e32 v204, 16, v120
	v_and_b32_e32 v205, 0xffff0000, v120
	v_lshlrev_b32_e32 v206, 16, v121
	v_and_b32_e32 v207, 0xffff0000, v121
	v_fmac_f32_e32 v210, v204, v204
	v_fmac_f32_e32 v211, v205, v205
	v_fmac_f32_e32 v210, v206, v206
	v_fmac_f32_e32 v211, v207, v207
	v_lshlrev_b32_e32 v200, 16, v90
	v_and_b32_e32 v201, 0xffff0000, v90
	v_lshlrev_b32_e32 v202, 16, v91
	v_and_b32_e32 v203, 0xffff0000, v91
	v_fmac_f32_e32 v208, v200, v200
	v_fmac_f32_e32 v209, v201, v201
	v_fmac_f32_e32 v208, v202, v202
	v_fmac_f32_e32 v209, v203, v203
	v_lshlrev_b32_e32 v204, 16, v122
	v_and_b32_e32 v205, 0xffff0000, v122
	v_lshlrev_b32_e32 v206, 16, v123
	v_and_b32_e32 v207, 0xffff0000, v123
	v_fmac_f32_e32 v210, v204, v204
	v_fmac_f32_e32 v211, v205, v205
	v_fmac_f32_e32 v210, v206, v206
	v_fmac_f32_e32 v211, v207, v207
	v_lshlrev_b32_e32 v200, 16, v92
	v_and_b32_e32 v201, 0xffff0000, v92
	v_lshlrev_b32_e32 v202, 16, v93
	v_and_b32_e32 v203, 0xffff0000, v93
	v_fmac_f32_e32 v208, v200, v200
	v_fmac_f32_e32 v209, v201, v201
	v_fmac_f32_e32 v208, v202, v202
	v_fmac_f32_e32 v209, v203, v203
	v_lshlrev_b32_e32 v204, 16, v124
	v_and_b32_e32 v205, 0xffff0000, v124
	v_lshlrev_b32_e32 v206, 16, v125
	v_and_b32_e32 v207, 0xffff0000, v125
	v_fmac_f32_e32 v210, v204, v204
	v_fmac_f32_e32 v211, v205, v205
	v_fmac_f32_e32 v210, v206, v206
	v_fmac_f32_e32 v211, v207, v207
	v_lshlrev_b32_e32 v200, 16, v94
	v_and_b32_e32 v201, 0xffff0000, v94
	v_lshlrev_b32_e32 v202, 16, v95
	v_and_b32_e32 v203, 0xffff0000, v95
	v_fmac_f32_e32 v208, v200, v200
	v_fmac_f32_e32 v209, v201, v201
	v_fmac_f32_e32 v208, v202, v202
	v_fmac_f32_e32 v209, v203, v203
	v_lshlrev_b32_e32 v204, 16, v126
	v_and_b32_e32 v205, 0xffff0000, v126
	v_lshlrev_b32_e32 v206, 16, v127
	v_and_b32_e32 v207, 0xffff0000, v127
	v_fmac_f32_e32 v210, v204, v204
	v_fmac_f32_e32 v211, v205, v205
	v_fmac_f32_e32 v210, v206, v206
	v_fmac_f32_e32 v211, v207, v207
	v_add_f32_e32 v208, v208, v209
	v_add_f32_e32 v210, v210, v211
	s_nop 0
	v_add_f32_dpp v212, v208, v208 quad_perm:[1,0,3,2] row_mask:0xf bank_mask:0xf
	v_add_f32_dpp v213, v210, v210 quad_perm:[1,0,3,2] row_mask:0xf bank_mask:0xf
	s_nop 0
	v_add_f32_dpp v212, v212, v212 quad_perm:[2,3,0,1] row_mask:0xf bank_mask:0xf
	v_add_f32_dpp v213, v213, v213 quad_perm:[2,3,0,1] row_mask:0xf bank_mask:0xf
	s_nop 0
	v_add_f32_dpp v212, v212, v212 row_half_mirror row_mask:0xf bank_mask:0xf
	v_add_f32_dpp v213, v213, v213 row_half_mirror row_mask:0xf bank_mask:0xf
	s_nop 0
	v_add_f32_dpp v212, v212, v212 row_mirror row_mask:0xf bank_mask:0xf
	v_add_f32_dpp v213, v213, v213 row_mirror row_mask:0xf bank_mask:0xf
	s_nop 0
	v_readlane_b32 s4, v212, 0
	v_readlane_b32 s5, v212, 16
	v_readlane_b32 s6, v212, 32
	v_readlane_b32 s7, v212, 48
	v_readlane_b32 s24, v213, 0
	v_readlane_b32 s25, v213, 16
	v_readlane_b32 s26, v213, 32
	v_readlane_b32 s27, v213, 48
	s_nop 1
	v_mov_b32_e32 v214, s4
	v_mov_b32_e32 v215, s24
	v_add_f32_e32 v214, s5, v214
	v_add_f32_e32 v215, s25, v215
	v_add_f32_e32 v214, s6, v214
	v_add_f32_e32 v215, s26, v215
	v_add_f32_e32 v214, s7, v214
	v_add_f32_e32 v215, s27, v215
	v_fmamk_f32 v214, v214, 0x3a000000, v195
	v_fmamk_f32 v215, v215, 0x3a000000, v195
; __device__ __forceinline__ float bf_lo(unsigned w) { return __uint_as_float(w << 16); }
; __device__ __forceinline__ float bf_hi(unsigned w) { return __uint_as_float(w & 0xffff0000u); }
; __global__ void __launch_bounds__(NWAVES * 64, 2) mk_fwd(Args args) {
;     ...
;                 const float rsy = __builtin_amdgcn_rsqf(wave_sum(sy) * (1.f / DM) + EPS);
; #pragma unroll
;                 for (int j = 0; j < 8; ++j) { const int col = 4 * F.lane + 256 * j;
;                     const f32x4 y4 = (f32x4){bf_lo(yw[q][j].x), bf_hi(yw[q][j].x), bf_lo(yw[q][j].y), bf_hi(yw[q][j].y)};
;                     *(f32x4*)(args.out + (size_t)row * DM + col) = v[q][j] + PA[j] * (y4 * rsy); }
	v_rsq_f32_e32 v214, v214
	v_rsq_f32_e32 v215, v215
	s_nop 0
	v_lshlrev_b32_e32 v200, 16, v80
	v_and_b32_e32 v201, 0xffff0000, v80
	v_lshlrev_b32_e32 v202, 16, v81
	v_and_b32_e32 v203, 0xffff0000, v81
	v_lshlrev_b32_e32 v204, 16, v112
	v_and_b32_e32 v205, 0xffff0000, v112
	v_lshlrev_b32_e32 v206, 16, v113
	v_and_b32_e32 v207, 0xffff0000, v113
	v_mul_f32_e32 v200, v214, v200
	v_mul_f32_e32 v201, v214, v201
	v_mul_f32_e32 v202, v214, v202
	v_mul_f32_e32 v203, v214, v203
	v_mul_f32_e32 v204, v215, v204
	v_mul_f32_e32 v205, v215, v205
	v_mul_f32_e32 v206, v215, v206
	v_mul_f32_e32 v207, v215, v207
	v_fmac_f32_e32 v32, v128, v200
	v_fmac_f32_e32 v33, v129, v201
	v_fmac_f32_e32 v34, v130, v202
	v_fmac_f32_e32 v35, v131, v203
	v_fmac_f32_e32 v32, v160, v204
	v_fmac_f32_e32 v33, v161, v205
	v_fmac_f32_e32 v34, v162, v206
	v_fmac_f32_e32 v35, v163, v207
	global_store_dwordx4 v192, v[32:35], s[18:19] offset:0
	v_lshlrev_b32_e32 v200, 16, v82
	v_and_b32_e32 v201, 0xffff0000, v82
	v_lshlrev_b32_e32 v202, 16, v83
	v_and_b32_e32 v203, 0xffff0000, v83
	v_lshlrev_b32_e32 v204, 16, v114
	v_and_b32_e32 v205, 0xffff0000, v114
	v_lshlrev_b32_e32 v206, 16, v115
	v_and_b32_e32 v207, 0xffff0000, v115
	v_mul_f32_e32 v200, v214, v200
	v_mul_f32_e32 v201, v214, v201
	v_mul_f32_e32 v202, v214, v202
	v_mul_f32_e32 v203, v214, v203
	v_mul_f32_e32 v204, v215, v204
	v_mul_f32_e32 v205, v215, v205
	v_mul_f32_e32 v206, v215, v206
	v_mul_f32_e32 v207, v215, v207
	v_fmac_f32_e32 v36, v132, v200
	v_fmac_f32_e32 v37, v133, v201
	v_fmac_f32_e32 v38, v134, v202
	v_fmac_f32_e32 v39, v135, v203
	v_fmac_f32_e32 v36, v164, v204
	v_fmac_f32_e32 v37, v165, v205
	v_fmac_f32_e32 v38, v166, v206
	v_fmac_f32_e32 v39, v167, v207
	global_store_dwordx4 v192, v[36:39], s[18:19] offset:1024
	v_lshlrev_b32_e32 v200, 16, v84
	v_and_b32_e32 v201, 0xffff0000, v84
	v_lshlrev_b32_e32 v202, 16, v85
	v_and_b32_e32 v203, 0xffff0000, v85
	v_lshlrev_b32_e32 v204, 16, v116
	v_and_b32_e32 v205, 0xffff0000, v116
	v_lshlrev_b32_e32 v206, 16, v117
	v_and_b32_e32 v207, 0xffff0000, v117
	v_mul_f32_e32 v200, v214, v200
	v_mul_f32_e32 v201, v214, v201
	v_mul_f32_e32 v202, v214, v202
	v_mul_f32_e32 v203, v214, v203
	v_mul_f32_e32 v204, v215, v204
	v_mul_f32_e32 v205, v215, v205
	v_mul_f32_e32 v206, v215, v206
	v_mul_f32_e32 v207, v215, v207
	v_fmac_f32_e32 v40, v136, v200
	v_fmac_f32_e32 v41, v137, v201
	v_fmac_f32_e32 v42, v138, v202
	v_fmac_f32_e32 v43, v139, v203
	v_fmac_f32_e32 v40, v168, v204
	v_fmac_f32_e32 v41, v169, v205
	v_fmac_f32_e32 v42, v170, v206
	v_fmac_f32_e32 v43, v171, v207
	global_store_dwordx4 v192, v[40:43], s[18:19] offset:2048
	v_lshlrev_b32_e32 v200, 16, v86
	v_and_b32_e32 v201, 0xffff0000, v86
	v_lshlrev_b32_e32 v202, 16, v87
	v_and_b32_e32 v203, 0xffff0000, v87
	v_lshlrev_b32_e32 v204, 16, v118
	v_and_b32_e32 v205, 0xffff0000, v118
	v_lshlrev_b32_e32 v206, 16, v119
	v_and_b32_e32 v207, 0xffff0000, v119
	v_mul_f32_e32 v200, v214, v200
	v_mul_f32_e32 v201, v214, v201
	v_mul_f32_e32 v202, v214, v202
	v_mul_f32_e32 v203, v214, v203
	v_mul_f32_e32 v204, v215, v204
	v_mul_f32_e32 v205, v215, v205
	v_mul_f32_e32 v206, v215, v206
	v_mul_f32_e32 v207, v215, v207
	v_fmac_f32_e32 v44, v140, v200
	v_fmac_f32_e32 v45, v141, v201
	v_fmac_f32_e32 v46, v142, v202
	v_fmac_f32_e32 v47, v143, v203
	v_fmac_f32_e32 v44, v172, v204
	v_fmac_f32_e32 v45, v173, v205
	v_fmac_f32_e32 v46, v174, v206
	v_fmac_f32_e32 v47, v175, v207
	global_store_dwordx4 v192, v[44:47], s[18:19] offset:3072
	v_lshlrev_b32_e32 v200, 16, v88
	v_and_b32_e32 v201, 0xffff0000, v88
	v_lshlrev_b32_e32 v202, 16, v89
	v_and_b32_e32 v203, 0xffff0000, v89
	v_lshlrev_b32_e32 v204, 16, v120
	v_and_b32_e32 v205, 0xffff0000, v120
	v_lshlrev_b32_e32 v206, 16, v121
	v_and_b32_e32 v207, 0xffff0000, v121
	v_mul_f32_e32 v200, v214, v200
	v_mul_f32_e32 v201, v214, v201
	v_mul_f32_e32 v202, v214, v202
	v_mul_f32_e32 v203, v214, v203
	v_mul_f32_e32 v204, v215, v204
	v_mul_f32_e32 v205, v215, v205
	v_mul_f32_e32 v206, v215, v206
	v_mul_f32_e32 v207, v215, v207
	v_fmac_f32_e32 v48, v144, v200
	v_fmac_f32_e32 v49, v145, v201
	v_fmac_f32_e32 v50, v146, v202
	v_fmac_f32_e32 v51, v147, v203
	v_fmac_f32_e32 v48, v176, v204
	v_fmac_f32_e32 v49, v177, v205
	v_fmac_f32_e32 v50, v178, v206
	v_fmac_f32_e32 v51, v179, v207
	global_store_dwordx4 v193, v[48:51], s[18:19] offset:0
	v_lshlrev_b32_e32 v200, 16, v90
	v_and_b32_e32 v201, 0xffff0000, v90
	v_lshlrev_b32_e32 v202, 16, v91
	v_and_b32_e32 v203, 0xffff0000, v91
	v_lshlrev_b32_e32 v204, 16, v122
	v_and_b32_e32 v205, 0xffff0000, v122
	v_lshlrev_b32_e32 v206, 16, v123
	v_and_b32_e32 v207, 0xffff0000, v123
	v_mul_f32_e32 v200, v214, v200
	v_mul_f32_e32 v201, v214, v201
	v_mul_f32_e32 v202, v214, v202
	v_mul_f32_e32 v203, v214, v203
	v_mul_f32_e32 v204, v215, v204
	v_mul_f32_e32 v205, v215, v205
	v_mul_f32_e32 v206, v215, v206
	v_mul_f32_e32 v207, v215, v207
	v_fmac_f32_e32 v52, v148, v200
	v_fmac_f32_e32 v53, v149, v201
	v_fmac_f32_e32 v54, v150, v202
	v_fmac_f32_e32 v55, v151, v203
	v_fmac_f32_e32 v52, v180, v204
	v_fmac_f32_e32 v53, v181, v205
	v_fmac_f32_e32 v54, v182, v206
	v_fmac_f32_e32 v55, v183, v207
	global_store_dwordx4 v193, v[52:55], s[18:19] offset:1024
	v_lshlrev_b32_e32 v200, 16, v92
	v_and_b32_e32 v201, 0xffff0000, v92
	v_lshlrev_b32_e32 v202, 16, v93
	v_and_b32_e32 v203, 0xffff0000, v93
	v_lshlrev_b32_e32 v204, 16, v124
	v_and_b32_e32 v205, 0xffff0000, v124
	v_lshlrev_b32_e32 v206, 16, v125
	v_and_b32_e32 v207, 0xffff0000, v125
	v_mul_f32_e32 v200, v214, v200
	v_mul_f32_e32 v201, v214, v201
	v_mul_f32_e32 v202, v214, v202
	v_mul_f32_e32 v203, v214, v203
	v_mul_f32_e32 v204, v215, v204
; __device__ __forceinline__ float bf_lo(unsigned w) { return __uint_as_float(w << 16); }
; __device__ __forceinline__ float bf_hi(unsigned w) { return __uint_as_float(w & 0xffff0000u); }
; __global__ void __launch_bounds__(NWAVES * 64, 2) mk_fwd(Args args) {
;     ...
;         for (int row0 = rbeg; row0 < rbeg + per2 && row0 < ML; row0 += 2) {
;             f32x4 v[2][8]; u32x2 yw[2][8];
; #pragma unroll
;             for (int q = 0; q < 2; ++q) { const int row = row0 + q; load_row_f32(args.out + (size_t)row * DM, F.lane, v[q]);
;                 const bf16_t* yr = Y + (size_t)row * DM;
; #pragma unroll
;                 for (int j = 0; j < 8; ++j) yw[q][j] = *(const u32x2*)(yr + 4 * F.lane + 256 * j); }
; #pragma unroll
;             for (int q = 0; q < 2; ++q) { const int row = row0 + q; const int r = row / SEQ;
;                 if (r != rcur) { const float* m1 = mod + (size_t)(9 + r) * 6144; rcur = r;
; #pragma unroll
;                     for (int j = 0; j < 8; ++j) { const int col = 4 * F.lane + 256 * j; PA[j] = *(const f32x4*)(m1 + 2 * DM + col) * *(const f32x4*)(post_norm + DM + col); } }
;                 float sy = 0.f;
; #pragma unroll
;                 for (int j = 0; j < 8; ++j) { const float a = bf_lo(yw[q][j].x), b = bf_hi(yw[q][j].x), c2 = bf_lo(yw[q][j].y), d = bf_hi(yw[q][j].y); sy += (a * a + b * b) + (c2 * c2 + d * d); }
	v_mul_f32_e32 v205, v215, v205
	v_mul_f32_e32 v206, v215, v206
	v_mul_f32_e32 v207, v215, v207
	v_fmac_f32_e32 v56, v152, v200
	v_fmac_f32_e32 v57, v153, v201
	v_fmac_f32_e32 v58, v154, v202
	v_fmac_f32_e32 v59, v155, v203
	v_fmac_f32_e32 v56, v184, v204
	v_fmac_f32_e32 v57, v185, v205
	v_fmac_f32_e32 v58, v186, v206
	v_fmac_f32_e32 v59, v187, v207
	global_store_dwordx4 v193, v[56:59], s[18:19] offset:2048
	v_lshlrev_b32_e32 v200, 16, v94
	v_and_b32_e32 v201, 0xffff0000, v94
	v_lshlrev_b32_e32 v202, 16, v95
	v_and_b32_e32 v203, 0xffff0000, v95
	v_lshlrev_b32_e32 v204, 16, v126
	v_and_b32_e32 v205, 0xffff0000, v126
	v_lshlrev_b32_e32 v206, 16, v127
	v_and_b32_e32 v207, 0xffff0000, v127
	v_mul_f32_e32 v200, v214, v200
	v_mul_f32_e32 v201, v214, v201
	v_mul_f32_e32 v202, v214, v202
	v_mul_f32_e32 v203, v214, v203
	v_mul_f32_e32 v204, v215, v204
	v_mul_f32_e32 v205, v215, v205
	v_mul_f32_e32 v206, v215, v206
	v_mul_f32_e32 v207, v215, v207
	v_fmac_f32_e32 v60, v156, v200
	v_fmac_f32_e32 v61, v157, v201
	v_fmac_f32_e32 v62, v158, v202
	v_fmac_f32_e32 v63, v159, v203
	v_fmac_f32_e32 v60, v188, v204
	v_fmac_f32_e32 v61, v189, v205
	v_fmac_f32_e32 v62, v190, v206
	v_fmac_f32_e32 v63, v191, v207
	global_store_dwordx4 v193, v[60:63], s[18:19] offset:3072
	s_add_u32 s18, s18, 0x2000
	s_addc_u32 s19, s19, 0
	global_load_dwordx4 v[32:35], v192, s[14:15] offset:0 nt
	global_load_dwordx4 v[36:39], v192, s[14:15] offset:1024 nt
	global_load_dwordx4 v[40:43], v192, s[14:15] offset:2048 nt
	global_load_dwordx4 v[44:47], v192, s[14:15] offset:3072 nt
	global_load_dwordx4 v[48:51], v193, s[14:15] offset:0 nt
	global_load_dwordx4 v[52:55], v193, s[14:15] offset:1024 nt
	global_load_dwordx4 v[56:59], v193, s[14:15] offset:2048 nt
	global_load_dwordx4 v[60:63], v193, s[14:15] offset:3072 nt
	global_load_dwordx2 v[80:81], v194, s[16:17] offset:0
	global_load_dwordx2 v[82:83], v194, s[16:17] offset:512
	global_load_dwordx2 v[84:85], v194, s[16:17] offset:1024
	global_load_dwordx2 v[86:87], v194, s[16:17] offset:1536
	global_load_dwordx2 v[88:89], v194, s[16:17] offset:2048
	global_load_dwordx2 v[90:91], v194, s[16:17] offset:2560
	global_load_dwordx2 v[92:93], v194, s[16:17] offset:3072
	global_load_dwordx2 v[94:95], v194, s[16:17] offset:3584
	global_load_dwordx2 v[112:113], v194, s[22:23] offset:0
	global_load_dwordx2 v[114:115], v194, s[22:23] offset:512
	global_load_dwordx2 v[116:117], v194, s[22:23] offset:1024
	global_load_dwordx2 v[118:119], v194, s[22:23] offset:1536
	global_load_dwordx2 v[120:121], v194, s[22:23] offset:2048
	global_load_dwordx2 v[122:123], v194, s[22:23] offset:2560
	global_load_dwordx2 v[124:125], v194, s[22:23] offset:3072
	global_load_dwordx2 v[126:127], v194, s[22:23] offset:3584
	s_add_u32 s14, s14, 0x2000
	s_addc_u32 s15, s15, 0
	s_add_u32 s16, s16, 0x1000
	s_addc_u32 s17, s17, 0
	s_add_u32 s22, s22, 0x1000
	s_addc_u32 s23, s23, 0
	s_waitcnt vmcnt(32)
	v_lshlrev_b32_e32 v200, 16, v64
	v_and_b32_e32 v201, 0xffff0000, v64
	v_lshlrev_b32_e32 v202, 16, v65
	v_and_b32_e32 v203, 0xffff0000, v65
	v_mul_f32_e32 v208, v200, v200
	v_mul_f32_e32 v209, v201, v201
	v_fmac_f32_e32 v208, v202, v202
	v_fmac_f32_e32 v209, v203, v203
	v_lshlrev_b32_e32 v204, 16, v96
	v_and_b32_e32 v205, 0xffff0000, v96
	v_lshlrev_b32_e32 v206, 16, v97
	v_and_b32_e32 v207, 0xffff0000, v97
	v_mul_f32_e32 v210, v204, v204
	v_mul_f32_e32 v211, v205, v205
	v_fmac_f32_e32 v210, v206, v206
	v_fmac_f32_e32 v211, v207, v207
	v_lshlrev_b32_e32 v200, 16, v66
	v_and_b32_e32 v201, 0xffff0000, v66
	v_lshlrev_b32_e32 v202, 16, v67
	v_and_b32_e32 v203, 0xffff0000, v67
	v_fmac_f32_e32 v208, v200, v200
	v_fmac_f32_e32 v209, v201, v201
	v_fmac_f32_e32 v208, v202, v202
	v_fmac_f32_e32 v209, v203, v203
	v_lshlrev_b32_e32 v204, 16, v98
	v_and_b32_e32 v205, 0xffff0000, v98
	v_lshlrev_b32_e32 v206, 16, v99
	v_and_b32_e32 v207, 0xffff0000, v99
	v_fmac_f32_e32 v210, v204, v204
	v_fmac_f32_e32 v211, v205, v205
	v_fmac_f32_e32 v210, v206, v206
	v_fmac_f32_e32 v211, v207, v207
	v_lshlrev_b32_e32 v200, 16, v68
	v_and_b32_e32 v201, 0xffff0000, v68
	v_lshlrev_b32_e32 v202, 16, v69
	v_and_b32_e32 v203, 0xffff0000, v69
	v_fmac_f32_e32 v208, v200, v200
	v_fmac_f32_e32 v209, v201, v201
	v_fmac_f32_e32 v208, v202, v202
	v_fmac_f32_e32 v209, v203, v203
	v_lshlrev_b32_e32 v204, 16, v100
	v_and_b32_e32 v205, 0xffff0000, v100
	v_lshlrev_b32_e32 v206, 16, v101
	v_and_b32_e32 v207, 0xffff0000, v101
	v_fmac_f32_e32 v210, v204, v204
	v_fmac_f32_e32 v211, v205, v205
	v_fmac_f32_e32 v210, v206, v206
	v_fmac_f32_e32 v211, v207, v207
	v_lshlrev_b32_e32 v200, 16, v70
	v_and_b32_e32 v201, 0xffff0000, v70
	v_lshlrev_b32_e32 v202, 16, v71
	v_and_b32_e32 v203, 0xffff0000, v71
	v_fmac_f32_e32 v208, v200, v200
	v_fmac_f32_e32 v209, v201, v201
	v_fmac_f32_e32 v208, v202, v202
	v_fmac_f32_e32 v209, v203, v203
	v_lshlrev_b32_e32 v204, 16, v102
	v_and_b32_e32 v205, 0xffff0000, v102
	v_lshlrev_b32_e32 v206, 16, v103
	v_and_b32_e32 v207, 0xffff0000, v103
	v_fmac_f32_e32 v210, v204, v204
	v_fmac_f32_e32 v211, v205, v205
	v_fmac_f32_e32 v210, v206, v206
	v_fmac_f32_e32 v211, v207, v207
	v_lshlrev_b32_e32 v200, 16, v72
	v_and_b32_e32 v201, 0xffff0000, v72
	v_lshlrev_b32_e32 v202, 16, v73
	v_and_b32_e32 v203, 0xffff0000, v73
	v_fmac_f32_e32 v208, v200, v200
	v_fmac_f32_e32 v209, v201, v201
	v_fmac_f32_e32 v208, v202, v202
	v_fmac_f32_e32 v209, v203, v203
	v_lshlrev_b32_e32 v204, 16, v104
	v_and_b32_e32 v205, 0xffff0000, v104
	v_lshlrev_b32_e32 v206, 16, v105
	v_and_b32_e32 v207, 0xffff0000, v105
	v_fmac_f32_e32 v210, v204, v204
	v_fmac_f32_e32 v211, v205, v205
	v_fmac_f32_e32 v210, v206, v206
	v_fmac_f32_e32 v211, v207, v207
; __device__ __forceinline__ float bf_lo(unsigned w) { return __uint_as_float(w << 16); }
; __device__ __forceinline__ float bf_hi(unsigned w) { return __uint_as_float(w & 0xffff0000u); }
; __global__ void __launch_bounds__(NWAVES * 64, 2) mk_fwd(Args args) {
;     ...
;                 float sy = 0.f;
; #pragma unroll
;                 for (int j = 0; j < 8; ++j) { const float a = bf_lo(yw[q][j].x), b = bf_hi(yw[q][j].x), c2 = bf_lo(yw[q][j].y), d = bf_hi(yw[q][j].y); sy += (a * a + b * b) + (c2 * c2 + d * d); }
;                 const float rsy = __builtin_amdgcn_rsqf(wave_sum(sy) * (1.f / DM) + EPS);
; #pragma unroll
;                 for (int j = 0; j < 8; ++j) { const int col = 4 * F.lane + 256 * j;
;                     const f32x4 y4 = (f32x4){bf_lo(yw[q][j].x), bf_hi(yw[q][j].x), bf_lo(yw[q][j].y), bf_hi(yw[q][j].y)};
;                     *(f32x4*)(args.out + (size_t)row * DM + col) = v[q][j] + PA[j] * (y4 * rsy); }
	v_lshlrev_b32_e32 v200, 16, v74
	v_and_b32_e32 v201, 0xffff0000, v74
	v_lshlrev_b32_e32 v202, 16, v75
	v_and_b32_e32 v203, 0xffff0000, v75
	v_fmac_f32_e32 v208, v200, v200
	v_fmac_f32_e32 v209, v201, v201
	v_fmac_f32_e32 v208, v202, v202
	v_fmac_f32_e32 v209, v203, v203
	v_lshlrev_b32_e32 v204, 16, v106
	v_and_b32_e32 v205, 0xffff0000, v106
	v_lshlrev_b32_e32 v206, 16, v107
	v_and_b32_e32 v207, 0xffff0000, v107
	v_fmac_f32_e32 v210, v204, v204
	v_fmac_f32_e32 v211, v205, v205
	v_fmac_f32_e32 v210, v206, v206
	v_fmac_f32_e32 v211, v207, v207
	v_lshlrev_b32_e32 v200, 16, v76
	v_and_b32_e32 v201, 0xffff0000, v76
	v_lshlrev_b32_e32 v202, 16, v77
	v_and_b32_e32 v203, 0xffff0000, v77
	v_fmac_f32_e32 v208, v200, v200
	v_fmac_f32_e32 v209, v201, v201
	v_fmac_f32_e32 v208, v202, v202
	v_fmac_f32_e32 v209, v203, v203
	v_lshlrev_b32_e32 v204, 16, v108
	v_and_b32_e32 v205, 0xffff0000, v108
	v_lshlrev_b32_e32 v206, 16, v109
	v_and_b32_e32 v207, 0xffff0000, v109
	v_fmac_f32_e32 v210, v204, v204
	v_fmac_f32_e32 v211, v205, v205
	v_fmac_f32_e32 v210, v206, v206
	v_fmac_f32_e32 v211, v207, v207
	v_lshlrev_b32_e32 v200, 16, v78
	v_and_b32_e32 v201, 0xffff0000, v78
	v_lshlrev_b32_e32 v202, 16, v79
	v_and_b32_e32 v203, 0xffff0000, v79
	v_fmac_f32_e32 v208, v200, v200
	v_fmac_f32_e32 v209, v201, v201
	v_fmac_f32_e32 v208, v202, v202
	v_fmac_f32_e32 v209, v203, v203
	v_lshlrev_b32_e32 v204, 16, v110
	v_and_b32_e32 v205, 0xffff0000, v110
	v_lshlrev_b32_e32 v206, 16, v111
	v_and_b32_e32 v207, 0xffff0000, v111
	v_fmac_f32_e32 v210, v204, v204
	v_fmac_f32_e32 v211, v205, v205
	v_fmac_f32_e32 v210, v206, v206
	v_fmac_f32_e32 v211, v207, v207
	v_add_f32_e32 v208, v208, v209
	v_add_f32_e32 v210, v210, v211
	s_nop 0
	v_add_f32_dpp v212, v208, v208 quad_perm:[1,0,3,2] row_mask:0xf bank_mask:0xf
	v_add_f32_dpp v213, v210, v210 quad_perm:[1,0,3,2] row_mask:0xf bank_mask:0xf
	s_nop 0
	v_add_f32_dpp v212, v212, v212 quad_perm:[2,3,0,1] row_mask:0xf bank_mask:0xf
	v_add_f32_dpp v213, v213, v213 quad_perm:[2,3,0,1] row_mask:0xf bank_mask:0xf
	s_nop 0
	v_add_f32_dpp v212, v212, v212 row_half_mirror row_mask:0xf bank_mask:0xf
	v_add_f32_dpp v213, v213, v213 row_half_mirror row_mask:0xf bank_mask:0xf
	s_nop 0
	v_add_f32_dpp v212, v212, v212 row_mirror row_mask:0xf bank_mask:0xf
	v_add_f32_dpp v213, v213, v213 row_mirror row_mask:0xf bank_mask:0xf
	s_nop 0
	v_readlane_b32 s4, v212, 0
	v_readlane_b32 s5, v212, 16
	v_readlane_b32 s6, v212, 32
	v_readlane_b32 s7, v212, 48
	v_readlane_b32 s24, v213, 0
	v_readlane_b32 s25, v213, 16
	v_readlane_b32 s26, v213, 32
	v_readlane_b32 s27, v213, 48
	s_nop 1
	v_mov_b32_e32 v214, s4
	v_mov_b32_e32 v215, s24
	v_add_f32_e32 v214, s5, v214
	v_add_f32_e32 v215, s25, v215
	v_add_f32_e32 v214, s6, v214
	v_add_f32_e32 v215, s26, v215
	v_add_f32_e32 v214, s7, v214
	v_add_f32_e32 v215, s27, v215
	v_fmamk_f32 v214, v214, 0x3a000000, v195
	v_fmamk_f32 v215, v215, 0x3a000000, v195
	v_rsq_f32_e32 v214, v214
	v_rsq_f32_e32 v215, v215
	s_nop 0
	v_lshlrev_b32_e32 v200, 16, v64
	v_and_b32_e32 v201, 0xffff0000, v64
	v_lshlrev_b32_e32 v202, 16, v65
	v_and_b32_e32 v203, 0xffff0000, v65
	v_lshlrev_b32_e32 v204, 16, v96
	v_and_b32_e32 v205, 0xffff0000, v96
	v_lshlrev_b32_e32 v206, 16, v97
	v_and_b32_e32 v207, 0xffff0000, v97
	v_mul_f32_e32 v200, v214, v200
	v_mul_f32_e32 v201, v214, v201
	v_mul_f32_e32 v202, v214, v202
	v_mul_f32_e32 v203, v214, v203
	v_mul_f32_e32 v204, v215, v204
	v_mul_f32_e32 v205, v215, v205
	v_mul_f32_e32 v206, v215, v206
	v_mul_f32_e32 v207, v215, v207
	v_fmac_f32_e32 v0, v128, v200
	v_fmac_f32_e32 v1, v129, v201
	v_fmac_f32_e32 v2, v130, v202
	v_fmac_f32_e32 v3, v131, v203
	v_fmac_f32_e32 v0, v160, v204
	v_fmac_f32_e32 v1, v161, v205
	v_fmac_f32_e32 v2, v162, v206
	v_fmac_f32_e32 v3, v163, v207
	global_store_dwordx4 v192, v[0:3], s[18:19] offset:0
	v_lshlrev_b32_e32 v200, 16, v66
	v_and_b32_e32 v201, 0xffff0000, v66
	v_lshlrev_b32_e32 v202, 16, v67
	v_and_b32_e32 v203, 0xffff0000, v67
	v_lshlrev_b32_e32 v204, 16, v98
	v_and_b32_e32 v205, 0xffff0000, v98
	v_lshlrev_b32_e32 v206, 16, v99
	v_and_b32_e32 v207, 0xffff0000, v99
	v_mul_f32_e32 v200, v214, v200
	v_mul_f32_e32 v201, v214, v201
	v_mul_f32_e32 v202, v214, v202
	v_mul_f32_e32 v203, v214, v203
	v_mul_f32_e32 v204, v215, v204
	v_mul_f32_e32 v205, v215, v205
	v_mul_f32_e32 v206, v215, v206
	v_mul_f32_e32 v207, v215, v207
	v_fmac_f32_e32 v4, v132, v200
	v_fmac_f32_e32 v5, v133, v201
	v_fmac_f32_e32 v6, v134, v202
	v_fmac_f32_e32 v7, v135, v203
	v_fmac_f32_e32 v4, v164, v204
	v_fmac_f32_e32 v5, v165, v205
	v_fmac_f32_e32 v6, v166, v206
	v_fmac_f32_e32 v7, v167, v207
	global_store_dwordx4 v192, v[4:7], s[18:19] offset:1024
	v_lshlrev_b32_e32 v200, 16, v68
	v_and_b32_e32 v201, 0xffff0000, v68
	v_lshlrev_b32_e32 v202, 16, v69
	v_and_b32_e32 v203, 0xffff0000, v69
	v_lshlrev_b32_e32 v204, 16, v100
	v_and_b32_e32 v205, 0xffff0000, v100
	v_lshlrev_b32_e32 v206, 16, v101
	v_and_b32_e32 v207, 0xffff0000, v101
	v_mul_f32_e32 v200, v214, v200
	v_mul_f32_e32 v201, v214, v201
	v_mul_f32_e32 v202, v214, v202
	v_mul_f32_e32 v203, v214, v203
	v_mul_f32_e32 v204, v215, v204
	v_mul_f32_e32 v205, v215, v205
	v_mul_f32_e32 v206, v215, v206
	v_mul_f32_e32 v207, v215, v207
	v_fmac_f32_e32 v8, v136, v200
	v_fmac_f32_e32 v9, v137, v201
	v_fmac_f32_e32 v10, v138, v202
	v_fmac_f32_e32 v11, v139, v203
	v_fmac_f32_e32 v8, v168, v204
	v_fmac_f32_e32 v9, v169, v205
	v_fmac_f32_e32 v10, v170, v206
	v_fmac_f32_e32 v11, v171, v207
	global_store_dwordx4 v192, v[8:11], s[18:19] offset:2048
	v_lshlrev_b32_e32 v200, 16, v70
	v_and_b32_e32 v201, 0xffff0000, v70
	v_lshlrev_b32_e32 v202, 16, v71
	v_and_b32_e32 v203, 0xffff0000, v71
; __device__ __forceinline__ float bf_lo(unsigned w) { return __uint_as_float(w << 16); }
; __device__ __forceinline__ float bf_hi(unsigned w) { return __uint_as_float(w & 0xffff0000u); }
; __global__ void __launch_bounds__(NWAVES * 64, 2) mk_fwd(Args args) {
;     ...
;             for (int q = 0; q < 2; ++q) { const int row = row0 + q; load_row_f32(args.out + (size_t)row * DM, F.lane, v[q]);
;                 const bf16_t* yr = Y + (size_t)row * DM;
; #pragma unroll
;                 for (int j = 0; j < 8; ++j) yw[q][j] = *(const u32x2*)(yr + 4 * F.lane + 256 * j); }
; #pragma unroll
;             for (int q = 0; q < 2; ++q) { const int row = row0 + q; const int r = row / SEQ;
;                 if (r != rcur) { const float* m1 = mod + (size_t)(9 + r) * 6144; rcur = r;
; #pragma unroll
;                     for (int j = 0; j < 8; ++j) { const int col = 4 * F.lane + 256 * j; PA[j] = *(const f32x4*)(m1 + 2 * DM + col) * *(const f32x4*)(post_norm + DM + col); } }
;                 float sy = 0.f;
; #pragma unroll
;                 for (int j = 0; j < 8; ++j) { const float a = bf_lo(yw[q][j].x), b = bf_hi(yw[q][j].x), c2 = bf_lo(yw[q][j].y), d = bf_hi(yw[q][j].y); sy += (a * a + b * b) + (c2 * c2 + d * d); }
;                 const float rsy = __builtin_amdgcn_rsqf(wave_sum(sy) * (1.f / DM) + EPS);
; #pragma unroll
;                 for (int j = 0; j < 8; ++j) { const int col = 4 * F.lane + 256 * j;
;                     const f32x4 y4 = (f32x4){bf_lo(yw[q][j].x), bf_hi(yw[q][j].x), bf_lo(yw[q][j].y), bf_hi(yw[q][j].y)};
;                     *(f32x4*)(args.out + (size_t)row * DM + col) = v[q][j] + PA[j] * (y4 * rsy); }
	v_lshlrev_b32_e32 v204, 16, v102
	v_and_b32_e32 v205, 0xffff0000, v102
	v_lshlrev_b32_e32 v206, 16, v103
	v_and_b32_e32 v207, 0xffff0000, v103
	v_mul_f32_e32 v200, v214, v200
	v_mul_f32_e32 v201, v214, v201
	v_mul_f32_e32 v202, v214, v202
	v_mul_f32_e32 v203, v214, v203
	v_mul_f32_e32 v204, v215, v204
	v_mul_f32_e32 v205, v215, v205
	v_mul_f32_e32 v206, v215, v206
	v_mul_f32_e32 v207, v215, v207
	v_fmac_f32_e32 v12, v140, v200
	v_fmac_f32_e32 v13, v141, v201
	v_fmac_f32_e32 v14, v142, v202
	v_fmac_f32_e32 v15, v143, v203
	v_fmac_f32_e32 v12, v172, v204
	v_fmac_f32_e32 v13, v173, v205
	v_fmac_f32_e32 v14, v174, v206
	v_fmac_f32_e32 v15, v175, v207
	global_store_dwordx4 v192, v[12:15], s[18:19] offset:3072
	v_lshlrev_b32_e32 v200, 16, v72
	v_and_b32_e32 v201, 0xffff0000, v72
	v_lshlrev_b32_e32 v202, 16, v73
	v_and_b32_e32 v203, 0xffff0000, v73
	v_lshlrev_b32_e32 v204, 16, v104
	v_and_b32_e32 v205, 0xffff0000, v104
	v_lshlrev_b32_e32 v206, 16, v105
	v_and_b32_e32 v207, 0xffff0000, v105
	v_mul_f32_e32 v200, v214, v200
	v_mul_f32_e32 v201, v214, v201
	v_mul_f32_e32 v202, v214, v202
	v_mul_f32_e32 v203, v214, v203
	v_mul_f32_e32 v204, v215, v204
	v_mul_f32_e32 v205, v215, v205
	v_mul_f32_e32 v206, v215, v206
	v_mul_f32_e32 v207, v215, v207
	v_fmac_f32_e32 v16, v144, v200
	v_fmac_f32_e32 v17, v145, v201
	v_fmac_f32_e32 v18, v146, v202
	v_fmac_f32_e32 v19, v147, v203
	v_fmac_f32_e32 v16, v176, v204
	v_fmac_f32_e32 v17, v177, v205
	v_fmac_f32_e32 v18, v178, v206
	v_fmac_f32_e32 v19, v179, v207
	global_store_dwordx4 v193, v[16:19], s[18:19] offset:0
	v_lshlrev_b32_e32 v200, 16, v74
	v_and_b32_e32 v201, 0xffff0000, v74
	v_lshlrev_b32_e32 v202, 16, v75
	v_and_b32_e32 v203, 0xffff0000, v75
	v_lshlrev_b32_e32 v204, 16, v106
	v_and_b32_e32 v205, 0xffff0000, v106
	v_lshlrev_b32_e32 v206, 16, v107
	v_and_b32_e32 v207, 0xffff0000, v107
	v_mul_f32_e32 v200, v214, v200
	v_mul_f32_e32 v201, v214, v201
	v_mul_f32_e32 v202, v214, v202
	v_mul_f32_e32 v203, v214, v203
	v_mul_f32_e32 v204, v215, v204
	v_mul_f32_e32 v205, v215, v205
	v_mul_f32_e32 v206, v215, v206
	v_mul_f32_e32 v207, v215, v207
	v_fmac_f32_e32 v20, v148, v200
	v_fmac_f32_e32 v21, v149, v201
	v_fmac_f32_e32 v22, v150, v202
	v_fmac_f32_e32 v23, v151, v203
	v_fmac_f32_e32 v20, v180, v204
	v_fmac_f32_e32 v21, v181, v205
	v_fmac_f32_e32 v22, v182, v206
	v_fmac_f32_e32 v23, v183, v207
	global_store_dwordx4 v193, v[20:23], s[18:19] offset:1024
	v_lshlrev_b32_e32 v200, 16, v76
	v_and_b32_e32 v201, 0xffff0000, v76
	v_lshlrev_b32_e32 v202, 16, v77
	v_and_b32_e32 v203, 0xffff0000, v77
	v_lshlrev_b32_e32 v204, 16, v108
	v_and_b32_e32 v205, 0xffff0000, v108
	v_lshlrev_b32_e32 v206, 16, v109
	v_and_b32_e32 v207, 0xffff0000, v109
	v_mul_f32_e32 v200, v214, v200
	v_mul_f32_e32 v201, v214, v201
	v_mul_f32_e32 v202, v214, v202
	v_mul_f32_e32 v203, v214, v203
	v_mul_f32_e32 v204, v215, v204
	v_mul_f32_e32 v205, v215, v205
	v_mul_f32_e32 v206, v215, v206
	v_mul_f32_e32 v207, v215, v207
	v_fmac_f32_e32 v24, v152, v200
	v_fmac_f32_e32 v25, v153, v201
	v_fmac_f32_e32 v26, v154, v202
	v_fmac_f32_e32 v27, v155, v203
	v_fmac_f32_e32 v24, v184, v204
	v_fmac_f32_e32 v25, v185, v205
	v_fmac_f32_e32 v26, v186, v206
	v_fmac_f32_e32 v27, v187, v207
	global_store_dwordx4 v193, v[24:27], s[18:19] offset:2048
	v_lshlrev_b32_e32 v200, 16, v78
	v_and_b32_e32 v201, 0xffff0000, v78
	v_lshlrev_b32_e32 v202, 16, v79
	v_and_b32_e32 v203, 0xffff0000, v79
	v_lshlrev_b32_e32 v204, 16, v110
	v_and_b32_e32 v205, 0xffff0000, v110
	v_lshlrev_b32_e32 v206, 16, v111
	v_and_b32_e32 v207, 0xffff0000, v111
	v_mul_f32_e32 v200, v214, v200
	v_mul_f32_e32 v201, v214, v201
	v_mul_f32_e32 v202, v214, v202
	v_mul_f32_e32 v203, v214, v203
	v_mul_f32_e32 v204, v215, v204
	v_mul_f32_e32 v205, v215, v205
	v_mul_f32_e32 v206, v215, v206
	v_mul_f32_e32 v207, v215, v207
	v_fmac_f32_e32 v28, v156, v200
	v_fmac_f32_e32 v29, v157, v201
	v_fmac_f32_e32 v30, v158, v202
	v_fmac_f32_e32 v31, v159, v203
	v_fmac_f32_e32 v28, v188, v204
	v_fmac_f32_e32 v29, v189, v205
	v_fmac_f32_e32 v30, v190, v206
	v_fmac_f32_e32 v31, v191, v207
	global_store_dwordx4 v193, v[28:31], s[18:19] offset:3072
	s_add_u32 s18, s18, 0x2000
	s_addc_u32 s19, s19, 0
	global_load_dwordx4 v[0:3], v192, s[14:15] offset:0 nt
	global_load_dwordx4 v[4:7], v192, s[14:15] offset:1024 nt
	global_load_dwordx4 v[8:11], v192, s[14:15] offset:2048 nt
	global_load_dwordx4 v[12:15], v192, s[14:15] offset:3072 nt
	global_load_dwordx4 v[16:19], v193, s[14:15] offset:0 nt
	global_load_dwordx4 v[20:23], v193, s[14:15] offset:1024 nt
	global_load_dwordx4 v[24:27], v193, s[14:15] offset:2048 nt
	global_load_dwordx4 v[28:31], v193, s[14:15] offset:3072 nt
	global_load_dwordx2 v[64:65], v194, s[16:17] offset:0
	global_load_dwordx2 v[66:67], v194, s[16:17] offset:512
	global_load_dwordx2 v[68:69], v194, s[16:17] offset:1024
	global_load_dwordx2 v[70:71], v194, s[16:17] offset:1536
	global_load_dwordx2 v[72:73], v194, s[16:17] offset:2048
	global_load_dwordx2 v[74:75], v194, s[16:17] offset:2560
	global_load_dwordx2 v[76:77], v194, s[16:17] offset:3072
	global_load_dwordx2 v[78:79], v194, s[16:17] offset:3584
	global_load_dwordx2 v[96:97], v194, s[22:23] offset:0
	global_load_dwordx2 v[98:99], v194, s[22:23] offset:512
	global_load_dwordx2 v[100:101], v194, s[22:23] offset:1024
	global_load_dwordx2 v[102:103], v194, s[22:23] offset:1536
	global_load_dwordx2 v[104:105], v194, s[22:23] offset:2048
	global_load_dwordx2 v[106:107], v194, s[22:23] offset:2560
	global_load_dwordx2 v[108:109], v194, s[22:23] offset:3072
	global_load_dwordx2 v[110:111], v194, s[22:23] offset:3584
	s_add_u32 s14, s14, 0x2000
	s_addc_u32 s15, s15, 0
	s_add_u32 s16, s16, 0x1000
	s_addc_u32 s17, s17, 0
	s_add_u32 s22, s22, 0x1000
	s_addc_u32 s23, s23, 0
	s_waitcnt vmcnt(32)
; __device__ __forceinline__ float bf_lo(unsigned w) { return __uint_as_float(w << 16); }
; __device__ __forceinline__ float bf_hi(unsigned w) { return __uint_as_float(w & 0xffff0000u); }
; __global__ void __launch_bounds__(NWAVES * 64, 2) mk_fwd(Args args) {
;     ...
;                 float sy = 0.f;
; #pragma unroll
;                 for (int j = 0; j < 8; ++j) { const float a = bf_lo(yw[q][j].x), b = bf_hi(yw[q][j].x), c2 = bf_lo(yw[q][j].y), d = bf_hi(yw[q][j].y); sy += (a * a + b * b) + (c2 * c2 + d * d); }
;                 const float rsy = __builtin_amdgcn_rsqf(wave_sum(sy) * (1.f / DM) + EPS);
	v_lshlrev_b32_e32 v200, 16, v80
	v_and_b32_e32 v201, 0xffff0000, v80
	v_lshlrev_b32_e32 v202, 16, v81
	v_and_b32_e32 v203, 0xffff0000, v81
	v_mul_f32_e32 v208, v200, v200
	v_mul_f32_e32 v209, v201, v201
	v_fmac_f32_e32 v208, v202, v202
	v_fmac_f32_e32 v209, v203, v203
	v_lshlrev_b32_e32 v204, 16, v112
	v_and_b32_e32 v205, 0xffff0000, v112
	v_lshlrev_b32_e32 v206, 16, v113
	v_and_b32_e32 v207, 0xffff0000, v113
	v_mul_f32_e32 v210, v204, v204
	v_mul_f32_e32 v211, v205, v205
	v_fmac_f32_e32 v210, v206, v206
	v_fmac_f32_e32 v211, v207, v207
	v_lshlrev_b32_e32 v200, 16, v82
	v_and_b32_e32 v201, 0xffff0000, v82
	v_lshlrev_b32_e32 v202, 16, v83
	v_and_b32_e32 v203, 0xffff0000, v83
	v_fmac_f32_e32 v208, v200, v200
	v_fmac_f32_e32 v209, v201, v201
	v_fmac_f32_e32 v208, v202, v202
	v_fmac_f32_e32 v209, v203, v203
	v_lshlrev_b32_e32 v204, 16, v114
	v_and_b32_e32 v205, 0xffff0000, v114
	v_lshlrev_b32_e32 v206, 16, v115
	v_and_b32_e32 v207, 0xffff0000, v115
	v_fmac_f32_e32 v210, v204, v204
	v_fmac_f32_e32 v211, v205, v205
	v_fmac_f32_e32 v210, v206, v206
	v_fmac_f32_e32 v211, v207, v207
	v_lshlrev_b32_e32 v200, 16, v84
	v_and_b32_e32 v201, 0xffff0000, v84
	v_lshlrev_b32_e32 v202, 16, v85
	v_and_b32_e32 v203, 0xffff0000, v85
	v_fmac_f32_e32 v208, v200, v200
	v_fmac_f32_e32 v209, v201, v201
	v_fmac_f32_e32 v208, v202, v202
	v_fmac_f32_e32 v209, v203, v203
	v_lshlrev_b32_e32 v204, 16, v116
	v_and_b32_e32 v205, 0xffff0000, v116
	v_lshlrev_b32_e32 v206, 16, v117
	v_and_b32_e32 v207, 0xffff0000, v117
	v_fmac_f32_e32 v210, v204, v204
	v_fmac_f32_e32 v211, v205, v205
	v_fmac_f32_e32 v210, v206, v206
	v_fmac_f32_e32 v211, v207, v207
	v_lshlrev_b32_e32 v200, 16, v86
	v_and_b32_e32 v201, 0xffff0000, v86
	v_lshlrev_b32_e32 v202, 16, v87
	v_and_b32_e32 v203, 0xffff0000, v87
	v_fmac_f32_e32 v208, v200, v200
	v_fmac_f32_e32 v209, v201, v201
	v_fmac_f32_e32 v208, v202, v202
	v_fmac_f32_e32 v209, v203, v203
	v_lshlrev_b32_e32 v204, 16, v118
	v_and_b32_e32 v205, 0xffff0000, v118
	v_lshlrev_b32_e32 v206, 16, v119
	v_and_b32_e32 v207, 0xffff0000, v119
	v_fmac_f32_e32 v210, v204, v204
	v_fmac_f32_e32 v211, v205, v205
	v_fmac_f32_e32 v210, v206, v206
	v_fmac_f32_e32 v211, v207, v207
	v_lshlrev_b32_e32 v200, 16, v88
	v_and_b32_e32 v201, 0xffff0000, v88
	v_lshlrev_b32_e32 v202, 16, v89
	v_and_b32_e32 v203, 0xffff0000, v89
	v_fmac_f32_e32 v208, v200, v200
	v_fmac_f32_e32 v209, v201, v201
	v_fmac_f32_e32 v208, v202, v202
	v_fmac_f32_e32 v209, v203, v203
	v_lshlrev_b32_e32 v204, 16, v120
	v_and_b32_e32 v205, 0xffff0000, v120
	v_lshlrev_b32_e32 v206, 16, v121
	v_and_b32_e32 v207, 0xffff0000, v121
	v_fmac_f32_e32 v210, v204, v204
	v_fmac_f32_e32 v211, v205, v205
	v_fmac_f32_e32 v210, v206, v206
	v_fmac_f32_e32 v211, v207, v207
	v_lshlrev_b32_e32 v200, 16, v90
	v_and_b32_e32 v201, 0xffff0000, v90
	v_lshlrev_b32_e32 v202, 16, v91
	v_and_b32_e32 v203, 0xffff0000, v91
	v_fmac_f32_e32 v208, v200, v200
	v_fmac_f32_e32 v209, v201, v201
	v_fmac_f32_e32 v208, v202, v202
	v_fmac_f32_e32 v209, v203, v203
	v_lshlrev_b32_e32 v204, 16, v122
	v_and_b32_e32 v205, 0xffff0000, v122
	v_lshlrev_b32_e32 v206, 16, v123
	v_and_b32_e32 v207, 0xffff0000, v123
	v_fmac_f32_e32 v210, v204, v204
	v_fmac_f32_e32 v211, v205, v205
	v_fmac_f32_e32 v210, v206, v206
	v_fmac_f32_e32 v211, v207, v207
	v_lshlrev_b32_e32 v200, 16, v92
	v_and_b32_e32 v201, 0xffff0000, v92
	v_lshlrev_b32_e32 v202, 16, v93
	v_and_b32_e32 v203, 0xffff0000, v93
	v_fmac_f32_e32 v208, v200, v200
	v_fmac_f32_e32 v209, v201, v201
	v_fmac_f32_e32 v208, v202, v202
	v_fmac_f32_e32 v209, v203, v203
	v_lshlrev_b32_e32 v204, 16, v124
	v_and_b32_e32 v205, 0xffff0000, v124
	v_lshlrev_b32_e32 v206, 16, v125
	v_and_b32_e32 v207, 0xffff0000, v125
	v_fmac_f32_e32 v210, v204, v204
	v_fmac_f32_e32 v211, v205, v205
	v_fmac_f32_e32 v210, v206, v206
	v_fmac_f32_e32 v211, v207, v207
	v_lshlrev_b32_e32 v200, 16, v94
	v_and_b32_e32 v201, 0xffff0000, v94
	v_lshlrev_b32_e32 v202, 16, v95
	v_and_b32_e32 v203, 0xffff0000, v95
	v_fmac_f32_e32 v208, v200, v200
	v_fmac_f32_e32 v209, v201, v201
	v_fmac_f32_e32 v208, v202, v202
	v_fmac_f32_e32 v209, v203, v203
	v_lshlrev_b32_e32 v204, 16, v126
	v_and_b32_e32 v205, 0xffff0000, v126
	v_lshlrev_b32_e32 v206, 16, v127
	v_and_b32_e32 v207, 0xffff0000, v127
	v_fmac_f32_e32 v210, v204, v204
	v_fmac_f32_e32 v211, v205, v205
	v_fmac_f32_e32 v210, v206, v206
	v_fmac_f32_e32 v211, v207, v207
	v_add_f32_e32 v208, v208, v209
	v_add_f32_e32 v210, v210, v211
	s_nop 0
	v_add_f32_dpp v212, v208, v208 quad_perm:[1,0,3,2] row_mask:0xf bank_mask:0xf
	v_add_f32_dpp v213, v210, v210 quad_perm:[1,0,3,2] row_mask:0xf bank_mask:0xf
	s_nop 0
	v_add_f32_dpp v212, v212, v212 quad_perm:[2,3,0,1] row_mask:0xf bank_mask:0xf
	v_add_f32_dpp v213, v213, v213 quad_perm:[2,3,0,1] row_mask:0xf bank_mask:0xf
	s_nop 0
	v_add_f32_dpp v212, v212, v212 row_half_mirror row_mask:0xf bank_mask:0xf
	v_add_f32_dpp v213, v213, v213 row_half_mirror row_mask:0xf bank_mask:0xf
	s_nop 0
	v_add_f32_dpp v212, v212, v212 row_mirror row_mask:0xf bank_mask:0xf
	v_add_f32_dpp v213, v213, v213 row_mirror row_mask:0xf bank_mask:0xf
	s_nop 0
	v_readlane_b32 s4, v212, 0
	v_readlane_b32 s5, v212, 16
	v_readlane_b32 s6, v212, 32
	v_readlane_b32 s7, v212, 48
	v_readlane_b32 s24, v213, 0
	v_readlane_b32 s25, v213, 16
	v_readlane_b32 s26, v213, 32
	v_readlane_b32 s27, v213, 48
	s_nop 1
	v_mov_b32_e32 v214, s4
	v_mov_b32_e32 v215, s24
	v_add_f32_e32 v214, s5, v214
	v_add_f32_e32 v215, s25, v215
	v_add_f32_e32 v214, s6, v214
	v_add_f32_e32 v215, s26, v215
	v_add_f32_e32 v214, s7, v214
	v_add_f32_e32 v215, s27, v215
	v_fmamk_f32 v214, v214, 0x3a000000, v195
	v_fmamk_f32 v215, v215, 0x3a000000, v195
; __device__ __forceinline__ float bf_lo(unsigned w) { return __uint_as_float(w << 16); }
; __device__ __forceinline__ float bf_hi(unsigned w) { return __uint_as_float(w & 0xffff0000u); }
; __global__ void __launch_bounds__(NWAVES * 64, 2) mk_fwd(Args args) {
;     ...
;                 const float rsy = __builtin_amdgcn_rsqf(wave_sum(sy) * (1.f / DM) + EPS);
; #pragma unroll
;                 for (int j = 0; j < 8; ++j) { const int col = 4 * F.lane + 256 * j;
;                     const f32x4 y4 = (f32x4){bf_lo(yw[q][j].x), bf_hi(yw[q][j].x), bf_lo(yw[q][j].y), bf_hi(yw[q][j].y)};
;                     *(f32x4*)(args.out + (size_t)row * DM + col) = v[q][j] + PA[j] * (y4 * rsy); }
	v_rsq_f32_e32 v214, v214
	v_rsq_f32_e32 v215, v215
	s_nop 0
	v_lshlrev_b32_e32 v200, 16, v80
	v_and_b32_e32 v201, 0xffff0000, v80
	v_lshlrev_b32_e32 v202, 16, v81
	v_and_b32_e32 v203, 0xffff0000, v81
	v_lshlrev_b32_e32 v204, 16, v112
	v_and_b32_e32 v205, 0xffff0000, v112
	v_lshlrev_b32_e32 v206, 16, v113
	v_and_b32_e32 v207, 0xffff0000, v113
	v_mul_f32_e32 v200, v214, v200
	v_mul_f32_e32 v201, v214, v201
	v_mul_f32_e32 v202, v214, v202
	v_mul_f32_e32 v203, v214, v203
	v_mul_f32_e32 v204, v215, v204
	v_mul_f32_e32 v205, v215, v205
	v_mul_f32_e32 v206, v215, v206
	v_mul_f32_e32 v207, v215, v207
	v_fmac_f32_e32 v32, v128, v200
	v_fmac_f32_e32 v33, v129, v201
	v_fmac_f32_e32 v34, v130, v202
	v_fmac_f32_e32 v35, v131, v203
	v_fmac_f32_e32 v32, v160, v204
	v_fmac_f32_e32 v33, v161, v205
	v_fmac_f32_e32 v34, v162, v206
	v_fmac_f32_e32 v35, v163, v207
	global_store_dwordx4 v192, v[32:35], s[18:19] offset:0
	v_lshlrev_b32_e32 v200, 16, v82
	v_and_b32_e32 v201, 0xffff0000, v82
	v_lshlrev_b32_e32 v202, 16, v83
	v_and_b32_e32 v203, 0xffff0000, v83
	v_lshlrev_b32_e32 v204, 16, v114
	v_and_b32_e32 v205, 0xffff0000, v114
	v_lshlrev_b32_e32 v206, 16, v115
	v_and_b32_e32 v207, 0xffff0000, v115
	v_mul_f32_e32 v200, v214, v200
	v_mul_f32_e32 v201, v214, v201
	v_mul_f32_e32 v202, v214, v202
	v_mul_f32_e32 v203, v214, v203
	v_mul_f32_e32 v204, v215, v204
	v_mul_f32_e32 v205, v215, v205
	v_mul_f32_e32 v206, v215, v206
	v_mul_f32_e32 v207, v215, v207
	v_fmac_f32_e32 v36, v132, v200
	v_fmac_f32_e32 v37, v133, v201
	v_fmac_f32_e32 v38, v134, v202
	v_fmac_f32_e32 v39, v135, v203
	v_fmac_f32_e32 v36, v164, v204
	v_fmac_f32_e32 v37, v165, v205
	v_fmac_f32_e32 v38, v166, v206
	v_fmac_f32_e32 v39, v167, v207
	global_store_dwordx4 v192, v[36:39], s[18:19] offset:1024
	v_lshlrev_b32_e32 v200, 16, v84
	v_and_b32_e32 v201, 0xffff0000, v84
	v_lshlrev_b32_e32 v202, 16, v85
	v_and_b32_e32 v203, 0xffff0000, v85
	v_lshlrev_b32_e32 v204, 16, v116
	v_and_b32_e32 v205, 0xffff0000, v116
	v_lshlrev_b32_e32 v206, 16, v117
	v_and_b32_e32 v207, 0xffff0000, v117
	v_mul_f32_e32 v200, v214, v200
	v_mul_f32_e32 v201, v214, v201
	v_mul_f32_e32 v202, v214, v202
	v_mul_f32_e32 v203, v214, v203
	v_mul_f32_e32 v204, v215, v204
	v_mul_f32_e32 v205, v215, v205
	v_mul_f32_e32 v206, v215, v206
	v_mul_f32_e32 v207, v215, v207
	v_fmac_f32_e32 v40, v136, v200
	v_fmac_f32_e32 v41, v137, v201
	v_fmac_f32_e32 v42, v138, v202
	v_fmac_f32_e32 v43, v139, v203
	v_fmac_f32_e32 v40, v168, v204
	v_fmac_f32_e32 v41, v169, v205
	v_fmac_f32_e32 v42, v170, v206
	v_fmac_f32_e32 v43, v171, v207
	global_store_dwordx4 v192, v[40:43], s[18:19] offset:2048
	v_lshlrev_b32_e32 v200, 16, v86
	v_and_b32_e32 v201, 0xffff0000, v86
	v_lshlrev_b32_e32 v202, 16, v87
	v_and_b32_e32 v203, 0xffff0000, v87
	v_lshlrev_b32_e32 v204, 16, v118
	v_and_b32_e32 v205, 0xffff0000, v118
	v_lshlrev_b32_e32 v206, 16, v119
	v_and_b32_e32 v207, 0xffff0000, v119
	v_mul_f32_e32 v200, v214, v200
	v_mul_f32_e32 v201, v214, v201
	v_mul_f32_e32 v202, v214, v202
	v_mul_f32_e32 v203, v214, v203
	v_mul_f32_e32 v204, v215, v204
	v_mul_f32_e32 v205, v215, v205
	v_mul_f32_e32 v206, v215, v206
	v_mul_f32_e32 v207, v215, v207
	v_fmac_f32_e32 v44, v140, v200
	v_fmac_f32_e32 v45, v141, v201
	v_fmac_f32_e32 v46, v142, v202
	v_fmac_f32_e32 v47, v143, v203
	v_fmac_f32_e32 v44, v172, v204
	v_fmac_f32_e32 v45, v173, v205
	v_fmac_f32_e32 v46, v174, v206
	v_fmac_f32_e32 v47, v175, v207
	global_store_dwordx4 v192, v[44:47], s[18:19] offset:3072
	v_lshlrev_b32_e32 v200, 16, v88
	v_and_b32_e32 v201, 0xffff0000, v88
	v_lshlrev_b32_e32 v202, 16, v89
	v_and_b32_e32 v203, 0xffff0000, v89
	v_lshlrev_b32_e32 v204, 16, v120
	v_and_b32_e32 v205, 0xffff0000, v120
	v_lshlrev_b32_e32 v206, 16, v121
	v_and_b32_e32 v207, 0xffff0000, v121
	v_mul_f32_e32 v200, v214, v200
	v_mul_f32_e32 v201, v214, v201
	v_mul_f32_e32 v202, v214, v202
	v_mul_f32_e32 v203, v214, v203
	v_mul_f32_e32 v204, v215, v204
	v_mul_f32_e32 v205, v215, v205
	v_mul_f32_e32 v206, v215, v206
	v_mul_f32_e32 v207, v215, v207
	v_fmac_f32_e32 v48, v144, v200
	v_fmac_f32_e32 v49, v145, v201
	v_fmac_f32_e32 v50, v146, v202
	v_fmac_f32_e32 v51, v147, v203
	v_fmac_f32_e32 v48, v176, v204
	v_fmac_f32_e32 v49, v177, v205
	v_fmac_f32_e32 v50, v178, v206
	v_fmac_f32_e32 v51, v179, v207
	global_store_dwordx4 v193, v[48:51], s[18:19] offset:0
	v_lshlrev_b32_e32 v200, 16, v90
	v_and_b32_e32 v201, 0xffff0000, v90
	v_lshlrev_b32_e32 v202, 16, v91
	v_and_b32_e32 v203, 0xffff0000, v91
	v_lshlrev_b32_e32 v204, 16, v122
	v_and_b32_e32 v205, 0xffff0000, v122
	v_lshlrev_b32_e32 v206, 16, v123
	v_and_b32_e32 v207, 0xffff0000, v123
	v_mul_f32_e32 v200, v214, v200
	v_mul_f32_e32 v201, v214, v201
	v_mul_f32_e32 v202, v214, v202
	v_mul_f32_e32 v203, v214, v203
	v_mul_f32_e32 v204, v215, v204
	v_mul_f32_e32 v205, v215, v205
	v_mul_f32_e32 v206, v215, v206
	v_mul_f32_e32 v207, v215, v207
	v_fmac_f32_e32 v52, v148, v200
	v_fmac_f32_e32 v53, v149, v201
	v_fmac_f32_e32 v54, v150, v202
	v_fmac_f32_e32 v55, v151, v203
	v_fmac_f32_e32 v52, v180, v204
	v_fmac_f32_e32 v53, v181, v205
	v_fmac_f32_e32 v54, v182, v206
	v_fmac_f32_e32 v55, v183, v207
	global_store_dwordx4 v193, v[52:55], s[18:19] offset:1024
	v_lshlrev_b32_e32 v200, 16, v92
	v_and_b32_e32 v201, 0xffff0000, v92
	v_lshlrev_b32_e32 v202, 16, v93
	v_and_b32_e32 v203, 0xffff0000, v93
	v_lshlrev_b32_e32 v204, 16, v124
	v_and_b32_e32 v205, 0xffff0000, v124
	v_lshlrev_b32_e32 v206, 16, v125
	v_and_b32_e32 v207, 0xffff0000, v125
	v_mul_f32_e32 v200, v214, v200
	v_mul_f32_e32 v201, v214, v201
	v_mul_f32_e32 v202, v214, v202
	v_mul_f32_e32 v203, v214, v203
	v_mul_f32_e32 v204, v215, v204
; __device__ __forceinline__ float bf_lo(unsigned w) { return __uint_as_float(w << 16); }
; __device__ __forceinline__ float bf_hi(unsigned w) { return __uint_as_float(w & 0xffff0000u); }
; __global__ void __launch_bounds__(NWAVES * 64, 2) mk_fwd(Args args) {
;     ...
;             for (int q = 0; q < 2; ++q) { const int row = row0 + q; load_row_f32(args.out + (size_t)row * DM, F.lane, v[q]);
;                 const bf16_t* yr = Y + (size_t)row * DM;
; #pragma unroll
;                 for (int j = 0; j < 8; ++j) yw[q][j] = *(const u32x2*)(yr + 4 * F.lane + 256 * j); }
; #pragma unroll
;             for (int q = 0; q < 2; ++q) { const int row = row0 + q; const int r = row / SEQ;
;                 if (r != rcur) { const float* m1 = mod + (size_t)(9 + r) * 6144; rcur = r;
; #pragma unroll
;                     for (int j = 0; j < 8; ++j) { const int col = 4 * F.lane + 256 * j; PA[j] = *(const f32x4*)(m1 + 2 * DM + col) * *(const f32x4*)(post_norm + DM + col); } }
;                 float sy = 0.f;
; #pragma unroll
;                 for (int j = 0; j < 8; ++j) { const float a = bf_lo(yw[q][j].x), b = bf_hi(yw[q][j].x), c2 = bf_lo(yw[q][j].y), d = bf_hi(yw[q][j].y); sy += (a * a + b * b) + (c2 * c2 + d * d); }
;                 const float rsy = __builtin_amdgcn_rsqf(wave_sum(sy) * (1.f / DM) + EPS);
; #pragma unroll
;                 for (int j = 0; j < 8; ++j) { const int col = 4 * F.lane + 256 * j;
;                     const f32x4 y4 = (f32x4){bf_lo(yw[q][j].x), bf_hi(yw[q][j].x), bf_lo(yw[q][j].y), bf_hi(yw[q][j].y)};
;                     *(f32x4*)(args.out + (size_t)row * DM + col) = v[q][j] + PA[j] * (y4 * rsy); }
	v_mul_f32_e32 v205, v215, v205
	v_mul_f32_e32 v206, v215, v206
	v_mul_f32_e32 v207, v215, v207
	v_fmac_f32_e32 v56, v152, v200
	v_fmac_f32_e32 v57, v153, v201
	v_fmac_f32_e32 v58, v154, v202
	v_fmac_f32_e32 v59, v155, v203
	v_fmac_f32_e32 v56, v184, v204
	v_fmac_f32_e32 v57, v185, v205
	v_fmac_f32_e32 v58, v186, v206
	v_fmac_f32_e32 v59, v187, v207
	global_store_dwordx4 v193, v[56:59], s[18:19] offset:2048
	v_lshlrev_b32_e32 v200, 16, v94
	v_and_b32_e32 v201, 0xffff0000, v94
	v_lshlrev_b32_e32 v202, 16, v95
	v_and_b32_e32 v203, 0xffff0000, v95
	v_lshlrev_b32_e32 v204, 16, v126
	v_and_b32_e32 v205, 0xffff0000, v126
	v_lshlrev_b32_e32 v206, 16, v127
	v_and_b32_e32 v207, 0xffff0000, v127
	v_mul_f32_e32 v200, v214, v200
	v_mul_f32_e32 v201, v214, v201
	v_mul_f32_e32 v202, v214, v202
	v_mul_f32_e32 v203, v214, v203
	v_mul_f32_e32 v204, v215, v204
	v_mul_f32_e32 v205, v215, v205
	v_mul_f32_e32 v206, v215, v206
	v_mul_f32_e32 v207, v215, v207
	v_fmac_f32_e32 v60, v156, v200
	v_fmac_f32_e32 v61, v157, v201
	v_fmac_f32_e32 v62, v158, v202
	v_fmac_f32_e32 v63, v159, v203
	v_fmac_f32_e32 v60, v188, v204
	v_fmac_f32_e32 v61, v189, v205
	v_fmac_f32_e32 v62, v190, v206
	v_fmac_f32_e32 v63, v191, v207
	global_store_dwordx4 v193, v[60:63], s[18:19] offset:3072
	s_add_u32 s18, s18, 0x2000
	s_addc_u32 s19, s19, 0
	global_load_dwordx4 v[32:35], v192, s[14:15] offset:0 nt
	global_load_dwordx4 v[36:39], v192, s[14:15] offset:1024 nt
	global_load_dwordx4 v[40:43], v192, s[14:15] offset:2048 nt
	global_load_dwordx4 v[44:47], v192, s[14:15] offset:3072 nt
	global_load_dwordx4 v[48:51], v193, s[14:15] offset:0 nt
	global_load_dwordx4 v[52:55], v193, s[14:15] offset:1024 nt
	global_load_dwordx4 v[56:59], v193, s[14:15] offset:2048 nt
	global_load_dwordx4 v[60:63], v193, s[14:15] offset:3072 nt
	global_load_dwordx2 v[80:81], v194, s[16:17] offset:0
	global_load_dwordx2 v[82:83], v194, s[16:17] offset:512
	global_load_dwordx2 v[84:85], v194, s[16:17] offset:1024
	global_load_dwordx2 v[86:87], v194, s[16:17] offset:1536
	global_load_dwordx2 v[88:89], v194, s[16:17] offset:2048
	global_load_dwordx2 v[90:91], v194, s[16:17] offset:2560
	global_load_dwordx2 v[92:93], v194, s[16:17] offset:3072
	global_load_dwordx2 v[94:95], v194, s[16:17] offset:3584
	global_load_dwordx2 v[112:113], v194, s[22:23] offset:0
	global_load_dwordx2 v[114:115], v194, s[22:23] offset:512
	global_load_dwordx2 v[116:117], v194, s[22:23] offset:1024
	global_load_dwordx2 v[118:119], v194, s[22:23] offset:1536
	global_load_dwordx2 v[120:121], v194, s[22:23] offset:2048
	global_load_dwordx2 v[122:123], v194, s[22:23] offset:2560
	global_load_dwordx2 v[124:125], v194, s[22:23] offset:3072
	global_load_dwordx2 v[126:127], v194, s[22:23] offset:3584
	s_add_u32 s14, s14, 0x2000
	s_addc_u32 s15, s15, 0
	s_add_u32 s16, s16, 0x1000
	s_addc_u32 s17, s17, 0
	s_add_u32 s22, s22, 0x1000
	s_addc_u32 s23, s23, 0
	s_waitcnt vmcnt(32)
	v_lshlrev_b32_e32 v200, 16, v64
	v_and_b32_e32 v201, 0xffff0000, v64
	v_lshlrev_b32_e32 v202, 16, v65
	v_and_b32_e32 v203, 0xffff0000, v65
	v_mul_f32_e32 v208, v200, v200
	v_mul_f32_e32 v209, v201, v201
	v_fmac_f32_e32 v208, v202, v202
	v_fmac_f32_e32 v209, v203, v203
	v_lshlrev_b32_e32 v204, 16, v96
	v_and_b32_e32 v205, 0xffff0000, v96
	v_lshlrev_b32_e32 v206, 16, v97
	v_and_b32_e32 v207, 0xffff0000, v97
	v_mul_f32_e32 v210, v204, v204
	v_mul_f32_e32 v211, v205, v205
	v_fmac_f32_e32 v210, v206, v206
	v_fmac_f32_e32 v211, v207, v207
	v_lshlrev_b32_e32 v200, 16, v66
	v_and_b32_e32 v201, 0xffff0000, v66
	v_lshlrev_b32_e32 v202, 16, v67
	v_and_b32_e32 v203, 0xffff0000, v67
	v_fmac_f32_e32 v208, v200, v200
	v_fmac_f32_e32 v209, v201, v201
	v_fmac_f32_e32 v208, v202, v202
	v_fmac_f32_e32 v209, v203, v203
	v_lshlrev_b32_e32 v204, 16, v98
	v_and_b32_e32 v205, 0xffff0000, v98
	v_lshlrev_b32_e32 v206, 16, v99
	v_and_b32_e32 v207, 0xffff0000, v99
	v_fmac_f32_e32 v210, v204, v204
	v_fmac_f32_e32 v211, v205, v205
	v_fmac_f32_e32 v210, v206, v206
	v_fmac_f32_e32 v211, v207, v207
	v_lshlrev_b32_e32 v200, 16, v68
	v_and_b32_e32 v201, 0xffff0000, v68
	v_lshlrev_b32_e32 v202, 16, v69
	v_and_b32_e32 v203, 0xffff0000, v69
	v_fmac_f32_e32 v208, v200, v200
	v_fmac_f32_e32 v209, v201, v201
	v_fmac_f32_e32 v208, v202, v202
	v_fmac_f32_e32 v209, v203, v203
	v_lshlrev_b32_e32 v204, 16, v100
	v_and_b32_e32 v205, 0xffff0000, v100
	v_lshlrev_b32_e32 v206, 16, v101
	v_and_b32_e32 v207, 0xffff0000, v101
	v_fmac_f32_e32 v210, v204, v204
	v_fmac_f32_e32 v211, v205, v205
	v_fmac_f32_e32 v210, v206, v206
	v_fmac_f32_e32 v211, v207, v207
	v_lshlrev_b32_e32 v200, 16, v70
	v_and_b32_e32 v201, 0xffff0000, v70
	v_lshlrev_b32_e32 v202, 16, v71
	v_and_b32_e32 v203, 0xffff0000, v71
	v_fmac_f32_e32 v208, v200, v200
	v_fmac_f32_e32 v209, v201, v201
	v_fmac_f32_e32 v208, v202, v202
	v_fmac_f32_e32 v209, v203, v203
	v_lshlrev_b32_e32 v204, 16, v102
	v_and_b32_e32 v205, 0xffff0000, v102
	v_lshlrev_b32_e32 v206, 16, v103
	v_and_b32_e32 v207, 0xffff0000, v103
	v_fmac_f32_e32 v210, v204, v204
	v_fmac_f32_e32 v211, v205, v205
	v_fmac_f32_e32 v210, v206, v206
	v_fmac_f32_e32 v211, v207, v207
	v_lshlrev_b32_e32 v200, 16, v72
	v_and_b32_e32 v201, 0xffff0000, v72
	v_lshlrev_b32_e32 v202, 16, v73
	v_and_b32_e32 v203, 0xffff0000, v73
	v_fmac_f32_e32 v208, v200, v200
	v_fmac_f32_e32 v209, v201, v201
	v_fmac_f32_e32 v208, v202, v202
	v_fmac_f32_e32 v209, v203, v203
	v_lshlrev_b32_e32 v204, 16, v104
	v_and_b32_e32 v205, 0xffff0000, v104
	v_lshlrev_b32_e32 v206, 16, v105
	v_and_b32_e32 v207, 0xffff0000, v105
	v_fmac_f32_e32 v210, v204, v204
	v_fmac_f32_e32 v211, v205, v205
	v_fmac_f32_e32 v210, v206, v206
	v_fmac_f32_e32 v211, v207, v207
; __device__ __forceinline__ float bf_lo(unsigned w) { return __uint_as_float(w << 16); }
; __device__ __forceinline__ float bf_hi(unsigned w) { return __uint_as_float(w & 0xffff0000u); }
; __global__ void __launch_bounds__(NWAVES * 64, 2) mk_fwd(Args args) {
;     ...
;                 float sy = 0.f;
; #pragma unroll
;                 for (int j = 0; j < 8; ++j) { const float a = bf_lo(yw[q][j].x), b = bf_hi(yw[q][j].x), c2 = bf_lo(yw[q][j].y), d = bf_hi(yw[q][j].y); sy += (a * a + b * b) + (c2 * c2 + d * d); }
;                 const float rsy = __builtin_amdgcn_rsqf(wave_sum(sy) * (1.f / DM) + EPS);
; #pragma unroll
;                 for (int j = 0; j < 8; ++j) { const int col = 4 * F.lane + 256 * j;
;                     const f32x4 y4 = (f32x4){bf_lo(yw[q][j].x), bf_hi(yw[q][j].x), bf_lo(yw[q][j].y), bf_hi(yw[q][j].y)};
;                     *(f32x4*)(args.out + (size_t)row * DM + col) = v[q][j] + PA[j] * (y4 * rsy); }
	v_lshlrev_b32_e32 v200, 16, v74
	v_and_b32_e32 v201, 0xffff0000, v74
	v_lshlrev_b32_e32 v202, 16, v75
	v_and_b32_e32 v203, 0xffff0000, v75
	v_fmac_f32_e32 v208, v200, v200
	v_fmac_f32_e32 v209, v201, v201
	v_fmac_f32_e32 v208, v202, v202
	v_fmac_f32_e32 v209, v203, v203
	v_lshlrev_b32_e32 v204, 16, v106
	v_and_b32_e32 v205, 0xffff0000, v106
	v_lshlrev_b32_e32 v206, 16, v107
	v_and_b32_e32 v207, 0xffff0000, v107
	v_fmac_f32_e32 v210, v204, v204
	v_fmac_f32_e32 v211, v205, v205
	v_fmac_f32_e32 v210, v206, v206
	v_fmac_f32_e32 v211, v207, v207
	v_lshlrev_b32_e32 v200, 16, v76
	v_and_b32_e32 v201, 0xffff0000, v76
	v_lshlrev_b32_e32 v202, 16, v77
	v_and_b32_e32 v203, 0xffff0000, v77
	v_fmac_f32_e32 v208, v200, v200
	v_fmac_f32_e32 v209, v201, v201
	v_fmac_f32_e32 v208, v202, v202
	v_fmac_f32_e32 v209, v203, v203
	v_lshlrev_b32_e32 v204, 16, v108
	v_and_b32_e32 v205, 0xffff0000, v108
	v_lshlrev_b32_e32 v206, 16, v109
	v_and_b32_e32 v207, 0xffff0000, v109
	v_fmac_f32_e32 v210, v204, v204
	v_fmac_f32_e32 v211, v205, v205
	v_fmac_f32_e32 v210, v206, v206
	v_fmac_f32_e32 v211, v207, v207
	v_lshlrev_b32_e32 v200, 16, v78
	v_and_b32_e32 v201, 0xffff0000, v78
	v_lshlrev_b32_e32 v202, 16, v79
	v_and_b32_e32 v203, 0xffff0000, v79
	v_fmac_f32_e32 v208, v200, v200
	v_fmac_f32_e32 v209, v201, v201
	v_fmac_f32_e32 v208, v202, v202
	v_fmac_f32_e32 v209, v203, v203
	v_lshlrev_b32_e32 v204, 16, v110
	v_and_b32_e32 v205, 0xffff0000, v110
	v_lshlrev_b32_e32 v206, 16, v111
	v_and_b32_e32 v207, 0xffff0000, v111
	v_fmac_f32_e32 v210, v204, v204
	v_fmac_f32_e32 v211, v205, v205
	v_fmac_f32_e32 v210, v206, v206
	v_fmac_f32_e32 v211, v207, v207
	v_add_f32_e32 v208, v208, v209
	v_add_f32_e32 v210, v210, v211
	s_nop 0
	v_add_f32_dpp v212, v208, v208 quad_perm:[1,0,3,2] row_mask:0xf bank_mask:0xf
	v_add_f32_dpp v213, v210, v210 quad_perm:[1,0,3,2] row_mask:0xf bank_mask:0xf
	s_nop 0
	v_add_f32_dpp v212, v212, v212 quad_perm:[2,3,0,1] row_mask:0xf bank_mask:0xf
	v_add_f32_dpp v213, v213, v213 quad_perm:[2,3,0,1] row_mask:0xf bank_mask:0xf
	s_nop 0
	v_add_f32_dpp v212, v212, v212 row_half_mirror row_mask:0xf bank_mask:0xf
	v_add_f32_dpp v213, v213, v213 row_half_mirror row_mask:0xf bank_mask:0xf
	s_nop 0
	v_add_f32_dpp v212, v212, v212 row_mirror row_mask:0xf bank_mask:0xf
	v_add_f32_dpp v213, v213, v213 row_mirror row_mask:0xf bank_mask:0xf
	s_nop 0
	v_readlane_b32 s4, v212, 0
	v_readlane_b32 s5, v212, 16
	v_readlane_b32 s6, v212, 32
	v_readlane_b32 s7, v212, 48
	v_readlane_b32 s24, v213, 0
	v_readlane_b32 s25, v213, 16
	v_readlane_b32 s26, v213, 32
	v_readlane_b32 s27, v213, 48
	s_nop 1
	v_mov_b32_e32 v214, s4
	v_mov_b32_e32 v215, s24
	v_add_f32_e32 v214, s5, v214
	v_add_f32_e32 v215, s25, v215
	v_add_f32_e32 v214, s6, v214
	v_add_f32_e32 v215, s26, v215
	v_add_f32_e32 v214, s7, v214
	v_add_f32_e32 v215, s27, v215
	v_fmamk_f32 v214, v214, 0x3a000000, v195
	v_fmamk_f32 v215, v215, 0x3a000000, v195
	v_rsq_f32_e32 v214, v214
	v_rsq_f32_e32 v215, v215
	s_nop 0
	v_lshlrev_b32_e32 v200, 16, v64
	v_and_b32_e32 v201, 0xffff0000, v64
	v_lshlrev_b32_e32 v202, 16, v65
	v_and_b32_e32 v203, 0xffff0000, v65
	v_lshlrev_b32_e32 v204, 16, v96
	v_and_b32_e32 v205, 0xffff0000, v96
	v_lshlrev_b32_e32 v206, 16, v97
	v_and_b32_e32 v207, 0xffff0000, v97
	v_mul_f32_e32 v200, v214, v200
	v_mul_f32_e32 v201, v214, v201
	v_mul_f32_e32 v202, v214, v202
	v_mul_f32_e32 v203, v214, v203
	v_mul_f32_e32 v204, v215, v204
	v_mul_f32_e32 v205, v215, v205
	v_mul_f32_e32 v206, v215, v206
	v_mul_f32_e32 v207, v215, v207
	v_fmac_f32_e32 v0, v128, v200
	v_fmac_f32_e32 v1, v129, v201
	v_fmac_f32_e32 v2, v130, v202
	v_fmac_f32_e32 v3, v131, v203
	v_fmac_f32_e32 v0, v160, v204
	v_fmac_f32_e32 v1, v161, v205
	v_fmac_f32_e32 v2, v162, v206
	v_fmac_f32_e32 v3, v163, v207
	global_store_dwordx4 v192, v[0:3], s[18:19] offset:0
	v_lshlrev_b32_e32 v200, 16, v66
	v_and_b32_e32 v201, 0xffff0000, v66
	v_lshlrev_b32_e32 v202, 16, v67
	v_and_b32_e32 v203, 0xffff0000, v67
	v_lshlrev_b32_e32 v204, 16, v98
	v_and_b32_e32 v205, 0xffff0000, v98
	v_lshlrev_b32_e32 v206, 16, v99
	v_and_b32_e32 v207, 0xffff0000, v99
	v_mul_f32_e32 v200, v214, v200
	v_mul_f32_e32 v201, v214, v201
	v_mul_f32_e32 v202, v214, v202
	v_mul_f32_e32 v203, v214, v203
	v_mul_f32_e32 v204, v215, v204
	v_mul_f32_e32 v205, v215, v205
	v_mul_f32_e32 v206, v215, v206
	v_mul_f32_e32 v207, v215, v207
	v_fmac_f32_e32 v4, v132, v200
	v_fmac_f32_e32 v5, v133, v201
	v_fmac_f32_e32 v6, v134, v202
	v_fmac_f32_e32 v7, v135, v203
	v_fmac_f32_e32 v4, v164, v204
	v_fmac_f32_e32 v5, v165, v205
	v_fmac_f32_e32 v6, v166, v206
	v_fmac_f32_e32 v7, v167, v207
	global_store_dwordx4 v192, v[4:7], s[18:19] offset:1024
	v_lshlrev_b32_e32 v200, 16, v68
	v_and_b32_e32 v201, 0xffff0000, v68
	v_lshlrev_b32_e32 v202, 16, v69
	v_and_b32_e32 v203, 0xffff0000, v69
	v_lshlrev_b32_e32 v204, 16, v100
	v_and_b32_e32 v205, 0xffff0000, v100
	v_lshlrev_b32_e32 v206, 16, v101
	v_and_b32_e32 v207, 0xffff0000, v101
	v_mul_f32_e32 v200, v214, v200
	v_mul_f32_e32 v201, v214, v201
	v_mul_f32_e32 v202, v214, v202
	v_mul_f32_e32 v203, v214, v203
	v_mul_f32_e32 v204, v215, v204
	v_mul_f32_e32 v205, v215, v205
	v_mul_f32_e32 v206, v215, v206
	v_mul_f32_e32 v207, v215, v207
	v_fmac_f32_e32 v8, v136, v200
	v_fmac_f32_e32 v9, v137, v201
	v_fmac_f32_e32 v10, v138, v202
	v_fmac_f32_e32 v11, v139, v203
	v_fmac_f32_e32 v8, v168, v204
	v_fmac_f32_e32 v9, v169, v205
	v_fmac_f32_e32 v10, v170, v206
	v_fmac_f32_e32 v11, v171, v207
	global_store_dwordx4 v192, v[8:11], s[18:19] offset:2048
	v_lshlrev_b32_e32 v200, 16, v70
	v_and_b32_e32 v201, 0xffff0000, v70
	v_lshlrev_b32_e32 v202, 16, v71
	v_and_b32_e32 v203, 0xffff0000, v71
; __device__ __forceinline__ float bf_lo(unsigned w) { return __uint_as_float(w << 16); }
; __device__ __forceinline__ float bf_hi(unsigned w) { return __uint_as_float(w & 0xffff0000u); }
; __global__ void __launch_bounds__(NWAVES * 64, 2) mk_fwd(Args args) {
;     ...
;             for (int q = 0; q < 2; ++q) { const int row = row0 + q; load_row_f32(args.out + (size_t)row * DM, F.lane, v[q]);
;                 const bf16_t* yr = Y + (size_t)row * DM;
; #pragma unroll
;                 for (int j = 0; j < 8; ++j) yw[q][j] = *(const u32x2*)(yr + 4 * F.lane + 256 * j); }
; #pragma unroll
;             for (int q = 0; q < 2; ++q) { const int row = row0 + q; const int r = row / SEQ;
;                 if (r != rcur) { const float* m1 = mod + (size_t)(9 + r) * 6144; rcur = r;
; #pragma unroll
;                     for (int j = 0; j < 8; ++j) { const int col = 4 * F.lane + 256 * j; PA[j] = *(const f32x4*)(m1 + 2 * DM + col) * *(const f32x4*)(post_norm + DM + col); } }
;                 float sy = 0.f;
; #pragma unroll
;                 for (int j = 0; j < 8; ++j) { const float a = bf_lo(yw[q][j].x), b = bf_hi(yw[q][j].x), c2 = bf_lo(yw[q][j].y), d = bf_hi(yw[q][j].y); sy += (a * a + b * b) + (c2 * c2 + d * d); }
;                 const float rsy = __builtin_amdgcn_rsqf(wave_sum(sy) * (1.f / DM) + EPS);
; #pragma unroll
;                 for (int j = 0; j < 8; ++j) { const int col = 4 * F.lane + 256 * j;
;                     const f32x4 y4 = (f32x4){bf_lo(yw[q][j].x), bf_hi(yw[q][j].x), bf_lo(yw[q][j].y), bf_hi(yw[q][j].y)};
;                     *(f32x4*)(args.out + (size_t)row * DM + col) = v[q][j] + PA[j] * (y4 * rsy); }
	v_lshlrev_b32_e32 v204, 16, v102
	v_and_b32_e32 v205, 0xffff0000, v102
	v_lshlrev_b32_e32 v206, 16, v103
	v_and_b32_e32 v207, 0xffff0000, v103
	v_mul_f32_e32 v200, v214, v200
	v_mul_f32_e32 v201, v214, v201
	v_mul_f32_e32 v202, v214, v202
	v_mul_f32_e32 v203, v214, v203
	v_mul_f32_e32 v204, v215, v204
	v_mul_f32_e32 v205, v215, v205
	v_mul_f32_e32 v206, v215, v206
	v_mul_f32_e32 v207, v215, v207
	v_fmac_f32_e32 v12, v140, v200
	v_fmac_f32_e32 v13, v141, v201
	v_fmac_f32_e32 v14, v142, v202
	v_fmac_f32_e32 v15, v143, v203
	v_fmac_f32_e32 v12, v172, v204
	v_fmac_f32_e32 v13, v173, v205
	v_fmac_f32_e32 v14, v174, v206
	v_fmac_f32_e32 v15, v175, v207
	global_store_dwordx4 v192, v[12:15], s[18:19] offset:3072
	v_lshlrev_b32_e32 v200, 16, v72
	v_and_b32_e32 v201, 0xffff0000, v72
	v_lshlrev_b32_e32 v202, 16, v73
	v_and_b32_e32 v203, 0xffff0000, v73
	v_lshlrev_b32_e32 v204, 16, v104
	v_and_b32_e32 v205, 0xffff0000, v104
	v_lshlrev_b32_e32 v206, 16, v105
	v_and_b32_e32 v207, 0xffff0000, v105
	v_mul_f32_e32 v200, v214, v200
	v_mul_f32_e32 v201, v214, v201
	v_mul_f32_e32 v202, v214, v202
	v_mul_f32_e32 v203, v214, v203
	v_mul_f32_e32 v204, v215, v204
	v_mul_f32_e32 v205, v215, v205
	v_mul_f32_e32 v206, v215, v206
	v_mul_f32_e32 v207, v215, v207
	v_fmac_f32_e32 v16, v144, v200
	v_fmac_f32_e32 v17, v145, v201
	v_fmac_f32_e32 v18, v146, v202
	v_fmac_f32_e32 v19, v147, v203
	v_fmac_f32_e32 v16, v176, v204
	v_fmac_f32_e32 v17, v177, v205
	v_fmac_f32_e32 v18, v178, v206
	v_fmac_f32_e32 v19, v179, v207
	global_store_dwordx4 v193, v[16:19], s[18:19] offset:0
	v_lshlrev_b32_e32 v200, 16, v74
	v_and_b32_e32 v201, 0xffff0000, v74
	v_lshlrev_b32_e32 v202, 16, v75
	v_and_b32_e32 v203, 0xffff0000, v75
	v_lshlrev_b32_e32 v204, 16, v106
	v_and_b32_e32 v205, 0xffff0000, v106
	v_lshlrev_b32_e32 v206, 16, v107
	v_and_b32_e32 v207, 0xffff0000, v107
	v_mul_f32_e32 v200, v214, v200
	v_mul_f32_e32 v201, v214, v201
	v_mul_f32_e32 v202, v214, v202
	v_mul_f32_e32 v203, v214, v203
	v_mul_f32_e32 v204, v215, v204
	v_mul_f32_e32 v205, v215, v205
	v_mul_f32_e32 v206, v215, v206
	v_mul_f32_e32 v207, v215, v207
	v_fmac_f32_e32 v20, v148, v200
	v_fmac_f32_e32 v21, v149, v201
	v_fmac_f32_e32 v22, v150, v202
	v_fmac_f32_e32 v23, v151, v203
	v_fmac_f32_e32 v20, v180, v204
	v_fmac_f32_e32 v21, v181, v205
	v_fmac_f32_e32 v22, v182, v206
	v_fmac_f32_e32 v23, v183, v207
	global_store_dwordx4 v193, v[20:23], s[18:19] offset:1024
	v_lshlrev_b32_e32 v200, 16, v76
	v_and_b32_e32 v201, 0xffff0000, v76
	v_lshlrev_b32_e32 v202, 16, v77
	v_and_b32_e32 v203, 0xffff0000, v77
	v_lshlrev_b32_e32 v204, 16, v108
	v_and_b32_e32 v205, 0xffff0000, v108
	v_lshlrev_b32_e32 v206, 16, v109
	v_and_b32_e32 v207, 0xffff0000, v109
	v_mul_f32_e32 v200, v214, v200
	v_mul_f32_e32 v201, v214, v201
	v_mul_f32_e32 v202, v214, v202
	v_mul_f32_e32 v203, v214, v203
	v_mul_f32_e32 v204, v215, v204
	v_mul_f32_e32 v205, v215, v205
	v_mul_f32_e32 v206, v215, v206
	v_mul_f32_e32 v207, v215, v207
	v_fmac_f32_e32 v24, v152, v200
	v_fmac_f32_e32 v25, v153, v201
	v_fmac_f32_e32 v26, v154, v202
	v_fmac_f32_e32 v27, v155, v203
	v_fmac_f32_e32 v24, v184, v204
	v_fmac_f32_e32 v25, v185, v205
	v_fmac_f32_e32 v26, v186, v206
	v_fmac_f32_e32 v27, v187, v207
	global_store_dwordx4 v193, v[24:27], s[18:19] offset:2048
	v_lshlrev_b32_e32 v200, 16, v78
	v_and_b32_e32 v201, 0xffff0000, v78
	v_lshlrev_b32_e32 v202, 16, v79
	v_and_b32_e32 v203, 0xffff0000, v79
	v_lshlrev_b32_e32 v204, 16, v110
	v_and_b32_e32 v205, 0xffff0000, v110
	v_lshlrev_b32_e32 v206, 16, v111
	v_and_b32_e32 v207, 0xffff0000, v111
	v_mul_f32_e32 v200, v214, v200
	v_mul_f32_e32 v201, v214, v201
	v_mul_f32_e32 v202, v214, v202
	v_mul_f32_e32 v203, v214, v203
	v_mul_f32_e32 v204, v215, v204
	v_mul_f32_e32 v205, v215, v205
	v_mul_f32_e32 v206, v215, v206
	v_mul_f32_e32 v207, v215, v207
	v_fmac_f32_e32 v28, v156, v200
	v_fmac_f32_e32 v29, v157, v201
	v_fmac_f32_e32 v30, v158, v202
	v_fmac_f32_e32 v31, v159, v203
	v_fmac_f32_e32 v28, v188, v204
	v_fmac_f32_e32 v29, v189, v205
	v_fmac_f32_e32 v30, v190, v206
	v_fmac_f32_e32 v31, v191, v207
	global_store_dwordx4 v193, v[28:31], s[18:19] offset:3072
	s_add_u32 s18, s18, 0x2000
	s_addc_u32 s19, s19, 0
	global_load_dwordx4 v[0:3], v192, s[14:15] offset:0 nt
	global_load_dwordx4 v[4:7], v192, s[14:15] offset:1024 nt
	global_load_dwordx4 v[8:11], v192, s[14:15] offset:2048 nt
	global_load_dwordx4 v[12:15], v192, s[14:15] offset:3072 nt
	global_load_dwordx4 v[16:19], v193, s[14:15] offset:0 nt
	global_load_dwordx4 v[20:23], v193, s[14:15] offset:1024 nt
	global_load_dwordx4 v[24:27], v193, s[14:15] offset:2048 nt
	global_load_dwordx4 v[28:31], v193, s[14:15] offset:3072 nt
	global_load_dwordx2 v[64:65], v194, s[16:17] offset:0
	global_load_dwordx2 v[66:67], v194, s[16:17] offset:512
	global_load_dwordx2 v[68:69], v194, s[16:17] offset:1024
	global_load_dwordx2 v[70:71], v194, s[16:17] offset:1536
	global_load_dwordx2 v[72:73], v194, s[16:17] offset:2048
	global_load_dwordx2 v[74:75], v194, s[16:17] offset:2560
	global_load_dwordx2 v[76:77], v194, s[16:17] offset:3072
	global_load_dwordx2 v[78:79], v194, s[16:17] offset:3584
	global_load_dwordx2 v[96:97], v194, s[22:23] offset:0
	global_load_dwordx2 v[98:99], v194, s[22:23] offset:512
	global_load_dwordx2 v[100:101], v194, s[22:23] offset:1024
	global_load_dwordx2 v[102:103], v194, s[22:23] offset:1536
	global_load_dwordx2 v[104:105], v194, s[22:23] offset:2048
	global_load_dwordx2 v[106:107], v194, s[22:23] offset:2560
	global_load_dwordx2 v[108:109], v194, s[22:23] offset:3072
	global_load_dwordx2 v[110:111], v194, s[22:23] offset:3584
	s_add_u32 s14, s14, 0x2000
	s_addc_u32 s15, s15, 0
	s_add_u32 s16, s16, 0x1000
	s_addc_u32 s17, s17, 0
	s_add_u32 s22, s22, 0x1000
	s_addc_u32 s23, s23, 0
	s_waitcnt vmcnt(32)
; __device__ __forceinline__ float bf_lo(unsigned w) { return __uint_as_float(w << 16); }
; __device__ __forceinline__ float bf_hi(unsigned w) { return __uint_as_float(w & 0xffff0000u); }
; __global__ void __launch_bounds__(NWAVES * 64, 2) mk_fwd(Args args) {
;     ...
;                 float sy = 0.f;
; #pragma unroll
;                 for (int j = 0; j < 8; ++j) { const float a = bf_lo(yw[q][j].x), b = bf_hi(yw[q][j].x), c2 = bf_lo(yw[q][j].y), d = bf_hi(yw[q][j].y); sy += (a * a + b * b) + (c2 * c2 + d * d); }
;                 const float rsy = __builtin_amdgcn_rsqf(wave_sum(sy) * (1.f / DM) + EPS);
	v_lshlrev_b32_e32 v200, 16, v80
	v_and_b32_e32 v201, 0xffff0000, v80
	v_lshlrev_b32_e32 v202, 16, v81
	v_and_b32_e32 v203, 0xffff0000, v81
	v_mul_f32_e32 v208, v200, v200
	v_mul_f32_e32 v209, v201, v201
	v_fmac_f32_e32 v208, v202, v202
	v_fmac_f32_e32 v209, v203, v203
	v_lshlrev_b32_e32 v204, 16, v112
	v_and_b32_e32 v205, 0xffff0000, v112
	v_lshlrev_b32_e32 v206, 16, v113
	v_and_b32_e32 v207, 0xffff0000, v113
	v_mul_f32_e32 v210, v204, v204
	v_mul_f32_e32 v211, v205, v205
	v_fmac_f32_e32 v210, v206, v206
	v_fmac_f32_e32 v211, v207, v207
	v_lshlrev_b32_e32 v200, 16, v82
	v_and_b32_e32 v201, 0xffff0000, v82
	v_lshlrev_b32_e32 v202, 16, v83
	v_and_b32_e32 v203, 0xffff0000, v83
	v_fmac_f32_e32 v208, v200, v200
	v_fmac_f32_e32 v209, v201, v201
	v_fmac_f32_e32 v208, v202, v202
	v_fmac_f32_e32 v209, v203, v203
	v_lshlrev_b32_e32 v204, 16, v114
	v_and_b32_e32 v205, 0xffff0000, v114
	v_lshlrev_b32_e32 v206, 16, v115
	v_and_b32_e32 v207, 0xffff0000, v115
	v_fmac_f32_e32 v210, v204, v204
	v_fmac_f32_e32 v211, v205, v205
	v_fmac_f32_e32 v210, v206, v206
	v_fmac_f32_e32 v211, v207, v207
	v_lshlrev_b32_e32 v200, 16, v84
	v_and_b32_e32 v201, 0xffff0000, v84
	v_lshlrev_b32_e32 v202, 16, v85
	v_and_b32_e32 v203, 0xffff0000, v85
	v_fmac_f32_e32 v208, v200, v200
	v_fmac_f32_e32 v209, v201, v201
	v_fmac_f32_e32 v208, v202, v202
	v_fmac_f32_e32 v209, v203, v203
	v_lshlrev_b32_e32 v204, 16, v116
	v_and_b32_e32 v205, 0xffff0000, v116
	v_lshlrev_b32_e32 v206, 16, v117
	v_and_b32_e32 v207, 0xffff0000, v117
	v_fmac_f32_e32 v210, v204, v204
	v_fmac_f32_e32 v211, v205, v205
	v_fmac_f32_e32 v210, v206, v206
	v_fmac_f32_e32 v211, v207, v207
	v_lshlrev_b32_e32 v200, 16, v86
	v_and_b32_e32 v201, 0xffff0000, v86
	v_lshlrev_b32_e32 v202, 16, v87
	v_and_b32_e32 v203, 0xffff0000, v87
	v_fmac_f32_e32 v208, v200, v200
	v_fmac_f32_e32 v209, v201, v201
	v_fmac_f32_e32 v208, v202, v202
	v_fmac_f32_e32 v209, v203, v203
	v_lshlrev_b32_e32 v204, 16, v118
	v_and_b32_e32 v205, 0xffff0000, v118
	v_lshlrev_b32_e32 v206, 16, v119
	v_and_b32_e32 v207, 0xffff0000, v119
	v_fmac_f32_e32 v210, v204, v204
	v_fmac_f32_e32 v211, v205, v205
	v_fmac_f32_e32 v210, v206, v206
	v_fmac_f32_e32 v211, v207, v207
	v_lshlrev_b32_e32 v200, 16, v88
	v_and_b32_e32 v201, 0xffff0000, v88
	v_lshlrev_b32_e32 v202, 16, v89
	v_and_b32_e32 v203, 0xffff0000, v89
	v_fmac_f32_e32 v208, v200, v200
	v_fmac_f32_e32 v209, v201, v201
	v_fmac_f32_e32 v208, v202, v202
	v_fmac_f32_e32 v209, v203, v203
	v_lshlrev_b32_e32 v204, 16, v120
	v_and_b32_e32 v205, 0xffff0000, v120
	v_lshlrev_b32_e32 v206, 16, v121
	v_and_b32_e32 v207, 0xffff0000, v121
	v_fmac_f32_e32 v210, v204, v204
	v_fmac_f32_e32 v211, v205, v205
	v_fmac_f32_e32 v210, v206, v206
	v_fmac_f32_e32 v211, v207, v207
	v_lshlrev_b32_e32 v200, 16, v90
	v_and_b32_e32 v201, 0xffff0000, v90
	v_lshlrev_b32_e32 v202, 16, v91
	v_and_b32_e32 v203, 0xffff0000, v91
	v_fmac_f32_e32 v208, v200, v200
	v_fmac_f32_e32 v209, v201, v201
	v_fmac_f32_e32 v208, v202, v202
	v_fmac_f32_e32 v209, v203, v203
	v_lshlrev_b32_e32 v204, 16, v122
	v_and_b32_e32 v205, 0xffff0000, v122
	v_lshlrev_b32_e32 v206, 16, v123
	v_and_b32_e32 v207, 0xffff0000, v123
	v_fmac_f32_e32 v210, v204, v204
	v_fmac_f32_e32 v211, v205, v205
	v_fmac_f32_e32 v210, v206, v206
	v_fmac_f32_e32 v211, v207, v207
	v_lshlrev_b32_e32 v200, 16, v92
	v_and_b32_e32 v201, 0xffff0000, v92
	v_lshlrev_b32_e32 v202, 16, v93
	v_and_b32_e32 v203, 0xffff0000, v93
	v_fmac_f32_e32 v208, v200, v200
	v_fmac_f32_e32 v209, v201, v201
	v_fmac_f32_e32 v208, v202, v202
	v_fmac_f32_e32 v209, v203, v203
	v_lshlrev_b32_e32 v204, 16, v124
	v_and_b32_e32 v205, 0xffff0000, v124
	v_lshlrev_b32_e32 v206, 16, v125
	v_and_b32_e32 v207, 0xffff0000, v125
	v_fmac_f32_e32 v210, v204, v204
	v_fmac_f32_e32 v211, v205, v205
	v_fmac_f32_e32 v210, v206, v206
	v_fmac_f32_e32 v211, v207, v207
	v_lshlrev_b32_e32 v200, 16, v94
	v_and_b32_e32 v201, 0xffff0000, v94
	v_lshlrev_b32_e32 v202, 16, v95
	v_and_b32_e32 v203, 0xffff0000, v95
	v_fmac_f32_e32 v208, v200, v200
	v_fmac_f32_e32 v209, v201, v201
	v_fmac_f32_e32 v208, v202, v202
	v_fmac_f32_e32 v209, v203, v203
	v_lshlrev_b32_e32 v204, 16, v126
	v_and_b32_e32 v205, 0xffff0000, v126
	v_lshlrev_b32_e32 v206, 16, v127
	v_and_b32_e32 v207, 0xffff0000, v127
	v_fmac_f32_e32 v210, v204, v204
	v_fmac_f32_e32 v211, v205, v205
	v_fmac_f32_e32 v210, v206, v206
	v_fmac_f32_e32 v211, v207, v207
	v_add_f32_e32 v208, v208, v209
	v_add_f32_e32 v210, v210, v211
	s_nop 0
	v_add_f32_dpp v212, v208, v208 quad_perm:[1,0,3,2] row_mask:0xf bank_mask:0xf
	v_add_f32_dpp v213, v210, v210 quad_perm:[1,0,3,2] row_mask:0xf bank_mask:0xf
	s_nop 0
	v_add_f32_dpp v212, v212, v212 quad_perm:[2,3,0,1] row_mask:0xf bank_mask:0xf
	v_add_f32_dpp v213, v213, v213 quad_perm:[2,3,0,1] row_mask:0xf bank_mask:0xf
	s_nop 0
	v_add_f32_dpp v212, v212, v212 row_half_mirror row_mask:0xf bank_mask:0xf
	v_add_f32_dpp v213, v213, v213 row_half_mirror row_mask:0xf bank_mask:0xf
	s_nop 0
	v_add_f32_dpp v212, v212, v212 row_mirror row_mask:0xf bank_mask:0xf
	v_add_f32_dpp v213, v213, v213 row_mirror row_mask:0xf bank_mask:0xf
	s_nop 0
	v_readlane_b32 s4, v212, 0
	v_readlane_b32 s5, v212, 16
	v_readlane_b32 s6, v212, 32
	v_readlane_b32 s7, v212, 48
	v_readlane_b32 s24, v213, 0
	v_readlane_b32 s25, v213, 16
	v_readlane_b32 s26, v213, 32
	v_readlane_b32 s27, v213, 48
	s_nop 1
	v_mov_b32_e32 v214, s4
	v_mov_b32_e32 v215, s24
	v_add_f32_e32 v214, s5, v214
	v_add_f32_e32 v215, s25, v215
	v_add_f32_e32 v214, s6, v214
	v_add_f32_e32 v215, s26, v215
	v_add_f32_e32 v214, s7, v214
	v_add_f32_e32 v215, s27, v215
	v_fmamk_f32 v214, v214, 0x3a000000, v195
	v_fmamk_f32 v215, v215, 0x3a000000, v195
; __device__ __forceinline__ float bf_lo(unsigned w) { return __uint_as_float(w << 16); }
; __device__ __forceinline__ float bf_hi(unsigned w) { return __uint_as_float(w & 0xffff0000u); }
; __global__ void __launch_bounds__(NWAVES * 64, 2) mk_fwd(Args args) {
;     ...
;                 const float rsy = __builtin_amdgcn_rsqf(wave_sum(sy) * (1.f / DM) + EPS);
; #pragma unroll
;                 for (int j = 0; j < 8; ++j) { const int col = 4 * F.lane + 256 * j;
;                     const f32x4 y4 = (f32x4){bf_lo(yw[q][j].x), bf_hi(yw[q][j].x), bf_lo(yw[q][j].y), bf_hi(yw[q][j].y)};
;                     *(f32x4*)(args.out + (size_t)row * DM + col) = v[q][j] + PA[j] * (y4 * rsy); }
	v_rsq_f32_e32 v214, v214
	v_rsq_f32_e32 v215, v215
	s_nop 0
	v_lshlrev_b32_e32 v200, 16, v80
	v_and_b32_e32 v201, 0xffff0000, v80
	v_lshlrev_b32_e32 v202, 16, v81
	v_and_b32_e32 v203, 0xffff0000, v81
	v_lshlrev_b32_e32 v204, 16, v112
	v_and_b32_e32 v205, 0xffff0000, v112
	v_lshlrev_b32_e32 v206, 16, v113
	v_and_b32_e32 v207, 0xffff0000, v113
	v_mul_f32_e32 v200, v214, v200
	v_mul_f32_e32 v201, v214, v201
	v_mul_f32_e32 v202, v214, v202
	v_mul_f32_e32 v203, v214, v203
	v_mul_f32_e32 v204, v215, v204
	v_mul_f32_e32 v205, v215, v205
	v_mul_f32_e32 v206, v215, v206
	v_mul_f32_e32 v207, v215, v207
	v_fmac_f32_e32 v32, v128, v200
	v_fmac_f32_e32 v33, v129, v201
	v_fmac_f32_e32 v34, v130, v202
	v_fmac_f32_e32 v35, v131, v203
	v_fmac_f32_e32 v32, v160, v204
	v_fmac_f32_e32 v33, v161, v205
	v_fmac_f32_e32 v34, v162, v206
	v_fmac_f32_e32 v35, v163, v207
	global_store_dwordx4 v192, v[32:35], s[18:19] offset:0
	v_lshlrev_b32_e32 v200, 16, v82
	v_and_b32_e32 v201, 0xffff0000, v82
	v_lshlrev_b32_e32 v202, 16, v83
	v_and_b32_e32 v203, 0xffff0000, v83
	v_lshlrev_b32_e32 v204, 16, v114
	v_and_b32_e32 v205, 0xffff0000, v114
	v_lshlrev_b32_e32 v206, 16, v115
	v_and_b32_e32 v207, 0xffff0000, v115
	v_mul_f32_e32 v200, v214, v200
	v_mul_f32_e32 v201, v214, v201
	v_mul_f32_e32 v202, v214, v202
	v_mul_f32_e32 v203, v214, v203
	v_mul_f32_e32 v204, v215, v204
	v_mul_f32_e32 v205, v215, v205
	v_mul_f32_e32 v206, v215, v206
	v_mul_f32_e32 v207, v215, v207
	v_fmac_f32_e32 v36, v132, v200
	v_fmac_f32_e32 v37, v133, v201
	v_fmac_f32_e32 v38, v134, v202
	v_fmac_f32_e32 v39, v135, v203
	v_fmac_f32_e32 v36, v164, v204
	v_fmac_f32_e32 v37, v165, v205
	v_fmac_f32_e32 v38, v166, v206
	v_fmac_f32_e32 v39, v167, v207
	global_store_dwordx4 v192, v[36:39], s[18:19] offset:1024
	v_lshlrev_b32_e32 v200, 16, v84
	v_and_b32_e32 v201, 0xffff0000, v84
	v_lshlrev_b32_e32 v202, 16, v85
	v_and_b32_e32 v203, 0xffff0000, v85
	v_lshlrev_b32_e32 v204, 16, v116
	v_and_b32_e32 v205, 0xffff0000, v116
	v_lshlrev_b32_e32 v206, 16, v117
	v_and_b32_e32 v207, 0xffff0000, v117
	v_mul_f32_e32 v200, v214, v200
	v_mul_f32_e32 v201, v214, v201
	v_mul_f32_e32 v202, v214, v202
	v_mul_f32_e32 v203, v214, v203
	v_mul_f32_e32 v204, v215, v204
	v_mul_f32_e32 v205, v215, v205
	v_mul_f32_e32 v206, v215, v206
	v_mul_f32_e32 v207, v215, v207
	v_fmac_f32_e32 v40, v136, v200
	v_fmac_f32_e32 v41, v137, v201
	v_fmac_f32_e32 v42, v138, v202
	v_fmac_f32_e32 v43, v139, v203
	v_fmac_f32_e32 v40, v168, v204
	v_fmac_f32_e32 v41, v169, v205
	v_fmac_f32_e32 v42, v170, v206
	v_fmac_f32_e32 v43, v171, v207
	global_store_dwordx4 v192, v[40:43], s[18:19] offset:2048
	v_lshlrev_b32_e32 v200, 16, v86
	v_and_b32_e32 v201, 0xffff0000, v86
	v_lshlrev_b32_e32 v202, 16, v87
	v_and_b32_e32 v203, 0xffff0000, v87
	v_lshlrev_b32_e32 v204, 16, v118
	v_and_b32_e32 v205, 0xffff0000, v118
	v_lshlrev_b32_e32 v206, 16, v119
	v_and_b32_e32 v207, 0xffff0000, v119
	v_mul_f32_e32 v200, v214, v200
	v_mul_f32_e32 v201, v214, v201
	v_mul_f32_e32 v202, v214, v202
	v_mul_f32_e32 v203, v214, v203
	v_mul_f32_e32 v204, v215, v204
	v_mul_f32_e32 v205, v215, v205
	v_mul_f32_e32 v206, v215, v206
	v_mul_f32_e32 v207, v215, v207
	v_fmac_f32_e32 v44, v140, v200
	v_fmac_f32_e32 v45, v141, v201
	v_fmac_f32_e32 v46, v142, v202
	v_fmac_f32_e32 v47, v143, v203
	v_fmac_f32_e32 v44, v172, v204
	v_fmac_f32_e32 v45, v173, v205
	v_fmac_f32_e32 v46, v174, v206
	v_fmac_f32_e32 v47, v175, v207
	global_store_dwordx4 v192, v[44:47], s[18:19] offset:3072
	v_lshlrev_b32_e32 v200, 16, v88
	v_and_b32_e32 v201, 0xffff0000, v88
	v_lshlrev_b32_e32 v202, 16, v89
	v_and_b32_e32 v203, 0xffff0000, v89
	v_lshlrev_b32_e32 v204, 16, v120
	v_and_b32_e32 v205, 0xffff0000, v120
	v_lshlrev_b32_e32 v206, 16, v121
	v_and_b32_e32 v207, 0xffff0000, v121
	v_mul_f32_e32 v200, v214, v200
	v_mul_f32_e32 v201, v214, v201
	v_mul_f32_e32 v202, v214, v202
	v_mul_f32_e32 v203, v214, v203
	v_mul_f32_e32 v204, v215, v204
	v_mul_f32_e32 v205, v215, v205
	v_mul_f32_e32 v206, v215, v206
	v_mul_f32_e32 v207, v215, v207
	v_fmac_f32_e32 v48, v144, v200
	v_fmac_f32_e32 v49, v145, v201
	v_fmac_f32_e32 v50, v146, v202
	v_fmac_f32_e32 v51, v147, v203
	v_fmac_f32_e32 v48, v176, v204
	v_fmac_f32_e32 v49, v177, v205
	v_fmac_f32_e32 v50, v178, v206
	v_fmac_f32_e32 v51, v179, v207
	global_store_dwordx4 v193, v[48:51], s[18:19] offset:0
	v_lshlrev_b32_e32 v200, 16, v90
	v_and_b32_e32 v201, 0xffff0000, v90
	v_lshlrev_b32_e32 v202, 16, v91
	v_and_b32_e32 v203, 0xffff0000, v91
	v_lshlrev_b32_e32 v204, 16, v122
	v_and_b32_e32 v205, 0xffff0000, v122
	v_lshlrev_b32_e32 v206, 16, v123
	v_and_b32_e32 v207, 0xffff0000, v123
	v_mul_f32_e32 v200, v214, v200
	v_mul_f32_e32 v201, v214, v201
	v_mul_f32_e32 v202, v214, v202
	v_mul_f32_e32 v203, v214, v203
	v_mul_f32_e32 v204, v215, v204
	v_mul_f32_e32 v205, v215, v205
	v_mul_f32_e32 v206, v215, v206
	v_mul_f32_e32 v207, v215, v207
	v_fmac_f32_e32 v52, v148, v200
	v_fmac_f32_e32 v53, v149, v201
	v_fmac_f32_e32 v54, v150, v202
	v_fmac_f32_e32 v55, v151, v203
	v_fmac_f32_e32 v52, v180, v204
	v_fmac_f32_e32 v53, v181, v205
	v_fmac_f32_e32 v54, v182, v206
	v_fmac_f32_e32 v55, v183, v207
	global_store_dwordx4 v193, v[52:55], s[18:19] offset:1024
	v_lshlrev_b32_e32 v200, 16, v92
	v_and_b32_e32 v201, 0xffff0000, v92
	v_lshlrev_b32_e32 v202, 16, v93
	v_and_b32_e32 v203, 0xffff0000, v93
	v_lshlrev_b32_e32 v204, 16, v124
	v_and_b32_e32 v205, 0xffff0000, v124
	v_lshlrev_b32_e32 v206, 16, v125
	v_and_b32_e32 v207, 0xffff0000, v125
	v_mul_f32_e32 v200, v214, v200
	v_mul_f32_e32 v201, v214, v201
	v_mul_f32_e32 v202, v214, v202
	v_mul_f32_e32 v203, v214, v203
	v_mul_f32_e32 v204, v215, v204
; __device__ __forceinline__ float bf_lo(unsigned w) { return __uint_as_float(w << 16); }
; __device__ __forceinline__ float bf_hi(unsigned w) { return __uint_as_float(w & 0xffff0000u); }
; __global__ void __launch_bounds__(NWAVES * 64, 2) mk_fwd(Args args) {
;     ...
;             for (int q = 0; q < 2; ++q) { const int row = row0 + q; load_row_f32(args.out + (size_t)row * DM, F.lane, v[q]);
;                 const bf16_t* yr = Y + (size_t)row * DM;
; #pragma unroll
;                 for (int j = 0; j < 8; ++j) yw[q][j] = *(const u32x2*)(yr + 4 * F.lane + 256 * j); }
; #pragma unroll
;             for (int q = 0; q < 2; ++q) { const int row = row0 + q; const int r = row / SEQ;
;                 if (r != rcur) { const float* m1 = mod + (size_t)(9 + r) * 6144; rcur = r;
; #pragma unroll
;                     for (int j = 0; j < 8; ++j) { const int col = 4 * F.lane + 256 * j; PA[j] = *(const f32x4*)(m1 + 2 * DM + col) * *(const f32x4*)(post_norm + DM + col); } }
;                 float sy = 0.f;
; #pragma unroll
;                 for (int j = 0; j < 8; ++j) { const float a = bf_lo(yw[q][j].x), b = bf_hi(yw[q][j].x), c2 = bf_lo(yw[q][j].y), d = bf_hi(yw[q][j].y); sy += (a * a + b * b) + (c2 * c2 + d * d); }
;                 const float rsy = __builtin_amdgcn_rsqf(wave_sum(sy) * (1.f / DM) + EPS);
; #pragma unroll
;                 for (int j = 0; j < 8; ++j) { const int col = 4 * F.lane + 256 * j;
;                     const f32x4 y4 = (f32x4){bf_lo(yw[q][j].x), bf_hi(yw[q][j].x), bf_lo(yw[q][j].y), bf_hi(yw[q][j].y)};
;                     *(f32x4*)(args.out + (size_t)row * DM + col) = v[q][j] + PA[j] * (y4 * rsy); }
	v_mul_f32_e32 v205, v215, v205
	v_mul_f32_e32 v206, v215, v206
	v_mul_f32_e32 v207, v215, v207
	v_fmac_f32_e32 v56, v152, v200
	v_fmac_f32_e32 v57, v153, v201
	v_fmac_f32_e32 v58, v154, v202
	v_fmac_f32_e32 v59, v155, v203
	v_fmac_f32_e32 v56, v184, v204
	v_fmac_f32_e32 v57, v185, v205
	v_fmac_f32_e32 v58, v186, v206
	v_fmac_f32_e32 v59, v187, v207
	global_store_dwordx4 v193, v[56:59], s[18:19] offset:2048
	v_lshlrev_b32_e32 v200, 16, v94
	v_and_b32_e32 v201, 0xffff0000, v94
	v_lshlrev_b32_e32 v202, 16, v95
	v_and_b32_e32 v203, 0xffff0000, v95
	v_lshlrev_b32_e32 v204, 16, v126
	v_and_b32_e32 v205, 0xffff0000, v126
	v_lshlrev_b32_e32 v206, 16, v127
	v_and_b32_e32 v207, 0xffff0000, v127
	v_mul_f32_e32 v200, v214, v200
	v_mul_f32_e32 v201, v214, v201
	v_mul_f32_e32 v202, v214, v202
	v_mul_f32_e32 v203, v214, v203
	v_mul_f32_e32 v204, v215, v204
	v_mul_f32_e32 v205, v215, v205
	v_mul_f32_e32 v206, v215, v206
	v_mul_f32_e32 v207, v215, v207
	v_fmac_f32_e32 v60, v156, v200
	v_fmac_f32_e32 v61, v157, v201
	v_fmac_f32_e32 v62, v158, v202
	v_fmac_f32_e32 v63, v159, v203
	v_fmac_f32_e32 v60, v188, v204
	v_fmac_f32_e32 v61, v189, v205
	v_fmac_f32_e32 v62, v190, v206
	v_fmac_f32_e32 v63, v191, v207
	global_store_dwordx4 v193, v[60:63], s[18:19] offset:3072
	s_add_u32 s18, s18, 0x2000
	s_addc_u32 s19, s19, 0
	global_load_dwordx4 v[32:35], v192, s[14:15] offset:0 nt
	global_load_dwordx4 v[36:39], v192, s[14:15] offset:1024 nt
	global_load_dwordx4 v[40:43], v192, s[14:15] offset:2048 nt
	global_load_dwordx4 v[44:47], v192, s[14:15] offset:3072 nt
	global_load_dwordx4 v[48:51], v193, s[14:15] offset:0 nt
	global_load_dwordx4 v[52:55], v193, s[14:15] offset:1024 nt
	global_load_dwordx4 v[56:59], v193, s[14:15] offset:2048 nt
	global_load_dwordx4 v[60:63], v193, s[14:15] offset:3072 nt
	global_load_dwordx2 v[80:81], v194, s[16:17] offset:0
	global_load_dwordx2 v[82:83], v194, s[16:17] offset:512
	global_load_dwordx2 v[84:85], v194, s[16:17] offset:1024
	global_load_dwordx2 v[86:87], v194, s[16:17] offset:1536
	global_load_dwordx2 v[88:89], v194, s[16:17] offset:2048
	global_load_dwordx2 v[90:91], v194, s[16:17] offset:2560
	global_load_dwordx2 v[92:93], v194, s[16:17] offset:3072
	global_load_dwordx2 v[94:95], v194, s[16:17] offset:3584
	global_load_dwordx2 v[112:113], v194, s[22:23] offset:0
	global_load_dwordx2 v[114:115], v194, s[22:23] offset:512
	global_load_dwordx2 v[116:117], v194, s[22:23] offset:1024
	global_load_dwordx2 v[118:119], v194, s[22:23] offset:1536
	global_load_dwordx2 v[120:121], v194, s[22:23] offset:2048
	global_load_dwordx2 v[122:123], v194, s[22:23] offset:2560
	global_load_dwordx2 v[124:125], v194, s[22:23] offset:3072
	global_load_dwordx2 v[126:127], v194, s[22:23] offset:3584
	s_add_u32 s14, s14, 0x2000
	s_addc_u32 s15, s15, 0
	s_add_u32 s16, s16, 0x1000
	s_addc_u32 s17, s17, 0
	s_add_u32 s22, s22, 0x1000
	s_addc_u32 s23, s23, 0
	s_waitcnt vmcnt(32)
	v_lshlrev_b32_e32 v200, 16, v64
	v_and_b32_e32 v201, 0xffff0000, v64
	v_lshlrev_b32_e32 v202, 16, v65
	v_and_b32_e32 v203, 0xffff0000, v65
	v_mul_f32_e32 v208, v200, v200
	v_mul_f32_e32 v209, v201, v201
	v_fmac_f32_e32 v208, v202, v202
	v_fmac_f32_e32 v209, v203, v203
	v_lshlrev_b32_e32 v204, 16, v96
	v_and_b32_e32 v205, 0xffff0000, v96
	v_lshlrev_b32_e32 v206, 16, v97
	v_and_b32_e32 v207, 0xffff0000, v97
	v_mul_f32_e32 v210, v204, v204
	v_mul_f32_e32 v211, v205, v205
	v_fmac_f32_e32 v210, v206, v206
	v_fmac_f32_e32 v211, v207, v207
	v_lshlrev_b32_e32 v200, 16, v66
	v_and_b32_e32 v201, 0xffff0000, v66
	v_lshlrev_b32_e32 v202, 16, v67
	v_and_b32_e32 v203, 0xffff0000, v67
	v_fmac_f32_e32 v208, v200, v200
	v_fmac_f32_e32 v209, v201, v201
	v_fmac_f32_e32 v208, v202, v202
	v_fmac_f32_e32 v209, v203, v203
	v_lshlrev_b32_e32 v204, 16, v98
	v_and_b32_e32 v205, 0xffff0000, v98
	v_lshlrev_b32_e32 v206, 16, v99
	v_and_b32_e32 v207, 0xffff0000, v99
	v_fmac_f32_e32 v210, v204, v204
	v_fmac_f32_e32 v211, v205, v205
	v_fmac_f32_e32 v210, v206, v206
	v_fmac_f32_e32 v211, v207, v207
	v_lshlrev_b32_e32 v200, 16, v68
	v_and_b32_e32 v201, 0xffff0000, v68
	v_lshlrev_b32_e32 v202, 16, v69
	v_and_b32_e32 v203, 0xffff0000, v69
	v_fmac_f32_e32 v208, v200, v200
	v_fmac_f32_e32 v209, v201, v201
	v_fmac_f32_e32 v208, v202, v202
	v_fmac_f32_e32 v209, v203, v203
	v_lshlrev_b32_e32 v204, 16, v100
	v_and_b32_e32 v205, 0xffff0000, v100
	v_lshlrev_b32_e32 v206, 16, v101
	v_and_b32_e32 v207, 0xffff0000, v101
	v_fmac_f32_e32 v210, v204, v204
	v_fmac_f32_e32 v211, v205, v205
	v_fmac_f32_e32 v210, v206, v206
	v_fmac_f32_e32 v211, v207, v207
	v_lshlrev_b32_e32 v200, 16, v70
	v_and_b32_e32 v201, 0xffff0000, v70
	v_lshlrev_b32_e32 v202, 16, v71
	v_and_b32_e32 v203, 0xffff0000, v71
	v_fmac_f32_e32 v208, v200, v200
	v_fmac_f32_e32 v209, v201, v201
	v_fmac_f32_e32 v208, v202, v202
	v_fmac_f32_e32 v209, v203, v203
	v_lshlrev_b32_e32 v204, 16, v102
	v_and_b32_e32 v205, 0xffff0000, v102
	v_lshlrev_b32_e32 v206, 16, v103
	v_and_b32_e32 v207, 0xffff0000, v103
	v_fmac_f32_e32 v210, v204, v204
	v_fmac_f32_e32 v211, v205, v205
	v_fmac_f32_e32 v210, v206, v206
	v_fmac_f32_e32 v211, v207, v207
	v_lshlrev_b32_e32 v200, 16, v72
	v_and_b32_e32 v201, 0xffff0000, v72
	v_lshlrev_b32_e32 v202, 16, v73
	v_and_b32_e32 v203, 0xffff0000, v73
	v_fmac_f32_e32 v208, v200, v200
	v_fmac_f32_e32 v209, v201, v201
	v_fmac_f32_e32 v208, v202, v202
	v_fmac_f32_e32 v209, v203, v203
	v_lshlrev_b32_e32 v204, 16, v104
	v_and_b32_e32 v205, 0xffff0000, v104
	v_lshlrev_b32_e32 v206, 16, v105
	v_and_b32_e32 v207, 0xffff0000, v105
	v_fmac_f32_e32 v210, v204, v204
	v_fmac_f32_e32 v211, v205, v205
	v_fmac_f32_e32 v210, v206, v206
	v_fmac_f32_e32 v211, v207, v207
; __device__ __forceinline__ float bf_lo(unsigned w) { return __uint_as_float(w << 16); }
; __device__ __forceinline__ float bf_hi(unsigned w) { return __uint_as_float(w & 0xffff0000u); }
; __global__ void __launch_bounds__(NWAVES * 64, 2) mk_fwd(Args args) {
;     ...
;                 float sy = 0.f;
; #pragma unroll
;                 for (int j = 0; j < 8; ++j) { const float a = bf_lo(yw[q][j].x), b = bf_hi(yw[q][j].x), c2 = bf_lo(yw[q][j].y), d = bf_hi(yw[q][j].y); sy += (a * a + b * b) + (c2 * c2 + d * d); }
;                 const float rsy = __builtin_amdgcn_rsqf(wave_sum(sy) * (1.f / DM) + EPS);
; #pragma unroll
;                 for (int j = 0; j < 8; ++j) { const int col = 4 * F.lane + 256 * j;
;                     const f32x4 y4 = (f32x4){bf_lo(yw[q][j].x), bf_hi(yw[q][j].x), bf_lo(yw[q][j].y), bf_hi(yw[q][j].y)};
;                     *(f32x4*)(args.out + (size_t)row * DM + col) = v[q][j] + PA[j] * (y4 * rsy); }
	v_lshlrev_b32_e32 v200, 16, v74
	v_and_b32_e32 v201, 0xffff0000, v74
	v_lshlrev_b32_e32 v202, 16, v75
	v_and_b32_e32 v203, 0xffff0000, v75
	v_fmac_f32_e32 v208, v200, v200
	v_fmac_f32_e32 v209, v201, v201
	v_fmac_f32_e32 v208, v202, v202
	v_fmac_f32_e32 v209, v203, v203
	v_lshlrev_b32_e32 v204, 16, v106
	v_and_b32_e32 v205, 0xffff0000, v106
	v_lshlrev_b32_e32 v206, 16, v107
	v_and_b32_e32 v207, 0xffff0000, v107
	v_fmac_f32_e32 v210, v204, v204
	v_fmac_f32_e32 v211, v205, v205
	v_fmac_f32_e32 v210, v206, v206
	v_fmac_f32_e32 v211, v207, v207
	v_lshlrev_b32_e32 v200, 16, v76
	v_and_b32_e32 v201, 0xffff0000, v76
	v_lshlrev_b32_e32 v202, 16, v77
	v_and_b32_e32 v203, 0xffff0000, v77
	v_fmac_f32_e32 v208, v200, v200
	v_fmac_f32_e32 v209, v201, v201
	v_fmac_f32_e32 v208, v202, v202
	v_fmac_f32_e32 v209, v203, v203
	v_lshlrev_b32_e32 v204, 16, v108
	v_and_b32_e32 v205, 0xffff0000, v108
	v_lshlrev_b32_e32 v206, 16, v109
	v_and_b32_e32 v207, 0xffff0000, v109
	v_fmac_f32_e32 v210, v204, v204
	v_fmac_f32_e32 v211, v205, v205
	v_fmac_f32_e32 v210, v206, v206
	v_fmac_f32_e32 v211, v207, v207
	v_lshlrev_b32_e32 v200, 16, v78
	v_and_b32_e32 v201, 0xffff0000, v78
	v_lshlrev_b32_e32 v202, 16, v79
	v_and_b32_e32 v203, 0xffff0000, v79
	v_fmac_f32_e32 v208, v200, v200
	v_fmac_f32_e32 v209, v201, v201
	v_fmac_f32_e32 v208, v202, v202
	v_fmac_f32_e32 v209, v203, v203
	v_lshlrev_b32_e32 v204, 16, v110
	v_and_b32_e32 v205, 0xffff0000, v110
	v_lshlrev_b32_e32 v206, 16, v111
	v_and_b32_e32 v207, 0xffff0000, v111
	v_fmac_f32_e32 v210, v204, v204
	v_fmac_f32_e32 v211, v205, v205
	v_fmac_f32_e32 v210, v206, v206
	v_fmac_f32_e32 v211, v207, v207
	v_add_f32_e32 v208, v208, v209
	v_add_f32_e32 v210, v210, v211
	s_nop 0
	v_add_f32_dpp v212, v208, v208 quad_perm:[1,0,3,2] row_mask:0xf bank_mask:0xf
	v_add_f32_dpp v213, v210, v210 quad_perm:[1,0,3,2] row_mask:0xf bank_mask:0xf
	s_nop 0
	v_add_f32_dpp v212, v212, v212 quad_perm:[2,3,0,1] row_mask:0xf bank_mask:0xf
	v_add_f32_dpp v213, v213, v213 quad_perm:[2,3,0,1] row_mask:0xf bank_mask:0xf
	s_nop 0
	v_add_f32_dpp v212, v212, v212 row_half_mirror row_mask:0xf bank_mask:0xf
	v_add_f32_dpp v213, v213, v213 row_half_mirror row_mask:0xf bank_mask:0xf
	s_nop 0
	v_add_f32_dpp v212, v212, v212 row_mirror row_mask:0xf bank_mask:0xf
	v_add_f32_dpp v213, v213, v213 row_mirror row_mask:0xf bank_mask:0xf
	s_nop 0
	v_readlane_b32 s4, v212, 0
	v_readlane_b32 s5, v212, 16
	v_readlane_b32 s6, v212, 32
	v_readlane_b32 s7, v212, 48
	v_readlane_b32 s24, v213, 0
	v_readlane_b32 s25, v213, 16
	v_readlane_b32 s26, v213, 32
	v_readlane_b32 s27, v213, 48
	s_nop 1
	v_mov_b32_e32 v214, s4
	v_mov_b32_e32 v215, s24
	v_add_f32_e32 v214, s5, v214
	v_add_f32_e32 v215, s25, v215
	v_add_f32_e32 v214, s6, v214
	v_add_f32_e32 v215, s26, v215
	v_add_f32_e32 v214, s7, v214
	v_add_f32_e32 v215, s27, v215
	v_fmamk_f32 v214, v214, 0x3a000000, v195
	v_fmamk_f32 v215, v215, 0x3a000000, v195
	v_rsq_f32_e32 v214, v214
	v_rsq_f32_e32 v215, v215
	s_nop 0
	v_lshlrev_b32_e32 v200, 16, v64
	v_and_b32_e32 v201, 0xffff0000, v64
	v_lshlrev_b32_e32 v202, 16, v65
	v_and_b32_e32 v203, 0xffff0000, v65
	v_lshlrev_b32_e32 v204, 16, v96
	v_and_b32_e32 v205, 0xffff0000, v96
	v_lshlrev_b32_e32 v206, 16, v97
	v_and_b32_e32 v207, 0xffff0000, v97
	v_mul_f32_e32 v200, v214, v200
	v_mul_f32_e32 v201, v214, v201
	v_mul_f32_e32 v202, v214, v202
	v_mul_f32_e32 v203, v214, v203
	v_mul_f32_e32 v204, v215, v204
	v_mul_f32_e32 v205, v215, v205
	v_mul_f32_e32 v206, v215, v206
	v_mul_f32_e32 v207, v215, v207
	v_fmac_f32_e32 v0, v128, v200
	v_fmac_f32_e32 v1, v129, v201
	v_fmac_f32_e32 v2, v130, v202
	v_fmac_f32_e32 v3, v131, v203
	v_fmac_f32_e32 v0, v160, v204
	v_fmac_f32_e32 v1, v161, v205
	v_fmac_f32_e32 v2, v162, v206
	v_fmac_f32_e32 v3, v163, v207
	global_store_dwordx4 v192, v[0:3], s[18:19] offset:0
	v_lshlrev_b32_e32 v200, 16, v66
	v_and_b32_e32 v201, 0xffff0000, v66
	v_lshlrev_b32_e32 v202, 16, v67
	v_and_b32_e32 v203, 0xffff0000, v67
	v_lshlrev_b32_e32 v204, 16, v98
	v_and_b32_e32 v205, 0xffff0000, v98
	v_lshlrev_b32_e32 v206, 16, v99
	v_and_b32_e32 v207, 0xffff0000, v99
	v_mul_f32_e32 v200, v214, v200
	v_mul_f32_e32 v201, v214, v201
	v_mul_f32_e32 v202, v214, v202
	v_mul_f32_e32 v203, v214, v203
	v_mul_f32_e32 v204, v215, v204
	v_mul_f32_e32 v205, v215, v205
	v_mul_f32_e32 v206, v215, v206
	v_mul_f32_e32 v207, v215, v207
	v_fmac_f32_e32 v4, v132, v200
	v_fmac_f32_e32 v5, v133, v201
	v_fmac_f32_e32 v6, v134, v202
	v_fmac_f32_e32 v7, v135, v203
	v_fmac_f32_e32 v4, v164, v204
	v_fmac_f32_e32 v5, v165, v205
	v_fmac_f32_e32 v6, v166, v206
	v_fmac_f32_e32 v7, v167, v207
	global_store_dwordx4 v192, v[4:7], s[18:19] offset:1024
	v_lshlrev_b32_e32 v200, 16, v68
	v_and_b32_e32 v201, 0xffff0000, v68
	v_lshlrev_b32_e32 v202, 16, v69
	v_and_b32_e32 v203, 0xffff0000, v69
	v_lshlrev_b32_e32 v204, 16, v100
	v_and_b32_e32 v205, 0xffff0000, v100
	v_lshlrev_b32_e32 v206, 16, v101
	v_and_b32_e32 v207, 0xffff0000, v101
	v_mul_f32_e32 v200, v214, v200
	v_mul_f32_e32 v201, v214, v201
	v_mul_f32_e32 v202, v214, v202
	v_mul_f32_e32 v203, v214, v203
	v_mul_f32_e32 v204, v215, v204
	v_mul_f32_e32 v205, v215, v205
	v_mul_f32_e32 v206, v215, v206
	v_mul_f32_e32 v207, v215, v207
	v_fmac_f32_e32 v8, v136, v200
	v_fmac_f32_e32 v9, v137, v201
	v_fmac_f32_e32 v10, v138, v202
	v_fmac_f32_e32 v11, v139, v203
	v_fmac_f32_e32 v8, v168, v204
	v_fmac_f32_e32 v9, v169, v205
	v_fmac_f32_e32 v10, v170, v206
	v_fmac_f32_e32 v11, v171, v207
	global_store_dwordx4 v192, v[8:11], s[18:19] offset:2048
	v_lshlrev_b32_e32 v200, 16, v70
	v_and_b32_e32 v201, 0xffff0000, v70
	v_lshlrev_b32_e32 v202, 16, v71
	v_and_b32_e32 v203, 0xffff0000, v71
; __device__ __forceinline__ float bf_lo(unsigned w) { return __uint_as_float(w << 16); }
; __device__ __forceinline__ float bf_hi(unsigned w) { return __uint_as_float(w & 0xffff0000u); }
; __global__ void __launch_bounds__(NWAVES * 64, 2) mk_fwd(Args args) {
;     ...
;                 float sy = 0.f;
; #pragma unroll
;                 for (int j = 0; j < 8; ++j) { const float a = bf_lo(yw[q][j].x), b = bf_hi(yw[q][j].x), c2 = bf_lo(yw[q][j].y), d = bf_hi(yw[q][j].y); sy += (a * a + b * b) + (c2 * c2 + d * d); }
;                 const float rsy = __builtin_amdgcn_rsqf(wave_sum(sy) * (1.f / DM) + EPS);
; #pragma unroll
;                 for (int j = 0; j < 8; ++j) { const int col = 4 * F.lane + 256 * j;
;                     const f32x4 y4 = (f32x4){bf_lo(yw[q][j].x), bf_hi(yw[q][j].x), bf_lo(yw[q][j].y), bf_hi(yw[q][j].y)};
;                     *(f32x4*)(args.out + (size_t)row * DM + col) = v[q][j] + PA[j] * (y4 * rsy); }
	v_lshlrev_b32_e32 v204, 16, v102
	v_and_b32_e32 v205, 0xffff0000, v102
	v_lshlrev_b32_e32 v206, 16, v103
	v_and_b32_e32 v207, 0xffff0000, v103
	v_mul_f32_e32 v200, v214, v200
	v_mul_f32_e32 v201, v214, v201
	v_mul_f32_e32 v202, v214, v202
	v_mul_f32_e32 v203, v214, v203
	v_mul_f32_e32 v204, v215, v204
	v_mul_f32_e32 v205, v215, v205
	v_mul_f32_e32 v206, v215, v206
	v_mul_f32_e32 v207, v215, v207
	v_fmac_f32_e32 v12, v140, v200
	v_fmac_f32_e32 v13, v141, v201
	v_fmac_f32_e32 v14, v142, v202
	v_fmac_f32_e32 v15, v143, v203
	v_fmac_f32_e32 v12, v172, v204
	v_fmac_f32_e32 v13, v173, v205
	v_fmac_f32_e32 v14, v174, v206
	v_fmac_f32_e32 v15, v175, v207
	global_store_dwordx4 v192, v[12:15], s[18:19] offset:3072
	v_lshlrev_b32_e32 v200, 16, v72
	v_and_b32_e32 v201, 0xffff0000, v72
	v_lshlrev_b32_e32 v202, 16, v73
	v_and_b32_e32 v203, 0xffff0000, v73
	v_lshlrev_b32_e32 v204, 16, v104
	v_and_b32_e32 v205, 0xffff0000, v104
	v_lshlrev_b32_e32 v206, 16, v105
	v_and_b32_e32 v207, 0xffff0000, v105
	v_mul_f32_e32 v200, v214, v200
	v_mul_f32_e32 v201, v214, v201
	v_mul_f32_e32 v202, v214, v202
	v_mul_f32_e32 v203, v214, v203
	v_mul_f32_e32 v204, v215, v204
	v_mul_f32_e32 v205, v215, v205
	v_mul_f32_e32 v206, v215, v206
	v_mul_f32_e32 v207, v215, v207
	v_fmac_f32_e32 v16, v144, v200
	v_fmac_f32_e32 v17, v145, v201
	v_fmac_f32_e32 v18, v146, v202
	v_fmac_f32_e32 v19, v147, v203
	v_fmac_f32_e32 v16, v176, v204
	v_fmac_f32_e32 v17, v177, v205
	v_fmac_f32_e32 v18, v178, v206
	v_fmac_f32_e32 v19, v179, v207
	global_store_dwordx4 v193, v[16:19], s[18:19] offset:0
	v_lshlrev_b32_e32 v200, 16, v74
	v_and_b32_e32 v201, 0xffff0000, v74
	v_lshlrev_b32_e32 v202, 16, v75
	v_and_b32_e32 v203, 0xffff0000, v75
	v_lshlrev_b32_e32 v204, 16, v106
	v_and_b32_e32 v205, 0xffff0000, v106
	v_lshlrev_b32_e32 v206, 16, v107
	v_and_b32_e32 v207, 0xffff0000, v107
	v_mul_f32_e32 v200, v214, v200
	v_mul_f32_e32 v201, v214, v201
	v_mul_f32_e32 v202, v214, v202
	v_mul_f32_e32 v203, v214, v203
	v_mul_f32_e32 v204, v215, v204
	v_mul_f32_e32 v205, v215, v205
	v_mul_f32_e32 v206, v215, v206
	v_mul_f32_e32 v207, v215, v207
	v_fmac_f32_e32 v20, v148, v200
	v_fmac_f32_e32 v21, v149, v201
	v_fmac_f32_e32 v22, v150, v202
	v_fmac_f32_e32 v23, v151, v203
	v_fmac_f32_e32 v20, v180, v204
	v_fmac_f32_e32 v21, v181, v205
	v_fmac_f32_e32 v22, v182, v206
	v_fmac_f32_e32 v23, v183, v207
	global_store_dwordx4 v193, v[20:23], s[18:19] offset:1024
	v_lshlrev_b32_e32 v200, 16, v76
	v_and_b32_e32 v201, 0xffff0000, v76
	v_lshlrev_b32_e32 v202, 16, v77
	v_and_b32_e32 v203, 0xffff0000, v77
	v_lshlrev_b32_e32 v204, 16, v108
	v_and_b32_e32 v205, 0xffff0000, v108
	v_lshlrev_b32_e32 v206, 16, v109
	v_and_b32_e32 v207, 0xffff0000, v109
	v_mul_f32_e32 v200, v214, v200
	v_mul_f32_e32 v201, v214, v201
	v_mul_f32_e32 v202, v214, v202
	v_mul_f32_e32 v203, v214, v203
	v_mul_f32_e32 v204, v215, v204
	v_mul_f32_e32 v205, v215, v205
	v_mul_f32_e32 v206, v215, v206
	v_mul_f32_e32 v207, v215, v207
	v_fmac_f32_e32 v24, v152, v200
	v_fmac_f32_e32 v25, v153, v201
	v_fmac_f32_e32 v26, v154, v202
	v_fmac_f32_e32 v27, v155, v203
	v_fmac_f32_e32 v24, v184, v204
	v_fmac_f32_e32 v25, v185, v205
	v_fmac_f32_e32 v26, v186, v206
	v_fmac_f32_e32 v27, v187, v207
	global_store_dwordx4 v193, v[24:27], s[18:19] offset:2048
	v_lshlrev_b32_e32 v200, 16, v78
	v_and_b32_e32 v201, 0xffff0000, v78
	v_lshlrev_b32_e32 v202, 16, v79
	v_and_b32_e32 v203, 0xffff0000, v79
	v_lshlrev_b32_e32 v204, 16, v110
	v_and_b32_e32 v205, 0xffff0000, v110
	v_lshlrev_b32_e32 v206, 16, v111
	v_and_b32_e32 v207, 0xffff0000, v111
	v_mul_f32_e32 v200, v214, v200
	v_mul_f32_e32 v201, v214, v201
	v_mul_f32_e32 v202, v214, v202
	v_mul_f32_e32 v203, v214, v203
	v_mul_f32_e32 v204, v215, v204
	v_mul_f32_e32 v205, v215, v205
	v_mul_f32_e32 v206, v215, v206
	v_mul_f32_e32 v207, v215, v207
	v_fmac_f32_e32 v28, v156, v200
	v_fmac_f32_e32 v29, v157, v201
	v_fmac_f32_e32 v30, v158, v202
	v_fmac_f32_e32 v31, v159, v203
	v_fmac_f32_e32 v28, v188, v204
	v_fmac_f32_e32 v29, v189, v205
	v_fmac_f32_e32 v30, v190, v206
	v_fmac_f32_e32 v31, v191, v207
	global_store_dwordx4 v193, v[28:31], s[18:19] offset:3072
	s_add_u32 s18, s18, 0x2000
	s_addc_u32 s19, s19, 0
	s_waitcnt vmcnt(8)
	v_lshlrev_b32_e32 v200, 16, v80
	v_and_b32_e32 v201, 0xffff0000, v80
	v_lshlrev_b32_e32 v202, 16, v81
	v_and_b32_e32 v203, 0xffff0000, v81
	v_mul_f32_e32 v208, v200, v200
	v_mul_f32_e32 v209, v201, v201
	v_fmac_f32_e32 v208, v202, v202
	v_fmac_f32_e32 v209, v203, v203
	v_lshlrev_b32_e32 v204, 16, v112
	v_and_b32_e32 v205, 0xffff0000, v112
	v_lshlrev_b32_e32 v206, 16, v113
	v_and_b32_e32 v207, 0xffff0000, v113
	v_mul_f32_e32 v210, v204, v204
	v_mul_f32_e32 v211, v205, v205
	v_fmac_f32_e32 v210, v206, v206
	v_fmac_f32_e32 v211, v207, v207
	v_lshlrev_b32_e32 v200, 16, v82
	v_and_b32_e32 v201, 0xffff0000, v82
	v_lshlrev_b32_e32 v202, 16, v83
	v_and_b32_e32 v203, 0xffff0000, v83
	v_fmac_f32_e32 v208, v200, v200
	v_fmac_f32_e32 v209, v201, v201
	v_fmac_f32_e32 v208, v202, v202
	v_fmac_f32_e32 v209, v203, v203
	v_lshlrev_b32_e32 v204, 16, v114
	v_and_b32_e32 v205, 0xffff0000, v114
	v_lshlrev_b32_e32 v206, 16, v115
	v_and_b32_e32 v207, 0xffff0000, v115
	v_fmac_f32_e32 v210, v204, v204
	v_fmac_f32_e32 v211, v205, v205
	v_fmac_f32_e32 v210, v206, v206
	v_fmac_f32_e32 v211, v207, v207
	v_lshlrev_b32_e32 v200, 16, v84
	v_and_b32_e32 v201, 0xffff0000, v84
	v_lshlrev_b32_e32 v202, 16, v85
	v_and_b32_e32 v203, 0xffff0000, v85
	v_fmac_f32_e32 v208, v200, v200
	v_fmac_f32_e32 v209, v201, v201
	v_fmac_f32_e32 v208, v202, v202
	v_fmac_f32_e32 v209, v203, v203
	v_lshlrev_b32_e32 v204, 16, v116
	v_and_b32_e32 v205, 0xffff0000, v116
; __device__ __forceinline__ float bf_lo(unsigned w) { return __uint_as_float(w << 16); }
; __device__ __forceinline__ float bf_hi(unsigned w) { return __uint_as_float(w & 0xffff0000u); }
; __global__ void __launch_bounds__(NWAVES * 64, 2) mk_fwd(Args args) {
;     ...
;                 float sy = 0.f;
; #pragma unroll
;                 for (int j = 0; j < 8; ++j) { const float a = bf_lo(yw[q][j].x), b = bf_hi(yw[q][j].x), c2 = bf_lo(yw[q][j].y), d = bf_hi(yw[q][j].y); sy += (a * a + b * b) + (c2 * c2 + d * d); }
;                 const float rsy = __builtin_amdgcn_rsqf(wave_sum(sy) * (1.f / DM) + EPS);
; #pragma unroll
;                 for (int j = 0; j < 8; ++j) { const int col = 4 * F.lane + 256 * j;
;                     const f32x4 y4 = (f32x4){bf_lo(yw[q][j].x), bf_hi(yw[q][j].x), bf_lo(yw[q][j].y), bf_hi(yw[q][j].y)};
;                     *(f32x4*)(args.out + (size_t)row * DM + col) = v[q][j] + PA[j] * (y4 * rsy); }
	v_lshlrev_b32_e32 v206, 16, v117
	v_and_b32_e32 v207, 0xffff0000, v117
	v_fmac_f32_e32 v210, v204, v204
	v_fmac_f32_e32 v211, v205, v205
	v_fmac_f32_e32 v210, v206, v206
	v_fmac_f32_e32 v211, v207, v207
	v_lshlrev_b32_e32 v200, 16, v86
	v_and_b32_e32 v201, 0xffff0000, v86
	v_lshlrev_b32_e32 v202, 16, v87
	v_and_b32_e32 v203, 0xffff0000, v87
	v_fmac_f32_e32 v208, v200, v200
	v_fmac_f32_e32 v209, v201, v201
	v_fmac_f32_e32 v208, v202, v202
	v_fmac_f32_e32 v209, v203, v203
	v_lshlrev_b32_e32 v204, 16, v118
	v_and_b32_e32 v205, 0xffff0000, v118
	v_lshlrev_b32_e32 v206, 16, v119
	v_and_b32_e32 v207, 0xffff0000, v119
	v_fmac_f32_e32 v210, v204, v204
	v_fmac_f32_e32 v211, v205, v205
	v_fmac_f32_e32 v210, v206, v206
	v_fmac_f32_e32 v211, v207, v207
	v_lshlrev_b32_e32 v200, 16, v88
	v_and_b32_e32 v201, 0xffff0000, v88
	v_lshlrev_b32_e32 v202, 16, v89
	v_and_b32_e32 v203, 0xffff0000, v89
	v_fmac_f32_e32 v208, v200, v200
	v_fmac_f32_e32 v209, v201, v201
	v_fmac_f32_e32 v208, v202, v202
	v_fmac_f32_e32 v209, v203, v203
	v_lshlrev_b32_e32 v204, 16, v120
	v_and_b32_e32 v205, 0xffff0000, v120
	v_lshlrev_b32_e32 v206, 16, v121
	v_and_b32_e32 v207, 0xffff0000, v121
	v_fmac_f32_e32 v210, v204, v204
	v_fmac_f32_e32 v211, v205, v205
	v_fmac_f32_e32 v210, v206, v206
	v_fmac_f32_e32 v211, v207, v207
	v_lshlrev_b32_e32 v200, 16, v90
	v_and_b32_e32 v201, 0xffff0000, v90
	v_lshlrev_b32_e32 v202, 16, v91
	v_and_b32_e32 v203, 0xffff0000, v91
	v_fmac_f32_e32 v208, v200, v200
	v_fmac_f32_e32 v209, v201, v201
	v_fmac_f32_e32 v208, v202, v202
	v_fmac_f32_e32 v209, v203, v203
	v_lshlrev_b32_e32 v204, 16, v122
	v_and_b32_e32 v205, 0xffff0000, v122
	v_lshlrev_b32_e32 v206, 16, v123
	v_and_b32_e32 v207, 0xffff0000, v123
	v_fmac_f32_e32 v210, v204, v204
	v_fmac_f32_e32 v211, v205, v205
	v_fmac_f32_e32 v210, v206, v206
	v_fmac_f32_e32 v211, v207, v207
	v_lshlrev_b32_e32 v200, 16, v92
	v_and_b32_e32 v201, 0xffff0000, v92
	v_lshlrev_b32_e32 v202, 16, v93
	v_and_b32_e32 v203, 0xffff0000, v93
	v_fmac_f32_e32 v208, v200, v200
	v_fmac_f32_e32 v209, v201, v201
	v_fmac_f32_e32 v208, v202, v202
	v_fmac_f32_e32 v209, v203, v203
	v_lshlrev_b32_e32 v204, 16, v124
	v_and_b32_e32 v205, 0xffff0000, v124
	v_lshlrev_b32_e32 v206, 16, v125
	v_and_b32_e32 v207, 0xffff0000, v125
	v_fmac_f32_e32 v210, v204, v204
	v_fmac_f32_e32 v211, v205, v205
	v_fmac_f32_e32 v210, v206, v206
	v_fmac_f32_e32 v211, v207, v207
	v_lshlrev_b32_e32 v200, 16, v94
	v_and_b32_e32 v201, 0xffff0000, v94
	v_lshlrev_b32_e32 v202, 16, v95
	v_and_b32_e32 v203, 0xffff0000, v95
	v_fmac_f32_e32 v208, v200, v200
	v_fmac_f32_e32 v209, v201, v201
	v_fmac_f32_e32 v208, v202, v202
	v_fmac_f32_e32 v209, v203, v203
	v_lshlrev_b32_e32 v204, 16, v126
	v_and_b32_e32 v205, 0xffff0000, v126
	v_lshlrev_b32_e32 v206, 16, v127
	v_and_b32_e32 v207, 0xffff0000, v127
	v_fmac_f32_e32 v210, v204, v204
	v_fmac_f32_e32 v211, v205, v205
	v_fmac_f32_e32 v210, v206, v206
	v_fmac_f32_e32 v211, v207, v207
	v_add_f32_e32 v208, v208, v209
	v_add_f32_e32 v210, v210, v211
	s_nop 0
	v_add_f32_dpp v212, v208, v208 quad_perm:[1,0,3,2] row_mask:0xf bank_mask:0xf
	v_add_f32_dpp v213, v210, v210 quad_perm:[1,0,3,2] row_mask:0xf bank_mask:0xf
	s_nop 0
	v_add_f32_dpp v212, v212, v212 quad_perm:[2,3,0,1] row_mask:0xf bank_mask:0xf
	v_add_f32_dpp v213, v213, v213 quad_perm:[2,3,0,1] row_mask:0xf bank_mask:0xf
	s_nop 0
	v_add_f32_dpp v212, v212, v212 row_half_mirror row_mask:0xf bank_mask:0xf
	v_add_f32_dpp v213, v213, v213 row_half_mirror row_mask:0xf bank_mask:0xf
	s_nop 0
	v_add_f32_dpp v212, v212, v212 row_mirror row_mask:0xf bank_mask:0xf
	v_add_f32_dpp v213, v213, v213 row_mirror row_mask:0xf bank_mask:0xf
	s_nop 0
	v_readlane_b32 s4, v212, 0
	v_readlane_b32 s5, v212, 16
	v_readlane_b32 s6, v212, 32
	v_readlane_b32 s7, v212, 48
	v_readlane_b32 s24, v213, 0
	v_readlane_b32 s25, v213, 16
	v_readlane_b32 s26, v213, 32
	v_readlane_b32 s27, v213, 48
	s_nop 1
	v_mov_b32_e32 v214, s4
	v_mov_b32_e32 v215, s24
	v_add_f32_e32 v214, s5, v214
	v_add_f32_e32 v215, s25, v215
	v_add_f32_e32 v214, s6, v214
	v_add_f32_e32 v215, s26, v215
	v_add_f32_e32 v214, s7, v214
	v_add_f32_e32 v215, s27, v215
	v_fmamk_f32 v214, v214, 0x3a000000, v195
	v_fmamk_f32 v215, v215, 0x3a000000, v195
	v_rsq_f32_e32 v214, v214
	v_rsq_f32_e32 v215, v215
	s_nop 0
	v_lshlrev_b32_e32 v200, 16, v80
	v_and_b32_e32 v201, 0xffff0000, v80
	v_lshlrev_b32_e32 v202, 16, v81
	v_and_b32_e32 v203, 0xffff0000, v81
	v_lshlrev_b32_e32 v204, 16, v112
	v_and_b32_e32 v205, 0xffff0000, v112
	v_lshlrev_b32_e32 v206, 16, v113
	v_and_b32_e32 v207, 0xffff0000, v113
	v_mul_f32_e32 v200, v214, v200
	v_mul_f32_e32 v201, v214, v201
	v_mul_f32_e32 v202, v214, v202
	v_mul_f32_e32 v203, v214, v203
	v_mul_f32_e32 v204, v215, v204
	v_mul_f32_e32 v205, v215, v205
	v_mul_f32_e32 v206, v215, v206
	v_mul_f32_e32 v207, v215, v207
	v_fmac_f32_e32 v32, v128, v200
	v_fmac_f32_e32 v33, v129, v201
	v_fmac_f32_e32 v34, v130, v202
	v_fmac_f32_e32 v35, v131, v203
	v_fmac_f32_e32 v32, v160, v204
	v_fmac_f32_e32 v33, v161, v205
	v_fmac_f32_e32 v34, v162, v206
	v_fmac_f32_e32 v35, v163, v207
	global_store_dwordx4 v192, v[32:35], s[18:19] offset:0
	v_lshlrev_b32_e32 v200, 16, v82
	v_and_b32_e32 v201, 0xffff0000, v82
	v_lshlrev_b32_e32 v202, 16, v83
	v_and_b32_e32 v203, 0xffff0000, v83
	v_lshlrev_b32_e32 v204, 16, v114
	v_and_b32_e32 v205, 0xffff0000, v114
	v_lshlrev_b32_e32 v206, 16, v115
	v_and_b32_e32 v207, 0xffff0000, v115
	v_mul_f32_e32 v200, v214, v200
	v_mul_f32_e32 v201, v214, v201
	v_mul_f32_e32 v202, v214, v202
	v_mul_f32_e32 v203, v214, v203
	v_mul_f32_e32 v204, v215, v204
	v_mul_f32_e32 v205, v215, v205
; __device__ __forceinline__ float bf_lo(unsigned w) { return __uint_as_float(w << 16); }
; __device__ __forceinline__ float bf_hi(unsigned w) { return __uint_as_float(w & 0xffff0000u); }
; __global__ void __launch_bounds__(NWAVES * 64, 2) mk_fwd(Args args) {
;     ...
;                 const float rsy = __builtin_amdgcn_rsqf(wave_sum(sy) * (1.f / DM) + EPS);
; #pragma unroll
;                 for (int j = 0; j < 8; ++j) { const int col = 4 * F.lane + 256 * j;
;                     const f32x4 y4 = (f32x4){bf_lo(yw[q][j].x), bf_hi(yw[q][j].x), bf_lo(yw[q][j].y), bf_hi(yw[q][j].y)};
;                     *(f32x4*)(args.out + (size_t)row * DM + col) = v[q][j] + PA[j] * (y4 * rsy); }
	v_mul_f32_e32 v206, v215, v206
	v_mul_f32_e32 v207, v215, v207
	v_fmac_f32_e32 v36, v132, v200
	v_fmac_f32_e32 v37, v133, v201
	v_fmac_f32_e32 v38, v134, v202
	v_fmac_f32_e32 v39, v135, v203
	v_fmac_f32_e32 v36, v164, v204
	v_fmac_f32_e32 v37, v165, v205
	v_fmac_f32_e32 v38, v166, v206
	v_fmac_f32_e32 v39, v167, v207
	global_store_dwordx4 v192, v[36:39], s[18:19] offset:1024
	v_lshlrev_b32_e32 v200, 16, v84
	v_and_b32_e32 v201, 0xffff0000, v84
	v_lshlrev_b32_e32 v202, 16, v85
	v_and_b32_e32 v203, 0xffff0000, v85
	v_lshlrev_b32_e32 v204, 16, v116
	v_and_b32_e32 v205, 0xffff0000, v116
	v_lshlrev_b32_e32 v206, 16, v117
	v_and_b32_e32 v207, 0xffff0000, v117
	v_mul_f32_e32 v200, v214, v200
	v_mul_f32_e32 v201, v214, v201
	v_mul_f32_e32 v202, v214, v202
	v_mul_f32_e32 v203, v214, v203
	v_mul_f32_e32 v204, v215, v204
	v_mul_f32_e32 v205, v215, v205
	v_mul_f32_e32 v206, v215, v206
	v_mul_f32_e32 v207, v215, v207
	v_fmac_f32_e32 v40, v136, v200
	v_fmac_f32_e32 v41, v137, v201
	v_fmac_f32_e32 v42, v138, v202
	v_fmac_f32_e32 v43, v139, v203
	v_fmac_f32_e32 v40, v168, v204
	v_fmac_f32_e32 v41, v169, v205
	v_fmac_f32_e32 v42, v170, v206
	v_fmac_f32_e32 v43, v171, v207
	global_store_dwordx4 v192, v[40:43], s[18:19] offset:2048
	v_lshlrev_b32_e32 v200, 16, v86
	v_and_b32_e32 v201, 0xffff0000, v86
	v_lshlrev_b32_e32 v202, 16, v87
	v_and_b32_e32 v203, 0xffff0000, v87
	v_lshlrev_b32_e32 v204, 16, v118
	v_and_b32_e32 v205, 0xffff0000, v118
	v_lshlrev_b32_e32 v206, 16, v119
	v_and_b32_e32 v207, 0xffff0000, v119
	v_mul_f32_e32 v200, v214, v200
	v_mul_f32_e32 v201, v214, v201
	v_mul_f32_e32 v202, v214, v202
	v_mul_f32_e32 v203, v214, v203
	v_mul_f32_e32 v204, v215, v204
	v_mul_f32_e32 v205, v215, v205
	v_mul_f32_e32 v206, v215, v206
	v_mul_f32_e32 v207, v215, v207
	v_fmac_f32_e32 v44, v140, v200
	v_fmac_f32_e32 v45, v141, v201
	v_fmac_f32_e32 v46, v142, v202
	v_fmac_f32_e32 v47, v143, v203
	v_fmac_f32_e32 v44, v172, v204
	v_fmac_f32_e32 v45, v173, v205
	v_fmac_f32_e32 v46, v174, v206
	v_fmac_f32_e32 v47, v175, v207
	global_store_dwordx4 v192, v[44:47], s[18:19] offset:3072
	v_lshlrev_b32_e32 v200, 16, v88
	v_and_b32_e32 v201, 0xffff0000, v88
	v_lshlrev_b32_e32 v202, 16, v89
	v_and_b32_e32 v203, 0xffff0000, v89
	v_lshlrev_b32_e32 v204, 16, v120
	v_and_b32_e32 v205, 0xffff0000, v120
	v_lshlrev_b32_e32 v206, 16, v121
	v_and_b32_e32 v207, 0xffff0000, v121
	v_mul_f32_e32 v200, v214, v200
	v_mul_f32_e32 v201, v214, v201
	v_mul_f32_e32 v202, v214, v202
	v_mul_f32_e32 v203, v214, v203
	v_mul_f32_e32 v204, v215, v204
	v_mul_f32_e32 v205, v215, v205
	v_mul_f32_e32 v206, v215, v206
	v_mul_f32_e32 v207, v215, v207
	v_fmac_f32_e32 v48, v144, v200
	v_fmac_f32_e32 v49, v145, v201
	v_fmac_f32_e32 v50, v146, v202
	v_fmac_f32_e32 v51, v147, v203
	v_fmac_f32_e32 v48, v176, v204
	v_fmac_f32_e32 v49, v177, v205
	v_fmac_f32_e32 v50, v178, v206
	v_fmac_f32_e32 v51, v179, v207
	global_store_dwordx4 v193, v[48:51], s[18:19] offset:0
	v_lshlrev_b32_e32 v200, 16, v90
	v_and_b32_e32 v201, 0xffff0000, v90
	v_lshlrev_b32_e32 v202, 16, v91
	v_and_b32_e32 v203, 0xffff0000, v91
	v_lshlrev_b32_e32 v204, 16, v122
	v_and_b32_e32 v205, 0xffff0000, v122
	v_lshlrev_b32_e32 v206, 16, v123
	v_and_b32_e32 v207, 0xffff0000, v123
	v_mul_f32_e32 v200, v214, v200
	v_mul_f32_e32 v201, v214, v201
	v_mul_f32_e32 v202, v214, v202
	v_mul_f32_e32 v203, v214, v203
	v_mul_f32_e32 v204, v215, v204
	v_mul_f32_e32 v205, v215, v205
	v_mul_f32_e32 v206, v215, v206
	v_mul_f32_e32 v207, v215, v207
	v_fmac_f32_e32 v52, v148, v200
	v_fmac_f32_e32 v53, v149, v201
	v_fmac_f32_e32 v54, v150, v202
	v_fmac_f32_e32 v55, v151, v203
	v_fmac_f32_e32 v52, v180, v204
	v_fmac_f32_e32 v53, v181, v205
	v_fmac_f32_e32 v54, v182, v206
	v_fmac_f32_e32 v55, v183, v207
	global_store_dwordx4 v193, v[52:55], s[18:19] offset:1024
	v_lshlrev_b32_e32 v200, 16, v92
	v_and_b32_e32 v201, 0xffff0000, v92
	v_lshlrev_b32_e32 v202, 16, v93
	v_and_b32_e32 v203, 0xffff0000, v93
	v_lshlrev_b32_e32 v204, 16, v124
	v_and_b32_e32 v205, 0xffff0000, v124
	v_lshlrev_b32_e32 v206, 16, v125
	v_and_b32_e32 v207, 0xffff0000, v125
	v_mul_f32_e32 v200, v214, v200
	v_mul_f32_e32 v201, v214, v201
	v_mul_f32_e32 v202, v214, v202
	v_mul_f32_e32 v203, v214, v203
	v_mul_f32_e32 v204, v215, v204
	v_mul_f32_e32 v205, v215, v205
	v_mul_f32_e32 v206, v215, v206
	v_mul_f32_e32 v207, v215, v207
	v_fmac_f32_e32 v56, v152, v200
	v_fmac_f32_e32 v57, v153, v201
	v_fmac_f32_e32 v58, v154, v202
	v_fmac_f32_e32 v59, v155, v203
	v_fmac_f32_e32 v56, v184, v204
	v_fmac_f32_e32 v57, v185, v205
	v_fmac_f32_e32 v58, v186, v206
	v_fmac_f32_e32 v59, v187, v207
	global_store_dwordx4 v193, v[56:59], s[18:19] offset:2048
	v_lshlrev_b32_e32 v200, 16, v94
	v_and_b32_e32 v201, 0xffff0000, v94
	v_lshlrev_b32_e32 v202, 16, v95
	v_and_b32_e32 v203, 0xffff0000, v95
	v_lshlrev_b32_e32 v204, 16, v126
	v_and_b32_e32 v205, 0xffff0000, v126
	v_lshlrev_b32_e32 v206, 16, v127
	v_and_b32_e32 v207, 0xffff0000, v127
	v_mul_f32_e32 v200, v214, v200
	v_mul_f32_e32 v201, v214, v201
	v_mul_f32_e32 v202, v214, v202
	v_mul_f32_e32 v203, v214, v203
	v_mul_f32_e32 v204, v215, v204
	v_mul_f32_e32 v205, v215, v205
	v_mul_f32_e32 v206, v215, v206
	v_mul_f32_e32 v207, v215, v207
	v_fmac_f32_e32 v60, v156, v200
	v_fmac_f32_e32 v61, v157, v201
	v_fmac_f32_e32 v62, v158, v202
	v_fmac_f32_e32 v63, v159, v203
	v_fmac_f32_e32 v60, v188, v204
	v_fmac_f32_e32 v61, v189, v205
	v_fmac_f32_e32 v62, v190, v206
	v_fmac_f32_e32 v63, v191, v207
	global_store_dwordx4 v193, v[60:63], s[18:19] offset:3072
	s_add_u32 s18, s18, 0x2000
	s_addc_u32 s19, s19, 0
	s_branch .LBB0_1296
